# 16-read load segments issue all LDS reads before their two LDS-DMA stages
# speedup vs baseline: 1.0067x; 1.0001x over previous
; #define PG8_STAGE(bufoff, gbase, voff) do { _Pragma("unroll") for (int _i = 0; _i < 2; ++_i) \
;         __builtin_amdgcn_global_load_lds((const unsigned*)((const char*)(gbase) + (voff)[_i]), (PG8_LAS unsigned*)(lds + (bufoff) + ldsw + _i * 8192), 16, 0, 0); } while (0)
; #define PG8_LDA(dst, b, h) do { _Pragma("unroll") for (int m = 0; m < 4; ++m) _Pragma("unroll") for (int k = 0; k < 2; ++k) dst[m][k] = *(const PG8_LAS bf16x8*)(lds + PG8_SA(b, h) + aoff + m * 2048 + k * 1024); } while (0)
; #define PG8_LDB(dst, b, h) do { _Pragma("unroll") for (int n = 0; n < 2; ++n) _Pragma("unroll") for (int k = 0; k < 2; ++k) dst[n][k] = *(const PG8_LAS bf16x8*)(lds + PG8_SB(b, h) + boff + n * 2048 + k * 1024); } while (0)
; #define PG8_MMA(ai, bj, At, Bt) do { __builtin_amdgcn_s_setprio(1); _Pragma("unroll") for (int m = 0; m < 4; ++m) _Pragma("unroll") for (int n = 0; n < 2; ++n) _Pragma("unroll") for (int k = 0; k < 2; ++k) \
;         acc[ai][bj][m][n] = __builtin_amdgcn_mfma_f32_16x16x32_bf16(Bt[n][k], At[m][k], acc[ai][bj][m][n], 0, 0, 0); __builtin_amdgcn_s_setprio(0); } while (0)
; #define PG8_WAIT_V(n) asm volatile("s_waitcnt vmcnt(" #n ")" ::: "memory")
; template <class Epi, class Sched>
; __device__ __forceinline__ void gemm_phase(PG8_LAS unsigned char* lds, const Gemm g, const Sched& S, const Epi& E) {
;     ...
;         for (int t = 0; t < nt; t += 2) {
;             const bool last = (t == nt - 2);
;             const char* a1 = cA + (size_t)(t + 1) * kstep;
;             const char* a2 = last ? nA : cA + (size_t)(t + 2) * kstep; const char* b2 = last ? nB : cB + (size_t)(t + 2) * kstepB;
;             const char* a3 = a2 + kstep; const char* b3 = b2 + kstepB;
;             if (last && has_next) S.a_ready(nxt);
;             PG8_LDB(B0, 0, 0); PG8_SCHED; PG8_LDA(At, 0, 0); PG8_STAGE(PG8_SA(1, 1), a1 + hstep, voffA);
;             PG8_WAIT_L(8); PG8_BAR; PG8_WAIT_L(0); PG8_MMA(0, 0, At, B0); PG8_BAR; PG8_SCHED;
;             PG8_LDB(B1, 0, 1); PG8_STAGE(PG8_SB(0, 0), b2, voffB);
;             PG8_BAR; PG8_WAIT_L(0); PG8_MMA(0, 1, At, B1); PG8_BAR;
;             PG8_LDA(At, 0, 1); PG8_STAGE(PG8_SA(0, 0), a2, voffA);
;             PG8_BAR; PG8_WAIT_L(0); PG8_MMA(1, 0, At, B0); PG8_BAR; PG8_SCHED;
;             PG8_STAGE(PG8_SB(0, 1), b2 + hstepB, voffB);
;             PG8_WAIT_V(6); PG8_BAR; PG8_MMA(1, 1, At, B1); PG8_BAR;
.Lhalf_skip_y_0:
.LBB0_79:
	ds_read_b128 v[152:155], v149
	ds_read_b128 v[156:159], v149 offset:1024
	ds_read_b128 v[160:163], v149 offset:2048
	ds_read_b128 v[164:167], v149 offset:3072
	s_add_u32 s24, s22, 0xfff80080
	s_addc_u32 s25, s23, -1
	s_cmp_eq_u32 s61, 28
	s_cselect_b32 s27, s13, s25
	s_cselect_b32 s26, s57, s24
	s_cselect_b32 s25, s15, s60
	s_cselect_b32 s24, s58, s59
	s_add_i32 m0, s21, 0xc000
	ds_read_b128 v[168:171], v150
	ds_read_b128 v[172:175], v150 offset:1024
	ds_read_b128 v[176:179], v150 offset:2048
	ds_read_b128 v[180:183], v150 offset:3072
	ds_read_b128 v[184:187], v150 offset:4096
	ds_read_b128 v[188:191], v150 offset:5120
	ds_read_b128 v[192:195], v150 offset:6144
	ds_read_b128 v[196:199], v150 offset:7168
	ds_read_b128 v[200:203], v151
	ds_read_b128 v[204:207], v151 offset:1024
	ds_read_b128 v[208:211], v151 offset:2048
	ds_read_b128 v[212:215], v151 offset:3072
	global_load_lds_dwordx4 v136, s[22:23]
	s_add_i32 m0, s21, 0xe000
	s_nop 0
	global_load_lds_dwordx4 v138, s[22:23]
	s_add_i32 s62, s53, s38
	s_mov_b32 m0, s62
	s_waitcnt vmcnt(8)
	s_waitcnt lgkmcnt(0)
	s_barrier
	v_mfma_f32_16x16x32_bf16 v[124:127], v[152:155], v[168:171], v[124:127]
	v_mfma_f32_16x16x32_bf16 v[120:123], v[160:163], v[168:171], v[120:123]
	v_mfma_f32_16x16x32_bf16 v[108:111], v[152:155], v[176:179], v[108:111]
	v_mfma_f32_16x16x32_bf16 v[104:107], v[160:163], v[176:179], v[104:107]
	v_mfma_f32_16x16x32_bf16 v[92:95], v[152:155], v[184:187], v[92:95]
	v_mfma_f32_16x16x32_bf16 v[88:91], v[160:163], v[184:187], v[88:91]
	v_mfma_f32_16x16x32_bf16 v[76:79], v[152:155], v[192:195], v[76:79]
	v_mfma_f32_16x16x32_bf16 v[72:75], v[160:163], v[192:195], v[72:75]
	v_mfma_f32_16x16x32_bf16 v[124:127], v[156:159], v[172:175], v[124:127]
	v_mfma_f32_16x16x32_bf16 v[120:123], v[164:167], v[172:175], v[120:123]
	v_mfma_f32_16x16x32_bf16 v[108:111], v[156:159], v[180:183], v[108:111]
	v_mfma_f32_16x16x32_bf16 v[104:107], v[164:167], v[180:183], v[104:107]
	v_mfma_f32_16x16x32_bf16 v[92:95], v[156:159], v[188:191], v[92:95]
	v_mfma_f32_16x16x32_bf16 v[88:91], v[164:167], v[188:191], v[88:91]
	v_mfma_f32_16x16x32_bf16 v[76:79], v[156:159], v[196:199], v[76:79]
	v_mfma_f32_16x16x32_bf16 v[72:75], v[164:167], v[196:199], v[72:75]
	v_mfma_f32_16x16x32_bf16 v[116:119], v[200:203], v[168:171], v[116:119]
	v_mfma_f32_16x16x32_bf16 v[112:115], v[208:211], v[168:171], v[112:115]
	v_mfma_f32_16x16x32_bf16 v[100:103], v[200:203], v[176:179], v[100:103]
	v_mfma_f32_16x16x32_bf16 v[96:99], v[208:211], v[176:179], v[96:99]
	v_mfma_f32_16x16x32_bf16 v[84:87], v[200:203], v[184:187], v[84:87]
	v_mfma_f32_16x16x32_bf16 v[80:83], v[208:211], v[184:187], v[80:83]
	v_mfma_f32_16x16x32_bf16 v[68:71], v[200:203], v[192:195], v[68:71]
	v_mfma_f32_16x16x32_bf16 v[64:67], v[208:211], v[192:195], v[64:67]
	v_mfma_f32_16x16x32_bf16 v[116:119], v[204:207], v[172:175], v[116:119]
	v_mfma_f32_16x16x32_bf16 v[112:115], v[212:215], v[172:175], v[112:115]
	v_mfma_f32_16x16x32_bf16 v[100:103], v[204:207], v[180:183], v[100:103]
	v_mfma_f32_16x16x32_bf16 v[96:99], v[212:215], v[180:183], v[96:99]
	v_mfma_f32_16x16x32_bf16 v[84:87], v[204:207], v[188:191], v[84:87]
	v_mfma_f32_16x16x32_bf16 v[80:83], v[212:215], v[188:191], v[80:83]
	v_mfma_f32_16x16x32_bf16 v[68:71], v[204:207], v[196:199], v[68:71]
	v_mfma_f32_16x16x32_bf16 v[64:67], v[212:215], v[196:199], v[64:67]
	s_barrier
	global_load_lds_dwordx4 v128, s[24:25]
	s_add_i32 m0, s62, 0x2000
	s_nop 0
	global_load_lds_dwordx4 v130, s[24:25]
	s_mov_b32 m0, s21
	v_lshl_add_u64 v[144:145], s[26:27], 0, v[134:135]
	ds_read_b128 v[168:171], v150 offset:16384
	ds_read_b128 v[172:175], v150 offset:17408
	ds_read_b128 v[176:179], v150 offset:18432
	ds_read_b128 v[180:183], v150 offset:19456
	ds_read_b128 v[184:187], v150 offset:20480
	ds_read_b128 v[188:191], v150 offset:21504
	ds_read_b128 v[192:195], v150 offset:22528
	ds_read_b128 v[196:199], v150 offset:23552
	global_load_lds_dwordx4 v[144:145], off
	v_lshl_add_u64 v[216:217], s[26:27], 0, v[132:133]
	s_mov_b32 m0, s46
	s_nop 0
	global_load_lds_dwordx4 v[216:217], off
	s_add_u32 s62, s24, 0x4000
	s_addc_u32 s63, s25, 0
	s_add_i32 s64, s54, s38
	s_mov_b32 m0, s64
	s_nop 0
	global_load_lds_dwordx4 v128, s[62:63]
	s_add_i32 m0, s64, 0x2000
	s_nop 0
	global_load_lds_dwordx4 v130, s[62:63]
	s_waitcnt vmcnt(8)
	s_waitcnt lgkmcnt(0)
	s_barrier
	v_mfma_f32_16x16x32_bf16 v[60:63], v[152:155], v[168:171], v[60:63]
	v_mfma_f32_16x16x32_bf16 v[56:59], v[160:163], v[168:171], v[56:59]
	v_mfma_f32_16x16x32_bf16 v[44:47], v[152:155], v[176:179], v[44:47]
	v_mfma_f32_16x16x32_bf16 v[40:43], v[160:163], v[176:179], v[40:43]
	v_mfma_f32_16x16x32_bf16 v[28:31], v[152:155], v[184:187], v[28:31]
	v_mfma_f32_16x16x32_bf16 v[24:27], v[160:163], v[184:187], v[24:27]
	v_mfma_f32_16x16x32_bf16 v[12:15], v[152:155], v[192:195], v[12:15]
	v_mfma_f32_16x16x32_bf16 v[8:11], v[160:163], v[192:195], v[8:11]
	v_mfma_f32_16x16x32_bf16 v[60:63], v[156:159], v[172:175], v[60:63]
	v_mfma_f32_16x16x32_bf16 v[56:59], v[164:167], v[172:175], v[56:59]
	v_mfma_f32_16x16x32_bf16 v[44:47], v[156:159], v[180:183], v[44:47]
	v_mfma_f32_16x16x32_bf16 v[40:43], v[164:167], v[180:183], v[40:43]
	v_mfma_f32_16x16x32_bf16 v[28:31], v[156:159], v[188:191], v[28:31]
	v_mfma_f32_16x16x32_bf16 v[24:27], v[164:167], v[188:191], v[24:27]
	v_mfma_f32_16x16x32_bf16 v[12:15], v[156:159], v[196:199], v[12:15]
	v_mfma_f32_16x16x32_bf16 v[8:11], v[164:167], v[196:199], v[8:11]
	v_mfma_f32_16x16x32_bf16 v[52:55], v[200:203], v[168:171], v[52:55]
	v_mfma_f32_16x16x32_bf16 v[48:51], v[208:211], v[168:171], v[48:51]
	v_mfma_f32_16x16x32_bf16 v[36:39], v[200:203], v[176:179], v[36:39]
	v_mfma_f32_16x16x32_bf16 v[32:35], v[208:211], v[176:179], v[32:35]
	v_mfma_f32_16x16x32_bf16 v[20:23], v[200:203], v[184:187], v[20:23]
	v_mfma_f32_16x16x32_bf16 v[16:19], v[208:211], v[184:187], v[16:19]
	v_mfma_f32_16x16x32_bf16 v[4:7], v[200:203], v[192:195], v[4:7]
	v_mfma_f32_16x16x32_bf16 v[0:3], v[208:211], v[192:195], v[0:3]
	v_mfma_f32_16x16x32_bf16 v[52:55], v[204:207], v[172:175], v[52:55]
	v_mfma_f32_16x16x32_bf16 v[48:51], v[212:215], v[172:175], v[48:51]
	v_mfma_f32_16x16x32_bf16 v[36:39], v[204:207], v[180:183], v[36:39]
	v_mfma_f32_16x16x32_bf16 v[32:35], v[212:215], v[180:183], v[32:35]
	v_mfma_f32_16x16x32_bf16 v[20:23], v[204:207], v[188:191], v[20:23]
	v_mfma_f32_16x16x32_bf16 v[16:19], v[212:215], v[188:191], v[16:19]
	v_mfma_f32_16x16x32_bf16 v[4:7], v[204:207], v[196:199], v[4:7]
	v_mfma_f32_16x16x32_bf16 v[0:3], v[212:215], v[196:199], v[0:3]
	s_barrier
; #define PG8_STAGE(bufoff, gbase, voff) do { _Pragma("unroll") for (int _i = 0; _i < 2; ++_i) \
;         __builtin_amdgcn_global_load_lds((const unsigned*)((const char*)(gbase) + (voff)[_i]), (PG8_LAS unsigned*)(lds + (bufoff) + ldsw + _i * 8192), 16, 0, 0); } while (0)
; #define PG8_LDA(dst, b, h) do { _Pragma("unroll") for (int m = 0; m < 4; ++m) _Pragma("unroll") for (int k = 0; k < 2; ++k) dst[m][k] = *(const PG8_LAS bf16x8*)(lds + PG8_SA(b, h) + aoff + m * 2048 + k * 1024); } while (0)
; #define PG8_LDB(dst, b, h) do { _Pragma("unroll") for (int n = 0; n < 2; ++n) _Pragma("unroll") for (int k = 0; k < 2; ++k) dst[n][k] = *(const PG8_LAS bf16x8*)(lds + PG8_SB(b, h) + boff + n * 2048 + k * 1024); } while (0)
; #define PG8_MMA(ai, bj, At, Bt) do { __builtin_amdgcn_s_setprio(1); _Pragma("unroll") for (int m = 0; m < 4; ++m) _Pragma("unroll") for (int n = 0; n < 2; ++n) _Pragma("unroll") for (int k = 0; k < 2; ++k) \
;         acc[ai][bj][m][n] = __builtin_amdgcn_mfma_f32_16x16x32_bf16(Bt[n][k], At[m][k], acc[ai][bj][m][n], 0, 0, 0); __builtin_amdgcn_s_setprio(0); } while (0)
; #define PG8_WAIT_V(n) asm volatile("s_waitcnt vmcnt(" #n ")" ::: "memory")
; #define PG8_WAIT_L(n) asm volatile("s_waitcnt lgkmcnt(" #n ")" ::: "memory")
; #define PG8_BAR __builtin_amdgcn_s_barrier()
; #define PG8_SCHED __builtin_amdgcn_sched_barrier(0)
; template <class Epi, class Sched>
; __device__ __forceinline__ void gemm_phase(PG8_LAS unsigned char* lds, const Gemm g, const Sched& S, const Epi& E) {
;     ...
;             PG8_LDB(B0, 1, 0); PG8_SCHED; PG8_LDA(At, 1, 0); PG8_STAGE(PG8_SA(0, 1), a2 + hstep, voffA);
;             PG8_WAIT_L(8); PG8_BAR; PG8_WAIT_L(0); PG8_MMA(0, 0, At, B0); PG8_BAR; PG8_SCHED;
;             PG8_LDB(B1, 1, 1); PG8_STAGE(PG8_SB(1, 0), b3, voffB);
;             PG8_BAR; PG8_WAIT_L(0); PG8_MMA(0, 1, At, B1); PG8_BAR;
;             PG8_LDA(At, 1, 1); PG8_STAGE(PG8_SA(1, 0), a3, voffA);
;             PG8_BAR; PG8_WAIT_L(0); PG8_MMA(1, 0, At, B0); PG8_BAR; PG8_SCHED;
;             PG8_STAGE(PG8_SB(1, 1), b3 + hstepB, voffB);
;             PG8_WAIT_V(6); PG8_BAR; PG8_MMA(1, 1, At, B1); PG8_BAR;
;         }
	s_add_i32 s62, 0, 0x18000
	v_add_u32_e32 v164, s62, v147
	ds_read_b128 v[152:155], v164
	ds_read_b128 v[156:159], v164 offset:1024
	ds_read_b128 v[160:163], v164 offset:2048
	ds_read_b128 v[164:167], v164 offset:3072
	s_add_u32 s26, s26, 0x80000
	s_addc_u32 s27, s27, 0
	s_mov_b32 m0, s47
	ds_read_b128 v[168:171], v150 offset:32768
	ds_read_b128 v[172:175], v150 offset:33792
	ds_read_b128 v[176:179], v150 offset:34816
	ds_read_b128 v[180:183], v150 offset:35840
	ds_read_b128 v[184:187], v150 offset:36864
	ds_read_b128 v[188:191], v150 offset:37888
	ds_read_b128 v[192:195], v150 offset:38912
	ds_read_b128 v[196:199], v150 offset:39936
	s_add_i32 s63, 0, 0x1c000
	v_add_u32_e32 v212, s63, v147
	ds_read_b128 v[200:203], v212
	ds_read_b128 v[204:207], v212 offset:1024
	ds_read_b128 v[208:211], v212 offset:2048
	ds_read_b128 v[212:215], v212 offset:3072
	global_load_lds_dwordx4 v134, s[26:27]
	s_mov_b32 m0, s48
	s_nop 0
	global_load_lds_dwordx4 v132, s[26:27]
	s_add_u32 s26, s24, 0x8000
	s_addc_u32 s27, s25, 0
	s_add_i32 s62, s62, s38
	s_mov_b32 m0, s62
	s_waitcnt vmcnt(8)
	s_waitcnt lgkmcnt(0)
	s_barrier
	v_mfma_f32_16x16x32_bf16 v[124:127], v[152:155], v[168:171], v[124:127]
	v_mfma_f32_16x16x32_bf16 v[120:123], v[160:163], v[168:171], v[120:123]
	v_mfma_f32_16x16x32_bf16 v[108:111], v[152:155], v[176:179], v[108:111]
	v_mfma_f32_16x16x32_bf16 v[104:107], v[160:163], v[176:179], v[104:107]
	v_mfma_f32_16x16x32_bf16 v[92:95], v[152:155], v[184:187], v[92:95]
	v_mfma_f32_16x16x32_bf16 v[88:91], v[160:163], v[184:187], v[88:91]
	v_mfma_f32_16x16x32_bf16 v[76:79], v[152:155], v[192:195], v[76:79]
	v_mfma_f32_16x16x32_bf16 v[72:75], v[160:163], v[192:195], v[72:75]
	v_mfma_f32_16x16x32_bf16 v[124:127], v[156:159], v[172:175], v[124:127]
	v_mfma_f32_16x16x32_bf16 v[120:123], v[164:167], v[172:175], v[120:123]
	v_mfma_f32_16x16x32_bf16 v[108:111], v[156:159], v[180:183], v[108:111]
	v_mfma_f32_16x16x32_bf16 v[104:107], v[164:167], v[180:183], v[104:107]
	v_mfma_f32_16x16x32_bf16 v[92:95], v[156:159], v[188:191], v[92:95]
	v_mfma_f32_16x16x32_bf16 v[88:91], v[164:167], v[188:191], v[88:91]
	v_mfma_f32_16x16x32_bf16 v[76:79], v[156:159], v[196:199], v[76:79]
	v_mfma_f32_16x16x32_bf16 v[72:75], v[164:167], v[196:199], v[72:75]
	v_mfma_f32_16x16x32_bf16 v[116:119], v[200:203], v[168:171], v[116:119]
	v_mfma_f32_16x16x32_bf16 v[112:115], v[208:211], v[168:171], v[112:115]
	v_mfma_f32_16x16x32_bf16 v[100:103], v[200:203], v[176:179], v[100:103]
	v_mfma_f32_16x16x32_bf16 v[96:99], v[208:211], v[176:179], v[96:99]
	v_mfma_f32_16x16x32_bf16 v[84:87], v[200:203], v[184:187], v[84:87]
	v_mfma_f32_16x16x32_bf16 v[80:83], v[208:211], v[184:187], v[80:83]
	v_mfma_f32_16x16x32_bf16 v[68:71], v[200:203], v[192:195], v[68:71]
	v_mfma_f32_16x16x32_bf16 v[64:67], v[208:211], v[192:195], v[64:67]
	v_mfma_f32_16x16x32_bf16 v[116:119], v[204:207], v[172:175], v[116:119]
	v_mfma_f32_16x16x32_bf16 v[112:115], v[212:215], v[172:175], v[112:115]
	v_mfma_f32_16x16x32_bf16 v[100:103], v[204:207], v[180:183], v[100:103]
	v_mfma_f32_16x16x32_bf16 v[96:99], v[212:215], v[180:183], v[96:99]
	v_mfma_f32_16x16x32_bf16 v[84:87], v[204:207], v[188:191], v[84:87]
	v_mfma_f32_16x16x32_bf16 v[80:83], v[212:215], v[188:191], v[80:83]
	v_mfma_f32_16x16x32_bf16 v[68:71], v[204:207], v[196:199], v[68:71]
	v_mfma_f32_16x16x32_bf16 v[64:67], v[212:215], v[196:199], v[64:67]
	s_barrier
	global_load_lds_dwordx4 v128, s[26:27]
	s_add_i32 m0, s62, 0x2000
	s_nop 0
	global_load_lds_dwordx4 v130, s[26:27]
	s_mov_b32 m0, s50
	v_lshl_add_u64 v[144:145], v[144:145], 0, s[10:11]
	ds_read_b128 v[168:171], v150 offset:49152
	ds_read_b128 v[172:175], v150 offset:50176
	ds_read_b128 v[176:179], v150 offset:51200
	ds_read_b128 v[180:183], v150 offset:52224
	ds_read_b128 v[184:187], v150 offset:53248
	ds_read_b128 v[188:191], v150 offset:54272
	ds_read_b128 v[192:195], v150 offset:55296
	ds_read_b128 v[196:199], v150 offset:56320
	global_load_lds_dwordx4 v[144:145], off
	v_lshl_add_u64 v[144:145], v[216:217], 0, s[10:11]
	s_mov_b32 m0, s51
	s_nop 0
	global_load_lds_dwordx4 v[144:145], off
	s_add_u32 s24, s24, 0xc000
	s_addc_u32 s25, s25, 0
	s_add_i32 s26, s63, s38
	s_mov_b32 m0, s26
	s_nop 0
	global_load_lds_dwordx4 v128, s[24:25]
	s_add_i32 m0, s26, 0x2000
	s_nop 0
	global_load_lds_dwordx4 v130, s[24:25]
	s_add_i32 s61, s61, 2
	s_add_u32 s59, s59, 0x10000
	s_addc_u32 s60, s60, 0
	s_add_u32 s22, s22, 0x100
	s_addc_u32 s23, s23, 0
	s_cmp_gt_u32 s61, 29
	s_waitcnt vmcnt(8)
	s_waitcnt lgkmcnt(0)
	s_barrier
	v_mfma_f32_16x16x32_bf16 v[60:63], v[152:155], v[168:171], v[60:63]
	v_mfma_f32_16x16x32_bf16 v[56:59], v[160:163], v[168:171], v[56:59]
	v_mfma_f32_16x16x32_bf16 v[44:47], v[152:155], v[176:179], v[44:47]
	v_mfma_f32_16x16x32_bf16 v[40:43], v[160:163], v[176:179], v[40:43]
	v_mfma_f32_16x16x32_bf16 v[28:31], v[152:155], v[184:187], v[28:31]
	v_mfma_f32_16x16x32_bf16 v[24:27], v[160:163], v[184:187], v[24:27]
	v_mfma_f32_16x16x32_bf16 v[12:15], v[152:155], v[192:195], v[12:15]
	v_mfma_f32_16x16x32_bf16 v[8:11], v[160:163], v[192:195], v[8:11]
	v_mfma_f32_16x16x32_bf16 v[60:63], v[156:159], v[172:175], v[60:63]
	v_mfma_f32_16x16x32_bf16 v[56:59], v[164:167], v[172:175], v[56:59]
	v_mfma_f32_16x16x32_bf16 v[44:47], v[156:159], v[180:183], v[44:47]
	v_mfma_f32_16x16x32_bf16 v[40:43], v[164:167], v[180:183], v[40:43]
	v_mfma_f32_16x16x32_bf16 v[28:31], v[156:159], v[188:191], v[28:31]
	v_mfma_f32_16x16x32_bf16 v[24:27], v[164:167], v[188:191], v[24:27]
	v_mfma_f32_16x16x32_bf16 v[12:15], v[156:159], v[196:199], v[12:15]
	v_mfma_f32_16x16x32_bf16 v[8:11], v[164:167], v[196:199], v[8:11]
	v_mfma_f32_16x16x32_bf16 v[52:55], v[200:203], v[168:171], v[52:55]
	v_mfma_f32_16x16x32_bf16 v[48:51], v[208:211], v[168:171], v[48:51]
	v_mfma_f32_16x16x32_bf16 v[36:39], v[200:203], v[176:179], v[36:39]
	v_mfma_f32_16x16x32_bf16 v[32:35], v[208:211], v[176:179], v[32:35]
	v_mfma_f32_16x16x32_bf16 v[20:23], v[200:203], v[184:187], v[20:23]
	v_mfma_f32_16x16x32_bf16 v[16:19], v[208:211], v[184:187], v[16:19]
	v_mfma_f32_16x16x32_bf16 v[4:7], v[200:203], v[192:195], v[4:7]
	v_mfma_f32_16x16x32_bf16 v[0:3], v[208:211], v[192:195], v[0:3]
	v_mfma_f32_16x16x32_bf16 v[52:55], v[204:207], v[172:175], v[52:55]
	v_mfma_f32_16x16x32_bf16 v[48:51], v[212:215], v[172:175], v[48:51]
	v_mfma_f32_16x16x32_bf16 v[36:39], v[204:207], v[180:183], v[36:39]
	v_mfma_f32_16x16x32_bf16 v[32:35], v[212:215], v[180:183], v[32:35]
	s_cbranch_scc1 .Lunit_exit_0
	v_mfma_f32_16x16x32_bf16 v[20:23], v[204:207], v[188:191], v[20:23]
	v_mfma_f32_16x16x32_bf16 v[16:19], v[212:215], v[188:191], v[16:19]
	v_mfma_f32_16x16x32_bf16 v[4:7], v[204:207], v[196:199], v[4:7]
	v_mfma_f32_16x16x32_bf16 v[0:3], v[212:215], v[196:199], v[0:3]
	s_barrier
	s_branch .LBB0_79

; #define PG8_STAGE(bufoff, gbase, voff) do { _Pragma("unroll") for (int _i = 0; _i < 2; ++_i) \
;         __builtin_amdgcn_global_load_lds((const unsigned*)((const char*)(gbase) + (voff)[_i]), (PG8_LAS unsigned*)(lds + (bufoff) + ldsw + _i * 8192), 16, 0, 0); } while (0)
; #define PG8_LDA(dst, b, h) do { _Pragma("unroll") for (int m = 0; m < 4; ++m) _Pragma("unroll") for (int k = 0; k < 2; ++k) dst[m][k] = *(const PG8_LAS bf16x8*)(lds + PG8_SA(b, h) + aoff + m * 2048 + k * 1024); } while (0)
; #define PG8_LDB(dst, b, h) do { _Pragma("unroll") for (int n = 0; n < 2; ++n) _Pragma("unroll") for (int k = 0; k < 2; ++k) dst[n][k] = *(const PG8_LAS bf16x8*)(lds + PG8_SB(b, h) + boff + n * 2048 + k * 1024); } while (0)
; #define PG8_MMA(ai, bj, At, Bt) do { __builtin_amdgcn_s_setprio(1); _Pragma("unroll") for (int m = 0; m < 4; ++m) _Pragma("unroll") for (int n = 0; n < 2; ++n) _Pragma("unroll") for (int k = 0; k < 2; ++k) \
;         acc[ai][bj][m][n] = __builtin_amdgcn_mfma_f32_16x16x32_bf16(Bt[n][k], At[m][k], acc[ai][bj][m][n], 0, 0, 0); __builtin_amdgcn_s_setprio(0); } while (0)
; #define PG8_WAIT_V(n) asm volatile("s_waitcnt vmcnt(" #n ")" ::: "memory")
; template <class Epi, class Sched>
; __device__ __forceinline__ void gemm_phase(PG8_LAS unsigned char* lds, const Gemm g, const Sched& S, const Epi& E) {
;     ...
;         for (int t = 0; t < nt; t += 2) {
;             const bool last = (t == nt - 2);
;             const char* a1 = cA + (size_t)(t + 1) * kstep;
;             const char* a2 = last ? nA : cA + (size_t)(t + 2) * kstep; const char* b2 = last ? nB : cB + (size_t)(t + 2) * kstepB;
;             const char* a3 = a2 + kstep; const char* b3 = b2 + kstepB;
;             if (last && has_next) S.a_ready(nxt);
;             PG8_LDB(B0, 0, 0); PG8_SCHED; PG8_LDA(At, 0, 0); PG8_STAGE(PG8_SA(1, 1), a1 + hstep, voffA);
;             PG8_WAIT_L(8); PG8_BAR; PG8_WAIT_L(0); PG8_MMA(0, 0, At, B0); PG8_BAR; PG8_SCHED;
;             PG8_LDB(B1, 0, 1); PG8_STAGE(PG8_SB(0, 0), b2, voffB);
;             PG8_BAR; PG8_WAIT_L(0); PG8_MMA(0, 1, At, B1); PG8_BAR;
;             PG8_LDA(At, 0, 1); PG8_STAGE(PG8_SA(0, 0), a2, voffA);
;             PG8_BAR; PG8_WAIT_L(0); PG8_MMA(1, 0, At, B0); PG8_BAR; PG8_SCHED;
;             PG8_STAGE(PG8_SB(0, 1), b2 + hstepB, voffB);
;             PG8_WAIT_V(6); PG8_BAR; PG8_MMA(1, 1, At, B1); PG8_BAR;
.Lhalf_skip_y_1:
.LBB0_155:
	ds_read_b128 v[144:147], v153
	ds_read_b128 v[156:159], v153 offset:1024
	ds_read_b128 v[160:163], v153 offset:2048
	ds_read_b128 v[164:167], v153 offset:3072
	s_add_u32 s26, s24, 0x100
	s_addc_u32 s27, s25, 0
	s_cmpk_eq_i32 s67, 0x52
	s_cselect_b32 s31, s7, s27
	s_cselect_b32 s30, s6, s26
	s_cselect_b32 s29, s9, s66
	s_cselect_b32 s28, s8, s65
	v_lshl_add_u64 v[148:149], s[24:25], 0, v[136:137]
	s_add_i32 m0, s51, 0xc000
	ds_read_b128 v[168:171], v154
	ds_read_b128 v[172:175], v154 offset:1024
	ds_read_b128 v[176:179], v154 offset:2048
	ds_read_b128 v[180:183], v154 offset:3072
	ds_read_b128 v[184:187], v154 offset:4096
	ds_read_b128 v[188:191], v154 offset:5120
	ds_read_b128 v[192:195], v154 offset:6144
	ds_read_b128 v[196:199], v154 offset:7168
	ds_read_b128 v[200:203], v155
	ds_read_b128 v[204:207], v155 offset:1024
	ds_read_b128 v[208:211], v155 offset:2048
	ds_read_b128 v[212:215], v155 offset:3072
	global_load_lds_dwordx4 v[148:149], off
	v_lshl_add_u64 v[148:149], s[24:25], 0, v[138:139]
	s_add_i32 m0, s51, 0xe000
	s_nop 0
	global_load_lds_dwordx4 v[148:149], off
	s_add_i32 s24, s59, s50
	s_mov_b32 m0, s24
	s_waitcnt vmcnt(8)
	s_waitcnt lgkmcnt(0)
	s_barrier
	v_mfma_f32_16x16x32_bf16 v[124:127], v[144:147], v[168:171], v[124:127]
	v_mfma_f32_16x16x32_bf16 v[120:123], v[160:163], v[168:171], v[120:123]
	v_mfma_f32_16x16x32_bf16 v[108:111], v[144:147], v[176:179], v[108:111]
	v_mfma_f32_16x16x32_bf16 v[104:107], v[160:163], v[176:179], v[104:107]
	v_mfma_f32_16x16x32_bf16 v[92:95], v[144:147], v[184:187], v[92:95]
	v_mfma_f32_16x16x32_bf16 v[88:91], v[160:163], v[184:187], v[88:91]
	v_mfma_f32_16x16x32_bf16 v[76:79], v[144:147], v[192:195], v[76:79]
	v_mfma_f32_16x16x32_bf16 v[72:75], v[160:163], v[192:195], v[72:75]
	v_mfma_f32_16x16x32_bf16 v[124:127], v[156:159], v[172:175], v[124:127]
	v_mfma_f32_16x16x32_bf16 v[120:123], v[164:167], v[172:175], v[120:123]
	v_mfma_f32_16x16x32_bf16 v[108:111], v[156:159], v[180:183], v[108:111]
	v_mfma_f32_16x16x32_bf16 v[104:107], v[164:167], v[180:183], v[104:107]
	v_mfma_f32_16x16x32_bf16 v[92:95], v[156:159], v[188:191], v[92:95]
	v_mfma_f32_16x16x32_bf16 v[88:91], v[164:167], v[188:191], v[88:91]
	v_mfma_f32_16x16x32_bf16 v[76:79], v[156:159], v[196:199], v[76:79]
	v_mfma_f32_16x16x32_bf16 v[72:75], v[164:167], v[196:199], v[72:75]
	v_mfma_f32_16x16x32_bf16 v[116:119], v[200:203], v[168:171], v[116:119]
	v_mfma_f32_16x16x32_bf16 v[112:115], v[208:211], v[168:171], v[112:115]
	v_mfma_f32_16x16x32_bf16 v[100:103], v[200:203], v[176:179], v[100:103]
	v_mfma_f32_16x16x32_bf16 v[96:99], v[208:211], v[176:179], v[96:99]
	v_mfma_f32_16x16x32_bf16 v[84:87], v[200:203], v[184:187], v[84:87]
	v_mfma_f32_16x16x32_bf16 v[80:83], v[208:211], v[184:187], v[80:83]
	v_mfma_f32_16x16x32_bf16 v[68:71], v[200:203], v[192:195], v[68:71]
	v_mfma_f32_16x16x32_bf16 v[64:67], v[208:211], v[192:195], v[64:67]
	v_mfma_f32_16x16x32_bf16 v[116:119], v[204:207], v[172:175], v[116:119]
	v_mfma_f32_16x16x32_bf16 v[112:115], v[212:215], v[172:175], v[112:115]
	v_mfma_f32_16x16x32_bf16 v[100:103], v[204:207], v[180:183], v[100:103]
	v_mfma_f32_16x16x32_bf16 v[96:99], v[212:215], v[180:183], v[96:99]
	v_mfma_f32_16x16x32_bf16 v[84:87], v[204:207], v[188:191], v[84:87]
	v_mfma_f32_16x16x32_bf16 v[80:83], v[212:215], v[188:191], v[80:83]
	v_mfma_f32_16x16x32_bf16 v[68:71], v[204:207], v[196:199], v[68:71]
	v_mfma_f32_16x16x32_bf16 v[64:67], v[212:215], v[196:199], v[64:67]
	s_barrier
	global_load_lds_dwordx4 v128, s[28:29]
	s_add_i32 m0, s24, 0x2000
	s_nop 0
	global_load_lds_dwordx4 v132, s[28:29]
	s_mov_b32 m0, s51
	v_lshl_add_u64 v[148:149], s[30:31], 0, v[130:131]
	ds_read_b128 v[168:171], v154 offset:16384
	ds_read_b128 v[172:175], v154 offset:17408
	ds_read_b128 v[176:179], v154 offset:18432
	ds_read_b128 v[180:183], v154 offset:19456
	ds_read_b128 v[184:187], v154 offset:20480
	ds_read_b128 v[188:191], v154 offset:21504
	ds_read_b128 v[192:195], v154 offset:22528
	ds_read_b128 v[196:199], v154 offset:23552
	global_load_lds_dwordx4 v[148:149], off
	v_lshl_add_u64 v[216:217], s[30:31], 0, v[134:135]
	s_mov_b32 m0, s52
	s_nop 0
	global_load_lds_dwordx4 v[216:217], off
	s_add_u32 s24, s28, 0x4000
	s_addc_u32 s25, s29, 0
	s_add_i32 s68, s60, s50
	s_mov_b32 m0, s68
	s_nop 0
	global_load_lds_dwordx4 v128, s[24:25]
	s_add_i32 m0, s68, 0x2000
	s_nop 0
	global_load_lds_dwordx4 v132, s[24:25]
	s_waitcnt vmcnt(8)
	s_waitcnt lgkmcnt(0)
	s_barrier
	v_mfma_f32_16x16x32_bf16 v[60:63], v[144:147], v[168:171], v[60:63]
	v_mfma_f32_16x16x32_bf16 v[56:59], v[160:163], v[168:171], v[56:59]
	v_mfma_f32_16x16x32_bf16 v[44:47], v[144:147], v[176:179], v[44:47]
	v_mfma_f32_16x16x32_bf16 v[40:43], v[160:163], v[176:179], v[40:43]
	v_mfma_f32_16x16x32_bf16 v[28:31], v[144:147], v[184:187], v[28:31]
	v_mfma_f32_16x16x32_bf16 v[24:27], v[160:163], v[184:187], v[24:27]
	v_mfma_f32_16x16x32_bf16 v[12:15], v[144:147], v[192:195], v[12:15]
	v_mfma_f32_16x16x32_bf16 v[8:11], v[160:163], v[192:195], v[8:11]
	v_mfma_f32_16x16x32_bf16 v[60:63], v[156:159], v[172:175], v[60:63]
	v_mfma_f32_16x16x32_bf16 v[56:59], v[164:167], v[172:175], v[56:59]
	v_mfma_f32_16x16x32_bf16 v[44:47], v[156:159], v[180:183], v[44:47]
	v_mfma_f32_16x16x32_bf16 v[40:43], v[164:167], v[180:183], v[40:43]
	v_mfma_f32_16x16x32_bf16 v[28:31], v[156:159], v[188:191], v[28:31]
	v_mfma_f32_16x16x32_bf16 v[24:27], v[164:167], v[188:191], v[24:27]
	v_mfma_f32_16x16x32_bf16 v[12:15], v[156:159], v[196:199], v[12:15]
	v_mfma_f32_16x16x32_bf16 v[8:11], v[164:167], v[196:199], v[8:11]
	v_mfma_f32_16x16x32_bf16 v[52:55], v[200:203], v[168:171], v[52:55]
	v_mfma_f32_16x16x32_bf16 v[48:51], v[208:211], v[168:171], v[48:51]
	v_mfma_f32_16x16x32_bf16 v[36:39], v[200:203], v[176:179], v[36:39]
	v_mfma_f32_16x16x32_bf16 v[32:35], v[208:211], v[176:179], v[32:35]
	v_mfma_f32_16x16x32_bf16 v[20:23], v[200:203], v[184:187], v[20:23]
	v_mfma_f32_16x16x32_bf16 v[16:19], v[208:211], v[184:187], v[16:19]
	v_mfma_f32_16x16x32_bf16 v[4:7], v[200:203], v[192:195], v[4:7]
	v_mfma_f32_16x16x32_bf16 v[0:3], v[208:211], v[192:195], v[0:3]
	v_mfma_f32_16x16x32_bf16 v[52:55], v[204:207], v[172:175], v[52:55]
	v_mfma_f32_16x16x32_bf16 v[48:51], v[212:215], v[172:175], v[48:51]
	v_mfma_f32_16x16x32_bf16 v[36:39], v[204:207], v[180:183], v[36:39]
	v_mfma_f32_16x16x32_bf16 v[32:35], v[212:215], v[180:183], v[32:35]
	v_mfma_f32_16x16x32_bf16 v[20:23], v[204:207], v[188:191], v[20:23]
	v_mfma_f32_16x16x32_bf16 v[16:19], v[212:215], v[188:191], v[16:19]
	v_mfma_f32_16x16x32_bf16 v[4:7], v[204:207], v[196:199], v[4:7]
	v_mfma_f32_16x16x32_bf16 v[0:3], v[212:215], v[196:199], v[0:3]
	s_barrier
; #define PG8_STAGE(bufoff, gbase, voff) do { _Pragma("unroll") for (int _i = 0; _i < 2; ++_i) \
;         __builtin_amdgcn_global_load_lds((const unsigned*)((const char*)(gbase) + (voff)[_i]), (PG8_LAS unsigned*)(lds + (bufoff) + ldsw + _i * 8192), 16, 0, 0); } while (0)
; #define PG8_LDA(dst, b, h) do { _Pragma("unroll") for (int m = 0; m < 4; ++m) _Pragma("unroll") for (int k = 0; k < 2; ++k) dst[m][k] = *(const PG8_LAS bf16x8*)(lds + PG8_SA(b, h) + aoff + m * 2048 + k * 1024); } while (0)
; #define PG8_LDB(dst, b, h) do { _Pragma("unroll") for (int n = 0; n < 2; ++n) _Pragma("unroll") for (int k = 0; k < 2; ++k) dst[n][k] = *(const PG8_LAS bf16x8*)(lds + PG8_SB(b, h) + boff + n * 2048 + k * 1024); } while (0)
; #define PG8_MMA(ai, bj, At, Bt) do { __builtin_amdgcn_s_setprio(1); _Pragma("unroll") for (int m = 0; m < 4; ++m) _Pragma("unroll") for (int n = 0; n < 2; ++n) _Pragma("unroll") for (int k = 0; k < 2; ++k) \
;         acc[ai][bj][m][n] = __builtin_amdgcn_mfma_f32_16x16x32_bf16(Bt[n][k], At[m][k], acc[ai][bj][m][n], 0, 0, 0); __builtin_amdgcn_s_setprio(0); } while (0)
; #define PG8_WAIT_V(n) asm volatile("s_waitcnt vmcnt(" #n ")" ::: "memory")
; #define PG8_WAIT_L(n) asm volatile("s_waitcnt lgkmcnt(" #n ")" ::: "memory")
; #define PG8_BAR __builtin_amdgcn_s_barrier()
; #define PG8_SCHED __builtin_amdgcn_sched_barrier(0)
; template <class Epi, class Sched>
; __device__ __forceinline__ void gemm_phase(PG8_LAS unsigned char* lds, const Gemm g, const Sched& S, const Epi& E) {
;     ...
;             PG8_LDB(B0, 1, 0); PG8_SCHED; PG8_LDA(At, 1, 0); PG8_STAGE(PG8_SA(0, 1), a2 + hstep, voffA);
;             PG8_WAIT_L(8); PG8_BAR; PG8_WAIT_L(0); PG8_MMA(0, 0, At, B0); PG8_BAR; PG8_SCHED;
;             PG8_LDB(B1, 1, 1); PG8_STAGE(PG8_SB(1, 0), b3, voffB);
;             PG8_BAR; PG8_WAIT_L(0); PG8_MMA(0, 1, At, B1); PG8_BAR;
;             PG8_LDA(At, 1, 1); PG8_STAGE(PG8_SA(1, 0), a3, voffA);
;             PG8_BAR; PG8_WAIT_L(0); PG8_MMA(1, 0, At, B0); PG8_BAR; PG8_SCHED;
;             PG8_STAGE(PG8_SB(1, 1), b3 + hstepB, voffB);
;             PG8_WAIT_V(6); PG8_BAR; PG8_MMA(1, 1, At, B1); PG8_BAR;
;         }
	s_add_i32 s68, 0, 0x18000
	v_add_u32_e32 v164, s68, v151
	ds_read_b128 v[144:147], v164
	ds_read_b128 v[156:159], v164 offset:1024
	ds_read_b128 v[160:163], v164 offset:2048
	ds_read_b128 v[164:167], v164 offset:3072
	s_add_u32 s24, s30, 0x158000
	s_addc_u32 s25, s31, 0
	s_mov_b32 m0, s53
	ds_read_b128 v[168:171], v154 offset:32768
	ds_read_b128 v[172:175], v154 offset:33792
	ds_read_b128 v[176:179], v154 offset:34816
	ds_read_b128 v[180:183], v154 offset:35840
	ds_read_b128 v[184:187], v154 offset:36864
	ds_read_b128 v[188:191], v154 offset:37888
	ds_read_b128 v[192:195], v154 offset:38912
	ds_read_b128 v[196:199], v154 offset:39936
	s_add_i32 s30, 0, 0x1c000
	v_add_u32_e32 v212, s30, v151
	ds_read_b128 v[200:203], v212
	ds_read_b128 v[204:207], v212 offset:1024
	ds_read_b128 v[208:211], v212 offset:2048
	ds_read_b128 v[212:215], v212 offset:3072
	global_load_lds_dwordx4 v130, s[24:25]
	s_mov_b32 m0, s54
	s_nop 0
	global_load_lds_dwordx4 v134, s[24:25]
	s_add_u32 s24, s28, 0x8000
	s_addc_u32 s25, s29, 0
	s_add_i32 s31, s68, s50
	s_mov_b32 m0, s31
	s_waitcnt vmcnt(8)
	s_waitcnt lgkmcnt(0)
	s_barrier
	v_mfma_f32_16x16x32_bf16 v[124:127], v[144:147], v[168:171], v[124:127]
	v_mfma_f32_16x16x32_bf16 v[120:123], v[160:163], v[168:171], v[120:123]
	v_mfma_f32_16x16x32_bf16 v[108:111], v[144:147], v[176:179], v[108:111]
	v_mfma_f32_16x16x32_bf16 v[104:107], v[160:163], v[176:179], v[104:107]
	v_mfma_f32_16x16x32_bf16 v[92:95], v[144:147], v[184:187], v[92:95]
	v_mfma_f32_16x16x32_bf16 v[88:91], v[160:163], v[184:187], v[88:91]
	v_mfma_f32_16x16x32_bf16 v[76:79], v[144:147], v[192:195], v[76:79]
	v_mfma_f32_16x16x32_bf16 v[72:75], v[160:163], v[192:195], v[72:75]
	v_mfma_f32_16x16x32_bf16 v[124:127], v[156:159], v[172:175], v[124:127]
	v_mfma_f32_16x16x32_bf16 v[120:123], v[164:167], v[172:175], v[120:123]
	v_mfma_f32_16x16x32_bf16 v[108:111], v[156:159], v[180:183], v[108:111]
	v_mfma_f32_16x16x32_bf16 v[104:107], v[164:167], v[180:183], v[104:107]
	v_mfma_f32_16x16x32_bf16 v[92:95], v[156:159], v[188:191], v[92:95]
	v_mfma_f32_16x16x32_bf16 v[88:91], v[164:167], v[188:191], v[88:91]
	v_mfma_f32_16x16x32_bf16 v[76:79], v[156:159], v[196:199], v[76:79]
	v_mfma_f32_16x16x32_bf16 v[72:75], v[164:167], v[196:199], v[72:75]
	v_mfma_f32_16x16x32_bf16 v[116:119], v[200:203], v[168:171], v[116:119]
	v_mfma_f32_16x16x32_bf16 v[112:115], v[208:211], v[168:171], v[112:115]
	v_mfma_f32_16x16x32_bf16 v[100:103], v[200:203], v[176:179], v[100:103]
	v_mfma_f32_16x16x32_bf16 v[96:99], v[208:211], v[176:179], v[96:99]
	v_mfma_f32_16x16x32_bf16 v[84:87], v[200:203], v[184:187], v[84:87]
	v_mfma_f32_16x16x32_bf16 v[80:83], v[208:211], v[184:187], v[80:83]
	v_mfma_f32_16x16x32_bf16 v[68:71], v[200:203], v[192:195], v[68:71]
	v_mfma_f32_16x16x32_bf16 v[64:67], v[208:211], v[192:195], v[64:67]
	v_mfma_f32_16x16x32_bf16 v[116:119], v[204:207], v[172:175], v[116:119]
	v_mfma_f32_16x16x32_bf16 v[112:115], v[212:215], v[172:175], v[112:115]
	v_mfma_f32_16x16x32_bf16 v[100:103], v[204:207], v[180:183], v[100:103]
	v_mfma_f32_16x16x32_bf16 v[96:99], v[212:215], v[180:183], v[96:99]
	v_mfma_f32_16x16x32_bf16 v[84:87], v[204:207], v[188:191], v[84:87]
	v_mfma_f32_16x16x32_bf16 v[80:83], v[212:215], v[188:191], v[80:83]
	v_mfma_f32_16x16x32_bf16 v[68:71], v[204:207], v[196:199], v[68:71]
	v_mfma_f32_16x16x32_bf16 v[64:67], v[212:215], v[196:199], v[64:67]
	s_barrier
	global_load_lds_dwordx4 v128, s[24:25]
	s_add_i32 m0, s31, 0x2000
	s_nop 0
	global_load_lds_dwordx4 v132, s[24:25]
	s_mov_b32 m0, s56
	v_lshl_add_u64 v[148:149], v[148:149], 0, s[14:15]
	ds_read_b128 v[168:171], v154 offset:49152
	ds_read_b128 v[172:175], v154 offset:50176
	ds_read_b128 v[176:179], v154 offset:51200
	ds_read_b128 v[180:183], v154 offset:52224
	ds_read_b128 v[184:187], v154 offset:53248
	ds_read_b128 v[188:191], v154 offset:54272
	ds_read_b128 v[192:195], v154 offset:55296
	ds_read_b128 v[196:199], v154 offset:56320
	global_load_lds_dwordx4 v[148:149], off
	v_lshl_add_u64 v[148:149], v[216:217], 0, s[14:15]
	s_mov_b32 m0, s57
	s_nop 0
	global_load_lds_dwordx4 v[148:149], off
	s_add_u32 s24, s28, 0xc000
	s_addc_u32 s25, s29, 0
	s_add_i32 s28, s30, s50
	s_mov_b32 m0, s28
	s_nop 0
	global_load_lds_dwordx4 v128, s[24:25]
	s_add_i32 m0, s28, 0x2000
	s_nop 0
	global_load_lds_dwordx4 v132, s[24:25]
	s_add_i32 s67, s67, 2
	s_add_u32 s65, s65, 0x10000
	s_addc_u32 s66, s66, 0
	s_cmpk_gt_u32 s67, 0x53
	s_mov_b64 s[24:25], s[26:27]
	s_waitcnt vmcnt(8)
	s_waitcnt lgkmcnt(0)
	s_barrier
	v_mfma_f32_16x16x32_bf16 v[60:63], v[144:147], v[168:171], v[60:63]
	v_mfma_f32_16x16x32_bf16 v[56:59], v[160:163], v[168:171], v[56:59]
	v_mfma_f32_16x16x32_bf16 v[44:47], v[144:147], v[176:179], v[44:47]
	v_mfma_f32_16x16x32_bf16 v[40:43], v[160:163], v[176:179], v[40:43]
	v_mfma_f32_16x16x32_bf16 v[28:31], v[144:147], v[184:187], v[28:31]
	v_mfma_f32_16x16x32_bf16 v[24:27], v[160:163], v[184:187], v[24:27]
	v_mfma_f32_16x16x32_bf16 v[12:15], v[144:147], v[192:195], v[12:15]
	v_mfma_f32_16x16x32_bf16 v[8:11], v[160:163], v[192:195], v[8:11]
	v_mfma_f32_16x16x32_bf16 v[60:63], v[156:159], v[172:175], v[60:63]
	v_mfma_f32_16x16x32_bf16 v[56:59], v[164:167], v[172:175], v[56:59]
	v_mfma_f32_16x16x32_bf16 v[44:47], v[156:159], v[180:183], v[44:47]
	v_mfma_f32_16x16x32_bf16 v[40:43], v[164:167], v[180:183], v[40:43]
	v_mfma_f32_16x16x32_bf16 v[28:31], v[156:159], v[188:191], v[28:31]
	v_mfma_f32_16x16x32_bf16 v[24:27], v[164:167], v[188:191], v[24:27]
	v_mfma_f32_16x16x32_bf16 v[12:15], v[156:159], v[196:199], v[12:15]
	v_mfma_f32_16x16x32_bf16 v[8:11], v[164:167], v[196:199], v[8:11]
	v_mfma_f32_16x16x32_bf16 v[52:55], v[200:203], v[168:171], v[52:55]
	v_mfma_f32_16x16x32_bf16 v[48:51], v[208:211], v[168:171], v[48:51]
	v_mfma_f32_16x16x32_bf16 v[36:39], v[200:203], v[176:179], v[36:39]
	v_mfma_f32_16x16x32_bf16 v[32:35], v[208:211], v[176:179], v[32:35]
	v_mfma_f32_16x16x32_bf16 v[20:23], v[200:203], v[184:187], v[20:23]
	v_mfma_f32_16x16x32_bf16 v[16:19], v[208:211], v[184:187], v[16:19]
	v_mfma_f32_16x16x32_bf16 v[4:7], v[200:203], v[192:195], v[4:7]
	v_mfma_f32_16x16x32_bf16 v[0:3], v[208:211], v[192:195], v[0:3]
	v_mfma_f32_16x16x32_bf16 v[52:55], v[204:207], v[172:175], v[52:55]
	v_mfma_f32_16x16x32_bf16 v[48:51], v[212:215], v[172:175], v[48:51]
	v_mfma_f32_16x16x32_bf16 v[36:39], v[204:207], v[180:183], v[36:39]
	v_mfma_f32_16x16x32_bf16 v[32:35], v[212:215], v[180:183], v[32:35]
	s_cbranch_scc1 .Lunit_exit_1
	v_mfma_f32_16x16x32_bf16 v[20:23], v[204:207], v[188:191], v[20:23]
	v_mfma_f32_16x16x32_bf16 v[16:19], v[212:215], v[188:191], v[16:19]
	v_mfma_f32_16x16x32_bf16 v[4:7], v[204:207], v[196:199], v[4:7]
	v_mfma_f32_16x16x32_bf16 v[0:3], v[212:215], v[196:199], v[0:3]
	s_barrier
	s_branch .LBB0_155

; #define PG8_STAGE(bufoff, gbase, voff) do { _Pragma("unroll") for (int _i = 0; _i < 2; ++_i) \
;         __builtin_amdgcn_global_load_lds((const unsigned*)((const char*)(gbase) + (voff)[_i]), (PG8_LAS unsigned*)(lds + (bufoff) + ldsw + _i * 8192), 16, 0, 0); } while (0)
; #define PG8_LDA(dst, b, h) do { _Pragma("unroll") for (int m = 0; m < 4; ++m) _Pragma("unroll") for (int k = 0; k < 2; ++k) dst[m][k] = *(const PG8_LAS bf16x8*)(lds + PG8_SA(b, h) + aoff + m * 2048 + k * 1024); } while (0)
; #define PG8_LDB(dst, b, h) do { _Pragma("unroll") for (int n = 0; n < 2; ++n) _Pragma("unroll") for (int k = 0; k < 2; ++k) dst[n][k] = *(const PG8_LAS bf16x8*)(lds + PG8_SB(b, h) + boff + n * 2048 + k * 1024); } while (0)
; #define PG8_MMA(ai, bj, At, Bt) do { __builtin_amdgcn_s_setprio(1); _Pragma("unroll") for (int m = 0; m < 4; ++m) _Pragma("unroll") for (int n = 0; n < 2; ++n) _Pragma("unroll") for (int k = 0; k < 2; ++k) \
;         acc[ai][bj][m][n] = __builtin_amdgcn_mfma_f32_16x16x32_bf16(Bt[n][k], At[m][k], acc[ai][bj][m][n], 0, 0, 0); __builtin_amdgcn_s_setprio(0); } while (0)
; #define PG8_WAIT_V(n) asm volatile("s_waitcnt vmcnt(" #n ")" ::: "memory")
; template <class Epi, class Sched>
; __device__ __forceinline__ void gemm_phase(PG8_LAS unsigned char* lds, const Gemm g, const Sched& S, const Epi& E) {
;     ...
;         for (int t = 0; t < nt; t += 2) {
;             const bool last = (t == nt - 2);
;             const char* a1 = cA + (size_t)(t + 1) * kstep;
;             const char* a2 = last ? nA : cA + (size_t)(t + 2) * kstep; const char* b2 = last ? nB : cB + (size_t)(t + 2) * kstepB;
;             const char* a3 = a2 + kstep; const char* b3 = b2 + kstepB;
;             if (last && has_next) S.a_ready(nxt);
;             PG8_LDB(B0, 0, 0); PG8_SCHED; PG8_LDA(At, 0, 0); PG8_STAGE(PG8_SA(1, 1), a1 + hstep, voffA);
;             PG8_WAIT_L(8); PG8_BAR; PG8_WAIT_L(0); PG8_MMA(0, 0, At, B0); PG8_BAR; PG8_SCHED;
;             PG8_LDB(B1, 0, 1); PG8_STAGE(PG8_SB(0, 0), b2, voffB);
;             PG8_BAR; PG8_WAIT_L(0); PG8_MMA(0, 1, At, B1); PG8_BAR;
;             PG8_LDA(At, 0, 1); PG8_STAGE(PG8_SA(0, 0), a2, voffA);
;             PG8_BAR; PG8_WAIT_L(0); PG8_MMA(1, 0, At, B0); PG8_BAR; PG8_SCHED;
;             PG8_STAGE(PG8_SB(0, 1), b2 + hstepB, voffB);
;             PG8_WAIT_V(6); PG8_BAR; PG8_MMA(1, 1, At, B1); PG8_BAR;
.Lhalf_skip_y_2:
.LBB0_280:
	ds_read_b128 v[150:153], v147
	ds_read_b128 v[154:157], v147 offset:1024
	ds_read_b128 v[158:161], v147 offset:2048
	ds_read_b128 v[162:165], v147 offset:3072
	s_add_u32 s48, s6, 0xfff80080
	s_addc_u32 s49, s7, -1
	s_cmp_eq_u32 s69, 28
	s_cselect_b32 s51, s9, s49
	s_cselect_b32 s50, s29, s48
	s_cselect_b32 s49, s31, s68
	s_cselect_b32 s48, s47, s67
	s_add_i32 m0, s54, 0xc000
	ds_read_b128 v[166:169], v148
	ds_read_b128 v[170:173], v148 offset:1024
	ds_read_b128 v[174:177], v148 offset:2048
	ds_read_b128 v[178:181], v148 offset:3072
	ds_read_b128 v[182:185], v148 offset:4096
	ds_read_b128 v[186:189], v148 offset:5120
	ds_read_b128 v[190:193], v148 offset:6144
	ds_read_b128 v[194:197], v148 offset:7168
	ds_read_b128 v[198:201], v149
	ds_read_b128 v[202:205], v149 offset:1024
	ds_read_b128 v[206:209], v149 offset:2048
	ds_read_b128 v[210:213], v149 offset:3072
	global_load_lds_dwordx4 v136, s[6:7]
	s_add_i32 m0, s54, 0xe000
	s_nop 0
	global_load_lds_dwordx4 v138, s[6:7]
	s_add_i32 s70, s63, s53
	s_mov_b32 m0, s70
	s_waitcnt vmcnt(8)
	s_waitcnt lgkmcnt(0)
	s_barrier
	v_mfma_f32_16x16x32_bf16 v[124:127], v[150:153], v[166:169], v[124:127]
	v_mfma_f32_16x16x32_bf16 v[120:123], v[158:161], v[166:169], v[120:123]
	v_mfma_f32_16x16x32_bf16 v[108:111], v[150:153], v[174:177], v[108:111]
	v_mfma_f32_16x16x32_bf16 v[104:107], v[158:161], v[174:177], v[104:107]
	v_mfma_f32_16x16x32_bf16 v[92:95], v[150:153], v[182:185], v[92:95]
	v_mfma_f32_16x16x32_bf16 v[88:91], v[158:161], v[182:185], v[88:91]
	v_mfma_f32_16x16x32_bf16 v[76:79], v[150:153], v[190:193], v[76:79]
	v_mfma_f32_16x16x32_bf16 v[72:75], v[158:161], v[190:193], v[72:75]
	v_mfma_f32_16x16x32_bf16 v[124:127], v[154:157], v[170:173], v[124:127]
	v_mfma_f32_16x16x32_bf16 v[120:123], v[162:165], v[170:173], v[120:123]
	v_mfma_f32_16x16x32_bf16 v[108:111], v[154:157], v[178:181], v[108:111]
	v_mfma_f32_16x16x32_bf16 v[104:107], v[162:165], v[178:181], v[104:107]
	v_mfma_f32_16x16x32_bf16 v[92:95], v[154:157], v[186:189], v[92:95]
	v_mfma_f32_16x16x32_bf16 v[88:91], v[162:165], v[186:189], v[88:91]
	v_mfma_f32_16x16x32_bf16 v[76:79], v[154:157], v[194:197], v[76:79]
	v_mfma_f32_16x16x32_bf16 v[72:75], v[162:165], v[194:197], v[72:75]
	v_mfma_f32_16x16x32_bf16 v[116:119], v[198:201], v[166:169], v[116:119]
	v_mfma_f32_16x16x32_bf16 v[112:115], v[206:209], v[166:169], v[112:115]
	v_mfma_f32_16x16x32_bf16 v[100:103], v[198:201], v[174:177], v[100:103]
	v_mfma_f32_16x16x32_bf16 v[96:99], v[206:209], v[174:177], v[96:99]
	v_mfma_f32_16x16x32_bf16 v[84:87], v[198:201], v[182:185], v[84:87]
	v_mfma_f32_16x16x32_bf16 v[80:83], v[206:209], v[182:185], v[80:83]
	v_mfma_f32_16x16x32_bf16 v[68:71], v[198:201], v[190:193], v[68:71]
	v_mfma_f32_16x16x32_bf16 v[64:67], v[206:209], v[190:193], v[64:67]
	v_mfma_f32_16x16x32_bf16 v[116:119], v[202:205], v[170:173], v[116:119]
	v_mfma_f32_16x16x32_bf16 v[112:115], v[210:213], v[170:173], v[112:115]
	v_mfma_f32_16x16x32_bf16 v[100:103], v[202:205], v[178:181], v[100:103]
	v_mfma_f32_16x16x32_bf16 v[96:99], v[210:213], v[178:181], v[96:99]
	v_mfma_f32_16x16x32_bf16 v[84:87], v[202:205], v[186:189], v[84:87]
	v_mfma_f32_16x16x32_bf16 v[80:83], v[210:213], v[186:189], v[80:83]
	v_mfma_f32_16x16x32_bf16 v[68:71], v[202:205], v[194:197], v[68:71]
	v_mfma_f32_16x16x32_bf16 v[64:67], v[210:213], v[194:197], v[64:67]
	s_barrier
	global_load_lds_dwordx4 v128, s[48:49]
	s_add_i32 m0, s70, 0x2000
	s_nop 0
	global_load_lds_dwordx4 v132, s[48:49]
	s_mov_b32 m0, s54
	v_lshl_add_u64 v[214:215], s[50:51], 0, v[130:131]
	ds_read_b128 v[166:169], v148 offset:16384
	ds_read_b128 v[170:173], v148 offset:17408
	ds_read_b128 v[174:177], v148 offset:18432
	ds_read_b128 v[178:181], v148 offset:19456
	ds_read_b128 v[182:185], v148 offset:20480
	ds_read_b128 v[186:189], v148 offset:21504
	ds_read_b128 v[190:193], v148 offset:22528
	ds_read_b128 v[194:197], v148 offset:23552
	global_load_lds_dwordx4 v[214:215], off
	v_lshl_add_u64 v[216:217], s[50:51], 0, v[134:135]
	s_mov_b32 m0, s55
	s_nop 0
	global_load_lds_dwordx4 v[216:217], off
	s_add_u32 s70, s48, 0x4000
	s_addc_u32 s71, s49, 0
	s_add_i32 s72, s64, s53
	s_mov_b32 m0, s72
	s_nop 0
	global_load_lds_dwordx4 v128, s[70:71]
	s_add_i32 m0, s72, 0x2000
	s_nop 0
	global_load_lds_dwordx4 v132, s[70:71]
	s_waitcnt vmcnt(8)
	s_waitcnt lgkmcnt(0)
	s_barrier
	v_mfma_f32_16x16x32_bf16 v[60:63], v[150:153], v[166:169], v[60:63]
	v_mfma_f32_16x16x32_bf16 v[56:59], v[158:161], v[166:169], v[56:59]
	v_mfma_f32_16x16x32_bf16 v[44:47], v[150:153], v[174:177], v[44:47]
	v_mfma_f32_16x16x32_bf16 v[40:43], v[158:161], v[174:177], v[40:43]
	v_mfma_f32_16x16x32_bf16 v[28:31], v[150:153], v[182:185], v[28:31]
	v_mfma_f32_16x16x32_bf16 v[24:27], v[158:161], v[182:185], v[24:27]
	v_mfma_f32_16x16x32_bf16 v[12:15], v[150:153], v[190:193], v[12:15]
	v_mfma_f32_16x16x32_bf16 v[8:11], v[158:161], v[190:193], v[8:11]
	v_mfma_f32_16x16x32_bf16 v[60:63], v[154:157], v[170:173], v[60:63]
	v_mfma_f32_16x16x32_bf16 v[56:59], v[162:165], v[170:173], v[56:59]
	v_mfma_f32_16x16x32_bf16 v[44:47], v[154:157], v[178:181], v[44:47]
	v_mfma_f32_16x16x32_bf16 v[40:43], v[162:165], v[178:181], v[40:43]
	v_mfma_f32_16x16x32_bf16 v[28:31], v[154:157], v[186:189], v[28:31]
	v_mfma_f32_16x16x32_bf16 v[24:27], v[162:165], v[186:189], v[24:27]
	v_mfma_f32_16x16x32_bf16 v[12:15], v[154:157], v[194:197], v[12:15]
	v_mfma_f32_16x16x32_bf16 v[8:11], v[162:165], v[194:197], v[8:11]
	v_mfma_f32_16x16x32_bf16 v[52:55], v[198:201], v[166:169], v[52:55]
	v_mfma_f32_16x16x32_bf16 v[48:51], v[206:209], v[166:169], v[48:51]
	v_mfma_f32_16x16x32_bf16 v[36:39], v[198:201], v[174:177], v[36:39]
	v_mfma_f32_16x16x32_bf16 v[32:35], v[206:209], v[174:177], v[32:35]
	v_mfma_f32_16x16x32_bf16 v[20:23], v[198:201], v[182:185], v[20:23]
	v_mfma_f32_16x16x32_bf16 v[16:19], v[206:209], v[182:185], v[16:19]
	v_mfma_f32_16x16x32_bf16 v[4:7], v[198:201], v[190:193], v[4:7]
	v_mfma_f32_16x16x32_bf16 v[0:3], v[206:209], v[190:193], v[0:3]
	v_mfma_f32_16x16x32_bf16 v[52:55], v[202:205], v[170:173], v[52:55]
	v_mfma_f32_16x16x32_bf16 v[48:51], v[210:213], v[170:173], v[48:51]
	v_mfma_f32_16x16x32_bf16 v[36:39], v[202:205], v[178:181], v[36:39]
	v_mfma_f32_16x16x32_bf16 v[32:35], v[210:213], v[178:181], v[32:35]
	v_mfma_f32_16x16x32_bf16 v[20:23], v[202:205], v[186:189], v[20:23]
	v_mfma_f32_16x16x32_bf16 v[16:19], v[210:213], v[186:189], v[16:19]
	v_mfma_f32_16x16x32_bf16 v[4:7], v[202:205], v[194:197], v[4:7]
	v_mfma_f32_16x16x32_bf16 v[0:3], v[210:213], v[194:197], v[0:3]
	s_barrier
; #define PG8_STAGE(bufoff, gbase, voff) do { _Pragma("unroll") for (int _i = 0; _i < 2; ++_i) \
;         __builtin_amdgcn_global_load_lds((const unsigned*)((const char*)(gbase) + (voff)[_i]), (PG8_LAS unsigned*)(lds + (bufoff) + ldsw + _i * 8192), 16, 0, 0); } while (0)
; #define PG8_LDA(dst, b, h) do { _Pragma("unroll") for (int m = 0; m < 4; ++m) _Pragma("unroll") for (int k = 0; k < 2; ++k) dst[m][k] = *(const PG8_LAS bf16x8*)(lds + PG8_SA(b, h) + aoff + m * 2048 + k * 1024); } while (0)
; #define PG8_LDB(dst, b, h) do { _Pragma("unroll") for (int n = 0; n < 2; ++n) _Pragma("unroll") for (int k = 0; k < 2; ++k) dst[n][k] = *(const PG8_LAS bf16x8*)(lds + PG8_SB(b, h) + boff + n * 2048 + k * 1024); } while (0)
; #define PG8_MMA(ai, bj, At, Bt) do { __builtin_amdgcn_s_setprio(1); _Pragma("unroll") for (int m = 0; m < 4; ++m) _Pragma("unroll") for (int n = 0; n < 2; ++n) _Pragma("unroll") for (int k = 0; k < 2; ++k) \
;         acc[ai][bj][m][n] = __builtin_amdgcn_mfma_f32_16x16x32_bf16(Bt[n][k], At[m][k], acc[ai][bj][m][n], 0, 0, 0); __builtin_amdgcn_s_setprio(0); } while (0)
; #define PG8_WAIT_V(n) asm volatile("s_waitcnt vmcnt(" #n ")" ::: "memory")
; #define PG8_WAIT_L(n) asm volatile("s_waitcnt lgkmcnt(" #n ")" ::: "memory")
; #define PG8_BAR __builtin_amdgcn_s_barrier()
; #define PG8_SCHED __builtin_amdgcn_sched_barrier(0)
; template <class Epi, class Sched>
; __device__ __forceinline__ void gemm_phase(PG8_LAS unsigned char* lds, const Gemm g, const Sched& S, const Epi& E) {
;     ...
;             PG8_LDB(B0, 1, 0); PG8_SCHED; PG8_LDA(At, 1, 0); PG8_STAGE(PG8_SA(0, 1), a2 + hstep, voffA);
;             PG8_WAIT_L(8); PG8_BAR; PG8_WAIT_L(0); PG8_MMA(0, 0, At, B0); PG8_BAR; PG8_SCHED;
;             PG8_LDB(B1, 1, 1); PG8_STAGE(PG8_SB(1, 0), b3, voffB);
;             PG8_BAR; PG8_WAIT_L(0); PG8_MMA(0, 1, At, B1); PG8_BAR;
;             PG8_LDA(At, 1, 1); PG8_STAGE(PG8_SA(1, 0), a3, voffA);
;             PG8_BAR; PG8_WAIT_L(0); PG8_MMA(1, 0, At, B0); PG8_BAR; PG8_SCHED;
;             PG8_STAGE(PG8_SB(1, 1), b3 + hstepB, voffB);
;             PG8_WAIT_V(6); PG8_BAR; PG8_MMA(1, 1, At, B1); PG8_BAR;
;         }
	s_add_i32 s70, 0, 0x18000
	v_add_u32_e32 v162, s70, v145
	ds_read_b128 v[150:153], v162
	ds_read_b128 v[154:157], v162 offset:1024
	ds_read_b128 v[158:161], v162 offset:2048
	ds_read_b128 v[162:165], v162 offset:3072
	s_add_u32 s50, s50, 0x80000
	s_addc_u32 s51, s51, 0
	s_mov_b32 m0, s56
	ds_read_b128 v[166:169], v148 offset:32768
	ds_read_b128 v[170:173], v148 offset:33792
	ds_read_b128 v[174:177], v148 offset:34816
	ds_read_b128 v[178:181], v148 offset:35840
	ds_read_b128 v[182:185], v148 offset:36864
	ds_read_b128 v[186:189], v148 offset:37888
	ds_read_b128 v[190:193], v148 offset:38912
	ds_read_b128 v[194:197], v148 offset:39936
	s_add_i32 s71, 0, 0x1c000
	v_add_u32_e32 v210, s71, v145
	ds_read_b128 v[198:201], v210
	ds_read_b128 v[202:205], v210 offset:1024
	ds_read_b128 v[206:209], v210 offset:2048
	ds_read_b128 v[210:213], v210 offset:3072
	global_load_lds_dwordx4 v130, s[50:51]
	s_mov_b32 m0, s57
	s_nop 0
	global_load_lds_dwordx4 v134, s[50:51]
	s_add_u32 s50, s48, 0x8000
	s_addc_u32 s51, s49, 0
	s_add_i32 s70, s70, s53
	s_mov_b32 m0, s70
	s_waitcnt vmcnt(8)
	s_waitcnt lgkmcnt(0)
	s_barrier
	v_mfma_f32_16x16x32_bf16 v[124:127], v[150:153], v[166:169], v[124:127]
	v_mfma_f32_16x16x32_bf16 v[120:123], v[158:161], v[166:169], v[120:123]
	v_mfma_f32_16x16x32_bf16 v[108:111], v[150:153], v[174:177], v[108:111]
	v_mfma_f32_16x16x32_bf16 v[104:107], v[158:161], v[174:177], v[104:107]
	v_mfma_f32_16x16x32_bf16 v[92:95], v[150:153], v[182:185], v[92:95]
	v_mfma_f32_16x16x32_bf16 v[88:91], v[158:161], v[182:185], v[88:91]
	v_mfma_f32_16x16x32_bf16 v[76:79], v[150:153], v[190:193], v[76:79]
	v_mfma_f32_16x16x32_bf16 v[72:75], v[158:161], v[190:193], v[72:75]
	v_mfma_f32_16x16x32_bf16 v[124:127], v[154:157], v[170:173], v[124:127]
	v_mfma_f32_16x16x32_bf16 v[120:123], v[162:165], v[170:173], v[120:123]
	v_mfma_f32_16x16x32_bf16 v[108:111], v[154:157], v[178:181], v[108:111]
	v_mfma_f32_16x16x32_bf16 v[104:107], v[162:165], v[178:181], v[104:107]
	v_mfma_f32_16x16x32_bf16 v[92:95], v[154:157], v[186:189], v[92:95]
	v_mfma_f32_16x16x32_bf16 v[88:91], v[162:165], v[186:189], v[88:91]
	v_mfma_f32_16x16x32_bf16 v[76:79], v[154:157], v[194:197], v[76:79]
	v_mfma_f32_16x16x32_bf16 v[72:75], v[162:165], v[194:197], v[72:75]
	v_mfma_f32_16x16x32_bf16 v[116:119], v[198:201], v[166:169], v[116:119]
	v_mfma_f32_16x16x32_bf16 v[112:115], v[206:209], v[166:169], v[112:115]
	v_mfma_f32_16x16x32_bf16 v[100:103], v[198:201], v[174:177], v[100:103]
	v_mfma_f32_16x16x32_bf16 v[96:99], v[206:209], v[174:177], v[96:99]
	v_mfma_f32_16x16x32_bf16 v[84:87], v[198:201], v[182:185], v[84:87]
	v_mfma_f32_16x16x32_bf16 v[80:83], v[206:209], v[182:185], v[80:83]
	v_mfma_f32_16x16x32_bf16 v[68:71], v[198:201], v[190:193], v[68:71]
	v_mfma_f32_16x16x32_bf16 v[64:67], v[206:209], v[190:193], v[64:67]
	v_mfma_f32_16x16x32_bf16 v[116:119], v[202:205], v[170:173], v[116:119]
	v_mfma_f32_16x16x32_bf16 v[112:115], v[210:213], v[170:173], v[112:115]
	v_mfma_f32_16x16x32_bf16 v[100:103], v[202:205], v[178:181], v[100:103]
	v_mfma_f32_16x16x32_bf16 v[96:99], v[210:213], v[178:181], v[96:99]
	v_mfma_f32_16x16x32_bf16 v[84:87], v[202:205], v[186:189], v[84:87]
	v_mfma_f32_16x16x32_bf16 v[80:83], v[210:213], v[186:189], v[80:83]
	v_mfma_f32_16x16x32_bf16 v[68:71], v[202:205], v[194:197], v[68:71]
	v_mfma_f32_16x16x32_bf16 v[64:67], v[210:213], v[194:197], v[64:67]
	s_barrier
	global_load_lds_dwordx4 v128, s[50:51]
	s_add_i32 m0, s70, 0x2000
	s_nop 0
	global_load_lds_dwordx4 v132, s[50:51]
	s_mov_b32 m0, s59
	v_lshl_add_u64 v[214:215], v[214:215], 0, s[12:13]
	ds_read_b128 v[166:169], v148 offset:49152
	ds_read_b128 v[170:173], v148 offset:50176
	ds_read_b128 v[174:177], v148 offset:51200
	ds_read_b128 v[178:181], v148 offset:52224
	ds_read_b128 v[182:185], v148 offset:53248
	ds_read_b128 v[186:189], v148 offset:54272
	ds_read_b128 v[190:193], v148 offset:55296
	ds_read_b128 v[194:197], v148 offset:56320
	global_load_lds_dwordx4 v[214:215], off
	v_lshl_add_u64 v[214:215], v[216:217], 0, s[12:13]
	s_mov_b32 m0, s60
	s_nop 0
	global_load_lds_dwordx4 v[214:215], off
	s_add_u32 s48, s48, 0xc000
	s_addc_u32 s49, s49, 0
	s_add_i32 s50, s71, s53
	s_mov_b32 m0, s50
	s_nop 0
	global_load_lds_dwordx4 v128, s[48:49]
	s_add_i32 m0, s50, 0x2000
	s_nop 0
	global_load_lds_dwordx4 v132, s[48:49]
	s_add_i32 s69, s69, 2
	s_add_u32 s67, s67, 0x10000
	s_addc_u32 s68, s68, 0
	s_add_u32 s6, s6, 0x100
	s_addc_u32 s7, s7, 0
	s_cmp_gt_u32 s69, 29
	s_waitcnt vmcnt(8)
	s_waitcnt lgkmcnt(0)
	s_barrier
	v_mfma_f32_16x16x32_bf16 v[60:63], v[150:153], v[166:169], v[60:63]
	v_mfma_f32_16x16x32_bf16 v[56:59], v[158:161], v[166:169], v[56:59]
	v_mfma_f32_16x16x32_bf16 v[44:47], v[150:153], v[174:177], v[44:47]
	v_mfma_f32_16x16x32_bf16 v[40:43], v[158:161], v[174:177], v[40:43]
	v_mfma_f32_16x16x32_bf16 v[28:31], v[150:153], v[182:185], v[28:31]
	v_mfma_f32_16x16x32_bf16 v[24:27], v[158:161], v[182:185], v[24:27]
	v_mfma_f32_16x16x32_bf16 v[12:15], v[150:153], v[190:193], v[12:15]
	v_mfma_f32_16x16x32_bf16 v[8:11], v[158:161], v[190:193], v[8:11]
	v_mfma_f32_16x16x32_bf16 v[60:63], v[154:157], v[170:173], v[60:63]
	v_mfma_f32_16x16x32_bf16 v[56:59], v[162:165], v[170:173], v[56:59]
	v_mfma_f32_16x16x32_bf16 v[44:47], v[154:157], v[178:181], v[44:47]
	v_mfma_f32_16x16x32_bf16 v[40:43], v[162:165], v[178:181], v[40:43]
	v_mfma_f32_16x16x32_bf16 v[28:31], v[154:157], v[186:189], v[28:31]
	v_mfma_f32_16x16x32_bf16 v[24:27], v[162:165], v[186:189], v[24:27]
	v_mfma_f32_16x16x32_bf16 v[12:15], v[154:157], v[194:197], v[12:15]
	v_mfma_f32_16x16x32_bf16 v[8:11], v[162:165], v[194:197], v[8:11]
	v_mfma_f32_16x16x32_bf16 v[52:55], v[198:201], v[166:169], v[52:55]
	v_mfma_f32_16x16x32_bf16 v[48:51], v[206:209], v[166:169], v[48:51]
	v_mfma_f32_16x16x32_bf16 v[36:39], v[198:201], v[174:177], v[36:39]
	v_mfma_f32_16x16x32_bf16 v[32:35], v[206:209], v[174:177], v[32:35]
	v_mfma_f32_16x16x32_bf16 v[20:23], v[198:201], v[182:185], v[20:23]
	v_mfma_f32_16x16x32_bf16 v[16:19], v[206:209], v[182:185], v[16:19]
	v_mfma_f32_16x16x32_bf16 v[4:7], v[198:201], v[190:193], v[4:7]
	v_mfma_f32_16x16x32_bf16 v[0:3], v[206:209], v[190:193], v[0:3]
	v_mfma_f32_16x16x32_bf16 v[52:55], v[202:205], v[170:173], v[52:55]
	v_mfma_f32_16x16x32_bf16 v[48:51], v[210:213], v[170:173], v[48:51]
	v_mfma_f32_16x16x32_bf16 v[36:39], v[202:205], v[178:181], v[36:39]
	v_mfma_f32_16x16x32_bf16 v[32:35], v[210:213], v[178:181], v[32:35]
	s_cbranch_scc1 .Lunit_exit_2
	v_mfma_f32_16x16x32_bf16 v[20:23], v[202:205], v[186:189], v[20:23]
	v_mfma_f32_16x16x32_bf16 v[16:19], v[210:213], v[186:189], v[16:19]
	v_mfma_f32_16x16x32_bf16 v[4:7], v[202:205], v[194:197], v[4:7]
	v_mfma_f32_16x16x32_bf16 v[0:3], v[210:213], v[194:197], v[0:3]
	s_barrier
	s_branch .LBB0_280

; #define PG8_STAGE(bufoff, gbase, voff) do { _Pragma("unroll") for (int _i = 0; _i < 2; ++_i) \
;         __builtin_amdgcn_global_load_lds((const unsigned*)((const char*)(gbase) + (voff)[_i]), (PG8_LAS unsigned*)(lds + (bufoff) + ldsw + _i * 8192), 16, 0, 0); } while (0)
; #define PG8_LDA(dst, b, h) do { _Pragma("unroll") for (int m = 0; m < 4; ++m) _Pragma("unroll") for (int k = 0; k < 2; ++k) dst[m][k] = *(const PG8_LAS bf16x8*)(lds + PG8_SA(b, h) + aoff + m * 2048 + k * 1024); } while (0)
; #define PG8_LDB(dst, b, h) do { _Pragma("unroll") for (int n = 0; n < 2; ++n) _Pragma("unroll") for (int k = 0; k < 2; ++k) dst[n][k] = *(const PG8_LAS bf16x8*)(lds + PG8_SB(b, h) + boff + n * 2048 + k * 1024); } while (0)
; #define PG8_MMA(ai, bj, At, Bt) do { __builtin_amdgcn_s_setprio(1); _Pragma("unroll") for (int m = 0; m < 4; ++m) _Pragma("unroll") for (int n = 0; n < 2; ++n) _Pragma("unroll") for (int k = 0; k < 2; ++k) \
;         acc[ai][bj][m][n] = __builtin_amdgcn_mfma_f32_16x16x32_bf16(Bt[n][k], At[m][k], acc[ai][bj][m][n], 0, 0, 0); __builtin_amdgcn_s_setprio(0); } while (0)
; #define PG8_WAIT_V(n) asm volatile("s_waitcnt vmcnt(" #n ")" ::: "memory")
; template <class Epi, class Sched>
; __device__ __forceinline__ void gemm_phase(PG8_LAS unsigned char* lds, const Gemm g, const Sched& S, const Epi& E) {
;     ...
;         for (int t = 0; t < nt; t += 2) {
;             const bool last = (t == nt - 2);
;             const char* a1 = cA + (size_t)(t + 1) * kstep;
;             const char* a2 = last ? nA : cA + (size_t)(t + 2) * kstep; const char* b2 = last ? nB : cB + (size_t)(t + 2) * kstepB;
;             const char* a3 = a2 + kstep; const char* b3 = b2 + kstepB;
;             if (last && has_next) S.a_ready(nxt);
;             PG8_LDB(B0, 0, 0); PG8_SCHED; PG8_LDA(At, 0, 0); PG8_STAGE(PG8_SA(1, 1), a1 + hstep, voffA);
;             PG8_WAIT_L(8); PG8_BAR; PG8_WAIT_L(0); PG8_MMA(0, 0, At, B0); PG8_BAR; PG8_SCHED;
;             PG8_LDB(B1, 0, 1); PG8_STAGE(PG8_SB(0, 0), b2, voffB);
;             PG8_BAR; PG8_WAIT_L(0); PG8_MMA(0, 1, At, B1); PG8_BAR;
;             PG8_LDA(At, 0, 1); PG8_STAGE(PG8_SA(0, 0), a2, voffA);
;             PG8_BAR; PG8_WAIT_L(0); PG8_MMA(1, 0, At, B0); PG8_BAR; PG8_SCHED;
;             PG8_STAGE(PG8_SB(0, 1), b2 + hstepB, voffB);
;             PG8_WAIT_V(6); PG8_BAR; PG8_MMA(1, 1, At, B1); PG8_BAR;
.Lhalf_skip_y_3:
.LBB0_397:
	ds_read_b128 v[142:145], v150
	ds_read_b128 v[154:157], v150 offset:1024
	ds_read_b128 v[158:161], v150 offset:2048
	ds_read_b128 v[162:165], v150 offset:3072
	s_add_u32 s26, s24, 0xfff80080
	s_addc_u32 s27, s25, -1
	s_cmp_eq_u32 s66, 28
	s_cselect_b32 s29, s5, s27
	s_cselect_b32 s28, s15, s26
	s_cselect_b32 s27, s17, s65
	s_cselect_b32 s26, s23, s64
	s_add_i32 m0, s48, 0xc000
	ds_read_b128 v[166:169], v151
	ds_read_b128 v[170:173], v151 offset:1024
	ds_read_b128 v[174:177], v151 offset:2048
	ds_read_b128 v[178:181], v151 offset:3072
	ds_read_b128 v[182:185], v151 offset:4096
	ds_read_b128 v[186:189], v151 offset:5120
	ds_read_b128 v[190:193], v151 offset:6144
	ds_read_b128 v[194:197], v151 offset:7168
	ds_read_b128 v[198:201], v152
	ds_read_b128 v[202:205], v152 offset:1024
	ds_read_b128 v[206:209], v152 offset:2048
	ds_read_b128 v[210:213], v152 offset:3072
	global_load_lds_dwordx4 v138, s[24:25]
	s_add_i32 m0, s48, 0xe000
	s_nop 0
	global_load_lds_dwordx4 v140, s[24:25]
	s_add_i32 s67, s59, s39
	s_mov_b32 m0, s67
	s_waitcnt vmcnt(8)
	s_waitcnt lgkmcnt(0)
	s_barrier
	v_mfma_f32_16x16x32_bf16 v[124:127], v[142:145], v[166:169], v[124:127]
	v_mfma_f32_16x16x32_bf16 v[120:123], v[158:161], v[166:169], v[120:123]
	v_mfma_f32_16x16x32_bf16 v[108:111], v[142:145], v[174:177], v[108:111]
	v_mfma_f32_16x16x32_bf16 v[104:107], v[158:161], v[174:177], v[104:107]
	v_mfma_f32_16x16x32_bf16 v[92:95], v[142:145], v[182:185], v[92:95]
	v_mfma_f32_16x16x32_bf16 v[88:91], v[158:161], v[182:185], v[88:91]
	v_mfma_f32_16x16x32_bf16 v[76:79], v[142:145], v[190:193], v[76:79]
	v_mfma_f32_16x16x32_bf16 v[72:75], v[158:161], v[190:193], v[72:75]
	v_mfma_f32_16x16x32_bf16 v[124:127], v[154:157], v[170:173], v[124:127]
	v_mfma_f32_16x16x32_bf16 v[120:123], v[162:165], v[170:173], v[120:123]
	v_mfma_f32_16x16x32_bf16 v[108:111], v[154:157], v[178:181], v[108:111]
	v_mfma_f32_16x16x32_bf16 v[104:107], v[162:165], v[178:181], v[104:107]
	v_mfma_f32_16x16x32_bf16 v[92:95], v[154:157], v[186:189], v[92:95]
	v_mfma_f32_16x16x32_bf16 v[88:91], v[162:165], v[186:189], v[88:91]
	v_mfma_f32_16x16x32_bf16 v[76:79], v[154:157], v[194:197], v[76:79]
	v_mfma_f32_16x16x32_bf16 v[72:75], v[162:165], v[194:197], v[72:75]
	v_mfma_f32_16x16x32_bf16 v[116:119], v[198:201], v[166:169], v[116:119]
	v_mfma_f32_16x16x32_bf16 v[112:115], v[206:209], v[166:169], v[112:115]
	v_mfma_f32_16x16x32_bf16 v[100:103], v[198:201], v[174:177], v[100:103]
	v_mfma_f32_16x16x32_bf16 v[96:99], v[206:209], v[174:177], v[96:99]
	v_mfma_f32_16x16x32_bf16 v[84:87], v[198:201], v[182:185], v[84:87]
	v_mfma_f32_16x16x32_bf16 v[80:83], v[206:209], v[182:185], v[80:83]
	v_mfma_f32_16x16x32_bf16 v[68:71], v[198:201], v[190:193], v[68:71]
	v_mfma_f32_16x16x32_bf16 v[64:67], v[206:209], v[190:193], v[64:67]
	v_mfma_f32_16x16x32_bf16 v[116:119], v[202:205], v[170:173], v[116:119]
	v_mfma_f32_16x16x32_bf16 v[112:115], v[210:213], v[170:173], v[112:115]
	v_mfma_f32_16x16x32_bf16 v[100:103], v[202:205], v[178:181], v[100:103]
	v_mfma_f32_16x16x32_bf16 v[96:99], v[210:213], v[178:181], v[96:99]
	v_mfma_f32_16x16x32_bf16 v[84:87], v[202:205], v[186:189], v[84:87]
	v_mfma_f32_16x16x32_bf16 v[80:83], v[210:213], v[186:189], v[80:83]
	v_mfma_f32_16x16x32_bf16 v[68:71], v[202:205], v[194:197], v[68:71]
	v_mfma_f32_16x16x32_bf16 v[64:67], v[210:213], v[194:197], v[64:67]
	s_barrier
	global_load_lds_dwordx4 v128, s[26:27]
	s_add_i32 m0, s67, 0x2000
	s_nop 0
	global_load_lds_dwordx4 v132, s[26:27]
	s_mov_b32 m0, s48
	v_lshl_add_u64 v[214:215], s[28:29], 0, v[130:131]
	ds_read_b128 v[166:169], v151 offset:16384
	ds_read_b128 v[170:173], v151 offset:17408
	ds_read_b128 v[174:177], v151 offset:18432
	ds_read_b128 v[178:181], v151 offset:19456
	ds_read_b128 v[182:185], v151 offset:20480
	ds_read_b128 v[186:189], v151 offset:21504
	ds_read_b128 v[190:193], v151 offset:22528
	ds_read_b128 v[194:197], v151 offset:23552
	global_load_lds_dwordx4 v[214:215], off
	v_lshl_add_u64 v[216:217], s[28:29], 0, v[134:135]
	s_mov_b32 m0, s49
	s_nop 0
	global_load_lds_dwordx4 v[216:217], off
	s_add_u32 s68, s26, 0x4000
	s_addc_u32 s69, s27, 0
	s_add_i32 s67, s60, s39
	s_mov_b32 m0, s67
	s_nop 0
	global_load_lds_dwordx4 v128, s[68:69]
	s_add_i32 m0, s67, 0x2000
	s_nop 0
	global_load_lds_dwordx4 v132, s[68:69]
	s_waitcnt vmcnt(8)
	s_waitcnt lgkmcnt(0)
	s_barrier
	v_mfma_f32_16x16x32_bf16 v[60:63], v[142:145], v[166:169], v[60:63]
	v_mfma_f32_16x16x32_bf16 v[56:59], v[158:161], v[166:169], v[56:59]
	v_mfma_f32_16x16x32_bf16 v[44:47], v[142:145], v[174:177], v[44:47]
	v_mfma_f32_16x16x32_bf16 v[40:43], v[158:161], v[174:177], v[40:43]
	v_mfma_f32_16x16x32_bf16 v[28:31], v[142:145], v[182:185], v[28:31]
	v_mfma_f32_16x16x32_bf16 v[24:27], v[158:161], v[182:185], v[24:27]
	v_mfma_f32_16x16x32_bf16 v[12:15], v[142:145], v[190:193], v[12:15]
	v_mfma_f32_16x16x32_bf16 v[8:11], v[158:161], v[190:193], v[8:11]
	v_mfma_f32_16x16x32_bf16 v[60:63], v[154:157], v[170:173], v[60:63]
	v_mfma_f32_16x16x32_bf16 v[56:59], v[162:165], v[170:173], v[56:59]
	v_mfma_f32_16x16x32_bf16 v[44:47], v[154:157], v[178:181], v[44:47]
	v_mfma_f32_16x16x32_bf16 v[40:43], v[162:165], v[178:181], v[40:43]
	v_mfma_f32_16x16x32_bf16 v[28:31], v[154:157], v[186:189], v[28:31]
	v_mfma_f32_16x16x32_bf16 v[24:27], v[162:165], v[186:189], v[24:27]
	v_mfma_f32_16x16x32_bf16 v[12:15], v[154:157], v[194:197], v[12:15]
	v_mfma_f32_16x16x32_bf16 v[8:11], v[162:165], v[194:197], v[8:11]
	v_mfma_f32_16x16x32_bf16 v[52:55], v[198:201], v[166:169], v[52:55]
	v_mfma_f32_16x16x32_bf16 v[48:51], v[206:209], v[166:169], v[48:51]
	v_mfma_f32_16x16x32_bf16 v[36:39], v[198:201], v[174:177], v[36:39]
	v_mfma_f32_16x16x32_bf16 v[32:35], v[206:209], v[174:177], v[32:35]
	v_mfma_f32_16x16x32_bf16 v[20:23], v[198:201], v[182:185], v[20:23]
	v_mfma_f32_16x16x32_bf16 v[16:19], v[206:209], v[182:185], v[16:19]
	v_mfma_f32_16x16x32_bf16 v[4:7], v[198:201], v[190:193], v[4:7]
	v_mfma_f32_16x16x32_bf16 v[0:3], v[206:209], v[190:193], v[0:3]
	v_mfma_f32_16x16x32_bf16 v[52:55], v[202:205], v[170:173], v[52:55]
	v_mfma_f32_16x16x32_bf16 v[48:51], v[210:213], v[170:173], v[48:51]
	v_mfma_f32_16x16x32_bf16 v[36:39], v[202:205], v[178:181], v[36:39]
	v_mfma_f32_16x16x32_bf16 v[32:35], v[210:213], v[178:181], v[32:35]
	v_mfma_f32_16x16x32_bf16 v[20:23], v[202:205], v[186:189], v[20:23]
	v_mfma_f32_16x16x32_bf16 v[16:19], v[210:213], v[186:189], v[16:19]
	v_mfma_f32_16x16x32_bf16 v[4:7], v[202:205], v[194:197], v[4:7]
	v_mfma_f32_16x16x32_bf16 v[0:3], v[210:213], v[194:197], v[0:3]
	s_barrier
; #define PG8_STAGE(bufoff, gbase, voff) do { _Pragma("unroll") for (int _i = 0; _i < 2; ++_i) \
;         __builtin_amdgcn_global_load_lds((const unsigned*)((const char*)(gbase) + (voff)[_i]), (PG8_LAS unsigned*)(lds + (bufoff) + ldsw + _i * 8192), 16, 0, 0); } while (0)
; #define PG8_LDA(dst, b, h) do { _Pragma("unroll") for (int m = 0; m < 4; ++m) _Pragma("unroll") for (int k = 0; k < 2; ++k) dst[m][k] = *(const PG8_LAS bf16x8*)(lds + PG8_SA(b, h) + aoff + m * 2048 + k * 1024); } while (0)
; #define PG8_LDB(dst, b, h) do { _Pragma("unroll") for (int n = 0; n < 2; ++n) _Pragma("unroll") for (int k = 0; k < 2; ++k) dst[n][k] = *(const PG8_LAS bf16x8*)(lds + PG8_SB(b, h) + boff + n * 2048 + k * 1024); } while (0)
; #define PG8_MMA(ai, bj, At, Bt) do { __builtin_amdgcn_s_setprio(1); _Pragma("unroll") for (int m = 0; m < 4; ++m) _Pragma("unroll") for (int n = 0; n < 2; ++n) _Pragma("unroll") for (int k = 0; k < 2; ++k) \
;         acc[ai][bj][m][n] = __builtin_amdgcn_mfma_f32_16x16x32_bf16(Bt[n][k], At[m][k], acc[ai][bj][m][n], 0, 0, 0); __builtin_amdgcn_s_setprio(0); } while (0)
; #define PG8_WAIT_V(n) asm volatile("s_waitcnt vmcnt(" #n ")" ::: "memory")
; #define PG8_WAIT_L(n) asm volatile("s_waitcnt lgkmcnt(" #n ")" ::: "memory")
; #define PG8_BAR __builtin_amdgcn_s_barrier()
; #define PG8_SCHED __builtin_amdgcn_sched_barrier(0)
; template <class Epi, class Sched>
; __device__ __forceinline__ void gemm_phase(PG8_LAS unsigned char* lds, const Gemm g, const Sched& S, const Epi& E) {
;     ...
;             PG8_LDB(B0, 1, 0); PG8_SCHED; PG8_LDA(At, 1, 0); PG8_STAGE(PG8_SA(0, 1), a2 + hstep, voffA);
;             PG8_WAIT_L(8); PG8_BAR; PG8_WAIT_L(0); PG8_MMA(0, 0, At, B0); PG8_BAR; PG8_SCHED;
;             PG8_LDB(B1, 1, 1); PG8_STAGE(PG8_SB(1, 0), b3, voffB);
;             PG8_BAR; PG8_WAIT_L(0); PG8_MMA(0, 1, At, B1); PG8_BAR;
;             PG8_LDA(At, 1, 1); PG8_STAGE(PG8_SA(1, 0), a3, voffA);
;             PG8_BAR; PG8_WAIT_L(0); PG8_MMA(1, 0, At, B0); PG8_BAR; PG8_SCHED;
;             PG8_STAGE(PG8_SB(1, 1), b3 + hstepB, voffB);
;             PG8_WAIT_V(6); PG8_BAR; PG8_MMA(1, 1, At, B1); PG8_BAR;
;         }
	s_add_i32 s67, 0, 0x18000
	v_add_u32_e32 v136, s67, v148
	ds_read_b128 v[142:145], v136
	ds_read_b128 v[154:157], v136 offset:1024
	ds_read_b128 v[158:161], v136 offset:2048
	ds_read_b128 v[162:165], v136 offset:3072
	s_add_u32 s28, s28, 0x80000
	s_addc_u32 s29, s29, 0
	s_mov_b32 m0, s50
	ds_read_b128 v[166:169], v151 offset:32768
	ds_read_b128 v[170:173], v151 offset:33792
	ds_read_b128 v[174:177], v151 offset:34816
	ds_read_b128 v[178:181], v151 offset:35840
	ds_read_b128 v[182:185], v151 offset:36864
	ds_read_b128 v[186:189], v151 offset:37888
	ds_read_b128 v[190:193], v151 offset:38912
	ds_read_b128 v[194:197], v151 offset:39936
	s_add_i32 s68, 0, 0x1c000
	v_add_u32_e32 v136, s68, v148
	ds_read_b128 v[198:201], v136
	ds_read_b128 v[202:205], v136 offset:1024
	ds_read_b128 v[206:209], v136 offset:2048
	ds_read_b128 v[210:213], v136 offset:3072
	global_load_lds_dwordx4 v130, s[28:29]
	s_mov_b32 m0, s51
	s_nop 0
	global_load_lds_dwordx4 v134, s[28:29]
	s_add_u32 s28, s26, 0x8000
	s_addc_u32 s29, s27, 0
	s_add_i32 s67, s67, s39
	s_mov_b32 m0, s67
	s_waitcnt vmcnt(8)
	s_waitcnt lgkmcnt(0)
	s_barrier
	v_mfma_f32_16x16x32_bf16 v[124:127], v[142:145], v[166:169], v[124:127]
	v_mfma_f32_16x16x32_bf16 v[120:123], v[158:161], v[166:169], v[120:123]
	v_mfma_f32_16x16x32_bf16 v[108:111], v[142:145], v[174:177], v[108:111]
	v_mfma_f32_16x16x32_bf16 v[104:107], v[158:161], v[174:177], v[104:107]
	v_mfma_f32_16x16x32_bf16 v[92:95], v[142:145], v[182:185], v[92:95]
	v_mfma_f32_16x16x32_bf16 v[88:91], v[158:161], v[182:185], v[88:91]
	v_mfma_f32_16x16x32_bf16 v[76:79], v[142:145], v[190:193], v[76:79]
	v_mfma_f32_16x16x32_bf16 v[72:75], v[158:161], v[190:193], v[72:75]
	v_mfma_f32_16x16x32_bf16 v[124:127], v[154:157], v[170:173], v[124:127]
	v_mfma_f32_16x16x32_bf16 v[120:123], v[162:165], v[170:173], v[120:123]
	v_mfma_f32_16x16x32_bf16 v[108:111], v[154:157], v[178:181], v[108:111]
	v_mfma_f32_16x16x32_bf16 v[104:107], v[162:165], v[178:181], v[104:107]
	v_mfma_f32_16x16x32_bf16 v[92:95], v[154:157], v[186:189], v[92:95]
	v_mfma_f32_16x16x32_bf16 v[88:91], v[162:165], v[186:189], v[88:91]
	v_mfma_f32_16x16x32_bf16 v[76:79], v[154:157], v[194:197], v[76:79]
	v_mfma_f32_16x16x32_bf16 v[72:75], v[162:165], v[194:197], v[72:75]
	v_mfma_f32_16x16x32_bf16 v[116:119], v[198:201], v[166:169], v[116:119]
	v_mfma_f32_16x16x32_bf16 v[112:115], v[206:209], v[166:169], v[112:115]
	v_mfma_f32_16x16x32_bf16 v[100:103], v[198:201], v[174:177], v[100:103]
	v_mfma_f32_16x16x32_bf16 v[96:99], v[206:209], v[174:177], v[96:99]
	v_mfma_f32_16x16x32_bf16 v[84:87], v[198:201], v[182:185], v[84:87]
	v_mfma_f32_16x16x32_bf16 v[80:83], v[206:209], v[182:185], v[80:83]
	v_mfma_f32_16x16x32_bf16 v[68:71], v[198:201], v[190:193], v[68:71]
	v_mfma_f32_16x16x32_bf16 v[64:67], v[206:209], v[190:193], v[64:67]
	v_mfma_f32_16x16x32_bf16 v[116:119], v[202:205], v[170:173], v[116:119]
	v_mfma_f32_16x16x32_bf16 v[112:115], v[210:213], v[170:173], v[112:115]
	v_mfma_f32_16x16x32_bf16 v[100:103], v[202:205], v[178:181], v[100:103]
	v_mfma_f32_16x16x32_bf16 v[96:99], v[210:213], v[178:181], v[96:99]
	v_mfma_f32_16x16x32_bf16 v[84:87], v[202:205], v[186:189], v[84:87]
	v_mfma_f32_16x16x32_bf16 v[80:83], v[210:213], v[186:189], v[80:83]
	v_mfma_f32_16x16x32_bf16 v[68:71], v[202:205], v[194:197], v[68:71]
	v_mfma_f32_16x16x32_bf16 v[64:67], v[210:213], v[194:197], v[64:67]
	s_barrier
	global_load_lds_dwordx4 v128, s[28:29]
	s_add_i32 m0, s67, 0x2000
	s_nop 0
	global_load_lds_dwordx4 v132, s[28:29]
	s_mov_b32 m0, s55
	v_lshl_add_u64 v[214:215], v[214:215], 0, s[10:11]
	ds_read_b128 v[166:169], v151 offset:49152
	ds_read_b128 v[170:173], v151 offset:50176
	ds_read_b128 v[174:177], v151 offset:51200
	ds_read_b128 v[178:181], v151 offset:52224
	ds_read_b128 v[182:185], v151 offset:53248
	ds_read_b128 v[186:189], v151 offset:54272
	ds_read_b128 v[190:193], v151 offset:55296
	ds_read_b128 v[194:197], v151 offset:56320
	global_load_lds_dwordx4 v[214:215], off
	v_lshl_add_u64 v[214:215], v[216:217], 0, s[10:11]
	s_mov_b32 m0, s56
	s_nop 0
	global_load_lds_dwordx4 v[214:215], off
	s_add_u32 s26, s26, 0xc000
	s_addc_u32 s27, s27, 0
	s_add_i32 s28, s68, s39
	s_mov_b32 m0, s28
	s_nop 0
	global_load_lds_dwordx4 v128, s[26:27]
	s_add_i32 m0, s28, 0x2000
	s_nop 0
	global_load_lds_dwordx4 v132, s[26:27]
	s_add_i32 s66, s66, 2
	s_add_u32 s64, s64, 0x10000
	s_addc_u32 s65, s65, 0
	s_add_u32 s24, s24, 0x100
	s_addc_u32 s25, s25, 0
	s_cmp_gt_u32 s66, 29
	s_waitcnt vmcnt(8)
	s_waitcnt lgkmcnt(0)
	s_barrier
	v_mfma_f32_16x16x32_bf16 v[60:63], v[142:145], v[166:169], v[60:63]
	v_mfma_f32_16x16x32_bf16 v[56:59], v[158:161], v[166:169], v[56:59]
	v_mfma_f32_16x16x32_bf16 v[44:47], v[142:145], v[174:177], v[44:47]
	v_mfma_f32_16x16x32_bf16 v[40:43], v[158:161], v[174:177], v[40:43]
	v_mfma_f32_16x16x32_bf16 v[28:31], v[142:145], v[182:185], v[28:31]
	v_mfma_f32_16x16x32_bf16 v[24:27], v[158:161], v[182:185], v[24:27]
	v_mfma_f32_16x16x32_bf16 v[12:15], v[142:145], v[190:193], v[12:15]
	v_mfma_f32_16x16x32_bf16 v[8:11], v[158:161], v[190:193], v[8:11]
	v_mfma_f32_16x16x32_bf16 v[60:63], v[154:157], v[170:173], v[60:63]
	v_mfma_f32_16x16x32_bf16 v[56:59], v[162:165], v[170:173], v[56:59]
	v_mfma_f32_16x16x32_bf16 v[44:47], v[154:157], v[178:181], v[44:47]
	v_mfma_f32_16x16x32_bf16 v[40:43], v[162:165], v[178:181], v[40:43]
	v_mfma_f32_16x16x32_bf16 v[28:31], v[154:157], v[186:189], v[28:31]
	v_mfma_f32_16x16x32_bf16 v[24:27], v[162:165], v[186:189], v[24:27]
	v_mfma_f32_16x16x32_bf16 v[12:15], v[154:157], v[194:197], v[12:15]
	v_mfma_f32_16x16x32_bf16 v[8:11], v[162:165], v[194:197], v[8:11]
	v_mfma_f32_16x16x32_bf16 v[52:55], v[198:201], v[166:169], v[52:55]
	v_mfma_f32_16x16x32_bf16 v[48:51], v[206:209], v[166:169], v[48:51]
	v_mfma_f32_16x16x32_bf16 v[36:39], v[198:201], v[174:177], v[36:39]
	v_mfma_f32_16x16x32_bf16 v[32:35], v[206:209], v[174:177], v[32:35]
	v_mfma_f32_16x16x32_bf16 v[20:23], v[198:201], v[182:185], v[20:23]
	v_mfma_f32_16x16x32_bf16 v[16:19], v[206:209], v[182:185], v[16:19]
	v_mfma_f32_16x16x32_bf16 v[4:7], v[198:201], v[190:193], v[4:7]
	v_mfma_f32_16x16x32_bf16 v[0:3], v[206:209], v[190:193], v[0:3]
	v_mfma_f32_16x16x32_bf16 v[52:55], v[202:205], v[170:173], v[52:55]
	v_mfma_f32_16x16x32_bf16 v[48:51], v[210:213], v[170:173], v[48:51]
	v_mfma_f32_16x16x32_bf16 v[36:39], v[202:205], v[178:181], v[36:39]
	v_mfma_f32_16x16x32_bf16 v[32:35], v[210:213], v[178:181], v[32:35]
	s_cbranch_scc1 .Lunit_exit_3
	v_mfma_f32_16x16x32_bf16 v[20:23], v[202:205], v[186:189], v[20:23]
	v_mfma_f32_16x16x32_bf16 v[16:19], v[210:213], v[186:189], v[16:19]
	v_mfma_f32_16x16x32_bf16 v[4:7], v[202:205], v[194:197], v[4:7]
	v_mfma_f32_16x16x32_bf16 v[0:3], v[210:213], v[194:197], v[0:3]
	s_barrier
	s_branch .LBB0_397

; #define PG8_STAGE(bufoff, gbase, voff) do { _Pragma("unroll") for (int _i = 0; _i < 2; ++_i) \
;         __builtin_amdgcn_global_load_lds((const unsigned*)((const char*)(gbase) + (voff)[_i]), (PG8_LAS unsigned*)(lds + (bufoff) + ldsw + _i * 8192), 16, 0, 0); } while (0)
; #define PG8_LDA(dst, b, h) do { _Pragma("unroll") for (int m = 0; m < 4; ++m) _Pragma("unroll") for (int k = 0; k < 2; ++k) dst[m][k] = *(const PG8_LAS bf16x8*)(lds + PG8_SA(b, h) + aoff + m * 2048 + k * 1024); } while (0)
; #define PG8_LDB(dst, b, h) do { _Pragma("unroll") for (int n = 0; n < 2; ++n) _Pragma("unroll") for (int k = 0; k < 2; ++k) dst[n][k] = *(const PG8_LAS bf16x8*)(lds + PG8_SB(b, h) + boff + n * 2048 + k * 1024); } while (0)
; #define PG8_MMA(ai, bj, At, Bt) do { __builtin_amdgcn_s_setprio(1); _Pragma("unroll") for (int m = 0; m < 4; ++m) _Pragma("unroll") for (int n = 0; n < 2; ++n) _Pragma("unroll") for (int k = 0; k < 2; ++k) \
;         acc[ai][bj][m][n] = __builtin_amdgcn_mfma_f32_16x16x32_bf16(Bt[n][k], At[m][k], acc[ai][bj][m][n], 0, 0, 0); __builtin_amdgcn_s_setprio(0); } while (0)
; #define PG8_WAIT_L(n) asm volatile("s_waitcnt lgkmcnt(" #n ")" ::: "memory")
; #define PG8_BAR __builtin_amdgcn_s_barrier()
; #define PG8_SCHED __builtin_amdgcn_sched_barrier(0)
; template <class Epi, class Sched>
; __device__ __forceinline__ void gemm_phase(PG8_LAS unsigned char* lds, const Gemm g, const Sched& S, const Epi& E) {
;     ...
;         for (int t = 0; t < nt; t += 2) {
;             const bool last = (t == nt - 2);
;             const char* a1 = cA + (size_t)(t + 1) * kstep;
;             const char* a2 = last ? nA : cA + (size_t)(t + 2) * kstep; const char* b2 = last ? nB : cB + (size_t)(t + 2) * kstepB;
;             const char* a3 = a2 + kstep; const char* b3 = b2 + kstepB;
;             if (last && has_next) S.a_ready(nxt);
;             PG8_LDB(B0, 0, 0); PG8_SCHED; PG8_LDA(At, 0, 0); PG8_STAGE(PG8_SA(1, 1), a1 + hstep, voffA);
;             PG8_WAIT_L(8); PG8_BAR; PG8_WAIT_L(0); PG8_MMA(0, 0, At, B0); PG8_BAR; PG8_SCHED;
;             PG8_LDB(B1, 0, 1); PG8_STAGE(PG8_SB(0, 0), b2, voffB);
;             PG8_BAR; PG8_WAIT_L(0); PG8_MMA(0, 1, At, B1); PG8_BAR;
;             PG8_LDA(At, 0, 1); PG8_STAGE(PG8_SA(0, 0), a2, voffA);
;             PG8_BAR; PG8_WAIT_L(0); PG8_MMA(1, 0, At, B0); PG8_BAR; PG8_SCHED;
;             PG8_STAGE(PG8_SB(0, 1), b2 + hstepB, voffB);
.Lhalf_skip_y_4:
.LBB0_613:
	v_add_u32_e32 v1, s57, v231
	ds_read_b128 v[132:135], v1
	ds_read_b128 v[136:139], v1 offset:1024
	ds_read_b128 v[140:143], v1 offset:2048
	ds_read_b128 v[144:147], v1 offset:3072
	s_add_u32 s26, s24, 0xfffc0080
	s_addc_u32 s27, s25, -1
	s_cmp_eq_u32 s63, 12
	s_cselect_b32 s29, s7, s27
	s_cselect_b32 s28, s15, s26
	s_cselect_b32 s27, s17, s62
	s_cselect_b32 s26, s19, s61
	v_lshl_add_u64 v[2:3], s[24:25], 0, v[204:205]
	s_add_i32 m0, s49, 0xc000
	ds_read_b128 v[148:151], v233
	ds_read_b128 v[152:155], v233 offset:1024
	ds_read_b128 v[156:159], v233 offset:2048
	ds_read_b128 v[160:163], v233 offset:3072
	ds_read_b128 v[164:167], v233 offset:4096
	ds_read_b128 v[168:171], v233 offset:5120
	ds_read_b128 v[172:175], v233 offset:6144
	ds_read_b128 v[176:179], v233 offset:7168
	v_add_u32_e32 v1, s58, v231
	ds_read_b128 v[180:183], v1
	ds_read_b128 v[184:187], v1 offset:1024
	ds_read_b128 v[188:191], v1 offset:2048
	ds_read_b128 v[192:195], v1 offset:3072
	global_load_lds_dwordx4 v[2:3], off
	v_lshl_add_u64 v[2:3], s[24:25], 0, v[206:207]
	s_add_i32 m0, s49, 0xe000
	s_nop 0
	global_load_lds_dwordx4 v[2:3], off
	s_add_i32 s64, s57, s48
	v_lshl_add_u64 v[250:251], s[26:27], 0, v[196:197]
	s_mov_b32 m0, s64
	s_waitcnt vmcnt(8)
	s_waitcnt lgkmcnt(0)
	s_barrier
	v_mfma_f32_16x16x32_bf16 v[2:5], v[132:135], v[148:151], v[4:7]
	v_mfma_f32_16x16x32_bf16 v[6:9], v[140:143], v[148:151], v[8:11]
	v_mfma_f32_16x16x32_bf16 v[32:35], v[132:135], v[156:159], v[32:35]
	v_mfma_f32_16x16x32_bf16 v[28:31], v[140:143], v[156:159], v[28:31]
	v_mfma_f32_16x16x32_bf16 v[24:27], v[132:135], v[164:167], v[24:27]
	v_mfma_f32_16x16x32_bf16 v[20:23], v[140:143], v[164:167], v[20:23]
	v_mfma_f32_16x16x32_bf16 v[16:19], v[132:135], v[172:175], v[16:19]
	v_mfma_f32_16x16x32_bf16 v[12:15], v[140:143], v[172:175], v[12:15]
	v_mfma_f32_16x16x32_bf16 v[2:5], v[136:139], v[152:155], v[2:5]
	v_mfma_f32_16x16x32_bf16 v[8:11], v[144:147], v[152:155], v[6:9]
	v_mfma_f32_16x16x32_bf16 v[32:35], v[136:139], v[160:163], v[32:35]
	v_mfma_f32_16x16x32_bf16 v[28:31], v[144:147], v[160:163], v[28:31]
	v_mfma_f32_16x16x32_bf16 v[24:27], v[136:139], v[168:171], v[24:27]
	v_mfma_f32_16x16x32_bf16 v[20:23], v[144:147], v[168:171], v[20:23]
	v_mfma_f32_16x16x32_bf16 v[16:19], v[136:139], v[176:179], v[16:19]
	v_mfma_f32_16x16x32_bf16 v[12:15], v[144:147], v[176:179], v[12:15]
	v_mfma_f32_16x16x32_bf16 v[128:131], v[180:183], v[148:151], v[128:131]
	v_mfma_f32_16x16x32_bf16 v[124:127], v[188:191], v[148:151], v[124:127]
	v_mfma_f32_16x16x32_bf16 v[120:123], v[180:183], v[156:159], v[120:123]
	v_mfma_f32_16x16x32_bf16 v[116:119], v[188:191], v[156:159], v[116:119]
	v_mfma_f32_16x16x32_bf16 v[112:115], v[180:183], v[164:167], v[112:115]
	v_mfma_f32_16x16x32_bf16 v[108:111], v[188:191], v[164:167], v[108:111]
	v_mfma_f32_16x16x32_bf16 v[104:107], v[180:183], v[172:175], v[104:107]
	v_mfma_f32_16x16x32_bf16 v[100:103], v[188:191], v[172:175], v[100:103]
	v_mfma_f32_16x16x32_bf16 v[128:131], v[184:187], v[152:155], v[128:131]
	v_mfma_f32_16x16x32_bf16 v[124:127], v[192:195], v[152:155], v[124:127]
	v_mfma_f32_16x16x32_bf16 v[120:123], v[184:187], v[160:163], v[120:123]
	v_mfma_f32_16x16x32_bf16 v[116:119], v[192:195], v[160:163], v[116:119]
	v_mfma_f32_16x16x32_bf16 v[112:115], v[184:187], v[168:171], v[112:115]
	v_mfma_f32_16x16x32_bf16 v[108:111], v[192:195], v[168:171], v[108:111]
	v_mfma_f32_16x16x32_bf16 v[104:107], v[184:187], v[176:179], v[104:107]
	v_mfma_f32_16x16x32_bf16 v[100:103], v[192:195], v[176:179], v[100:103]
	s_barrier
	global_load_lds_dwordx4 v[250:251], off
	v_lshl_add_u64 v[250:251], s[26:27], 0, v[200:201]
	s_add_i32 m0, s64, 0x2000
	s_nop 0
	global_load_lds_dwordx4 v[250:251], off
	s_mov_b32 m0, s49
	v_lshl_add_u64 v[212:213], s[28:29], 0, v[198:199]
	ds_read_b128 v[148:151], v233 offset:16384
	ds_read_b128 v[152:155], v233 offset:17408
	ds_read_b128 v[156:159], v233 offset:18432
	ds_read_b128 v[160:163], v233 offset:19456
	ds_read_b128 v[164:167], v233 offset:20480
	ds_read_b128 v[168:171], v233 offset:21504
	ds_read_b128 v[172:175], v233 offset:22528
	ds_read_b128 v[176:179], v233 offset:23552
	global_load_lds_dwordx4 v[212:213], off
	v_lshl_add_u64 v[214:215], s[28:29], 0, v[202:203]
	s_mov_b32 m0, s50
	s_nop 0
	global_load_lds_dwordx4 v[214:215], off
	s_add_u32 s64, s26, 0x4000
	s_addc_u32 s65, s27, 0
	s_add_i32 s66, s58, s48
	v_lshl_add_u64 v[6:7], s[64:65], 0, v[196:197]
	s_mov_b32 m0, s66
	s_nop 0
	global_load_lds_dwordx4 v[6:7], off
	v_lshl_add_u64 v[6:7], s[64:65], 0, v[200:201]
	s_add_i32 m0, s66, 0x2000
	s_nop 0
	global_load_lds_dwordx4 v[6:7], off
	s_waitcnt vmcnt(8)
	s_waitcnt lgkmcnt(0)
	s_barrier
; #define PG8_STAGE(bufoff, gbase, voff) do { _Pragma("unroll") for (int _i = 0; _i < 2; ++_i) \
;         __builtin_amdgcn_global_load_lds((const unsigned*)((const char*)(gbase) + (voff)[_i]), (PG8_LAS unsigned*)(lds + (bufoff) + ldsw + _i * 8192), 16, 0, 0); } while (0)
; #define PG8_LDA(dst, b, h) do { _Pragma("unroll") for (int m = 0; m < 4; ++m) _Pragma("unroll") for (int k = 0; k < 2; ++k) dst[m][k] = *(const PG8_LAS bf16x8*)(lds + PG8_SA(b, h) + aoff + m * 2048 + k * 1024); } while (0)
; #define PG8_LDB(dst, b, h) do { _Pragma("unroll") for (int n = 0; n < 2; ++n) _Pragma("unroll") for (int k = 0; k < 2; ++k) dst[n][k] = *(const PG8_LAS bf16x8*)(lds + PG8_SB(b, h) + boff + n * 2048 + k * 1024); } while (0)
; #define PG8_MMA(ai, bj, At, Bt) do { __builtin_amdgcn_s_setprio(1); _Pragma("unroll") for (int m = 0; m < 4; ++m) _Pragma("unroll") for (int n = 0; n < 2; ++n) _Pragma("unroll") for (int k = 0; k < 2; ++k) \
;         acc[ai][bj][m][n] = __builtin_amdgcn_mfma_f32_16x16x32_bf16(Bt[n][k], At[m][k], acc[ai][bj][m][n], 0, 0, 0); __builtin_amdgcn_s_setprio(0); } while (0)
; #define PG8_WAIT_V(n) asm volatile("s_waitcnt vmcnt(" #n ")" ::: "memory")
; #define PG8_WAIT_L(n) asm volatile("s_waitcnt lgkmcnt(" #n ")" ::: "memory")
; #define PG8_BAR __builtin_amdgcn_s_barrier()
; #define PG8_SCHED __builtin_amdgcn_sched_barrier(0)
; template <class Epi, class Sched>
; __device__ __forceinline__ void gemm_phase(PG8_LAS unsigned char* lds, const Gemm g, const Sched& S, const Epi& E) {
;     ...
;             PG8_WAIT_V(6); PG8_BAR; PG8_MMA(1, 1, At, B1); PG8_BAR;
;             PG8_LDB(B0, 1, 0); PG8_SCHED; PG8_LDA(At, 1, 0); PG8_STAGE(PG8_SA(0, 1), a2 + hstep, voffA);
;             PG8_WAIT_L(8); PG8_BAR; PG8_WAIT_L(0); PG8_MMA(0, 0, At, B0); PG8_BAR; PG8_SCHED;
;             PG8_LDB(B1, 1, 1); PG8_STAGE(PG8_SB(1, 0), b3, voffB);
;             PG8_BAR; PG8_WAIT_L(0); PG8_MMA(0, 1, At, B1); PG8_BAR;
;             PG8_LDA(At, 1, 1); PG8_STAGE(PG8_SA(1, 0), a3, voffA);
	v_mfma_f32_16x16x32_bf16 v[96:99], v[132:135], v[148:151], v[96:99]
	v_mfma_f32_16x16x32_bf16 v[92:95], v[140:143], v[148:151], v[92:95]
	v_mfma_f32_16x16x32_bf16 v[88:91], v[132:135], v[156:159], v[88:91]
	v_mfma_f32_16x16x32_bf16 v[84:87], v[140:143], v[156:159], v[84:87]
	v_mfma_f32_16x16x32_bf16 v[80:83], v[132:135], v[164:167], v[80:83]
	v_mfma_f32_16x16x32_bf16 v[76:79], v[140:143], v[164:167], v[76:79]
	v_mfma_f32_16x16x32_bf16 v[72:75], v[132:135], v[172:175], v[72:75]
	v_mfma_f32_16x16x32_bf16 v[68:71], v[140:143], v[172:175], v[68:71]
	v_mfma_f32_16x16x32_bf16 v[96:99], v[136:139], v[152:155], v[96:99]
	v_mfma_f32_16x16x32_bf16 v[92:95], v[144:147], v[152:155], v[92:95]
	v_mfma_f32_16x16x32_bf16 v[88:91], v[136:139], v[160:163], v[88:91]
	v_mfma_f32_16x16x32_bf16 v[84:87], v[144:147], v[160:163], v[84:87]
	v_mfma_f32_16x16x32_bf16 v[80:83], v[136:139], v[168:171], v[80:83]
	v_mfma_f32_16x16x32_bf16 v[76:79], v[144:147], v[168:171], v[76:79]
	v_mfma_f32_16x16x32_bf16 v[72:75], v[136:139], v[176:179], v[72:75]
	v_mfma_f32_16x16x32_bf16 v[68:71], v[144:147], v[176:179], v[68:71]
	v_mfma_f32_16x16x32_bf16 v[64:67], v[180:183], v[148:151], v[64:67]
	v_mfma_f32_16x16x32_bf16 v[60:63], v[188:191], v[148:151], v[60:63]
	v_mfma_f32_16x16x32_bf16 v[56:59], v[180:183], v[156:159], v[56:59]
	v_mfma_f32_16x16x32_bf16 v[52:55], v[188:191], v[156:159], v[52:55]
	v_mfma_f32_16x16x32_bf16 v[48:51], v[180:183], v[164:167], v[48:51]
	v_mfma_f32_16x16x32_bf16 v[44:47], v[188:191], v[164:167], v[44:47]
	v_mfma_f32_16x16x32_bf16 v[40:43], v[180:183], v[172:175], v[40:43]
	v_mfma_f32_16x16x32_bf16 v[36:39], v[188:191], v[172:175], v[36:39]
	v_mfma_f32_16x16x32_bf16 v[64:67], v[184:187], v[152:155], v[64:67]
	v_mfma_f32_16x16x32_bf16 v[60:63], v[192:195], v[152:155], v[60:63]
	v_mfma_f32_16x16x32_bf16 v[56:59], v[184:187], v[160:163], v[56:59]
	v_mfma_f32_16x16x32_bf16 v[52:55], v[192:195], v[160:163], v[52:55]
	v_mfma_f32_16x16x32_bf16 v[48:51], v[184:187], v[168:171], v[48:51]
	v_mfma_f32_16x16x32_bf16 v[44:47], v[192:195], v[168:171], v[44:47]
	v_mfma_f32_16x16x32_bf16 v[40:43], v[184:187], v[176:179], v[40:43]
	v_mfma_f32_16x16x32_bf16 v[36:39], v[192:195], v[176:179], v[36:39]
	s_barrier
	s_add_i32 s64, 0, 0x18000
	v_add_u32_e32 v1, s64, v231
	ds_read_b128 v[132:135], v1
	ds_read_b128 v[136:139], v1 offset:1024
	ds_read_b128 v[140:143], v1 offset:2048
	ds_read_b128 v[144:147], v1 offset:3072
	s_add_u32 s28, s28, 0x40000
	s_addc_u32 s29, s29, 0
	s_mov_b32 m0, s51
	v_lshl_add_u64 v[6:7], s[28:29], 0, v[198:199]
	ds_read_b128 v[148:151], v233 offset:32768
	ds_read_b128 v[152:155], v233 offset:33792
	ds_read_b128 v[156:159], v233 offset:34816
	ds_read_b128 v[160:163], v233 offset:35840
	ds_read_b128 v[164:167], v233 offset:36864
	ds_read_b128 v[168:171], v233 offset:37888
	ds_read_b128 v[172:175], v233 offset:38912
	ds_read_b128 v[176:179], v233 offset:39936
	s_add_i32 s65, 0, 0x1c000
	v_add_u32_e32 v1, s65, v231
	ds_read_b128 v[180:183], v1
	ds_read_b128 v[184:187], v1 offset:1024
	ds_read_b128 v[188:191], v1 offset:2048
	ds_read_b128 v[192:195], v1 offset:3072
	global_load_lds_dwordx4 v[6:7], off
	v_lshl_add_u64 v[6:7], s[28:29], 0, v[202:203]
	s_mov_b32 m0, s52
	s_nop 0
	global_load_lds_dwordx4 v[6:7], off
	s_add_u32 s28, s26, 0x8000
	s_addc_u32 s29, s27, 0
	s_add_i32 s64, s64, s48
	v_lshl_add_u64 v[252:253], s[28:29], 0, v[196:197]
	s_mov_b32 m0, s64
	s_waitcnt vmcnt(8)
	s_waitcnt lgkmcnt(0)
	s_barrier
	v_mfma_f32_16x16x32_bf16 v[2:5], v[132:135], v[148:151], v[2:5]
	v_mfma_f32_16x16x32_bf16 v[8:11], v[140:143], v[148:151], v[8:11]
	v_mfma_f32_16x16x32_bf16 v[32:35], v[132:135], v[156:159], v[32:35]
	v_mfma_f32_16x16x32_bf16 v[28:31], v[140:143], v[156:159], v[28:31]
	v_mfma_f32_16x16x32_bf16 v[24:27], v[132:135], v[164:167], v[24:27]
	v_mfma_f32_16x16x32_bf16 v[20:23], v[140:143], v[164:167], v[20:23]
	v_mfma_f32_16x16x32_bf16 v[16:19], v[132:135], v[172:175], v[16:19]
	v_mfma_f32_16x16x32_bf16 v[12:15], v[140:143], v[172:175], v[12:15]
	v_mfma_f32_16x16x32_bf16 v[4:7], v[136:139], v[152:155], v[2:5]
	v_mfma_f32_16x16x32_bf16 v[8:11], v[144:147], v[152:155], v[8:11]
	v_mfma_f32_16x16x32_bf16 v[32:35], v[136:139], v[160:163], v[32:35]
	v_mfma_f32_16x16x32_bf16 v[28:31], v[144:147], v[160:163], v[28:31]
	v_mfma_f32_16x16x32_bf16 v[24:27], v[136:139], v[168:171], v[24:27]
	v_mfma_f32_16x16x32_bf16 v[20:23], v[144:147], v[168:171], v[20:23]
	v_mfma_f32_16x16x32_bf16 v[16:19], v[136:139], v[176:179], v[16:19]
	v_mfma_f32_16x16x32_bf16 v[12:15], v[144:147], v[176:179], v[12:15]
	v_mfma_f32_16x16x32_bf16 v[128:131], v[180:183], v[148:151], v[128:131]
	v_mfma_f32_16x16x32_bf16 v[124:127], v[188:191], v[148:151], v[124:127]
	v_mfma_f32_16x16x32_bf16 v[120:123], v[180:183], v[156:159], v[120:123]
	v_mfma_f32_16x16x32_bf16 v[116:119], v[188:191], v[156:159], v[116:119]
	v_mfma_f32_16x16x32_bf16 v[112:115], v[180:183], v[164:167], v[112:115]
	v_mfma_f32_16x16x32_bf16 v[108:111], v[188:191], v[164:167], v[108:111]
	v_mfma_f32_16x16x32_bf16 v[104:107], v[180:183], v[172:175], v[104:107]
	v_mfma_f32_16x16x32_bf16 v[100:103], v[188:191], v[172:175], v[100:103]
	v_mfma_f32_16x16x32_bf16 v[128:131], v[184:187], v[152:155], v[128:131]
	v_mfma_f32_16x16x32_bf16 v[124:127], v[192:195], v[152:155], v[124:127]
	v_mfma_f32_16x16x32_bf16 v[120:123], v[184:187], v[160:163], v[120:123]
	v_mfma_f32_16x16x32_bf16 v[116:119], v[192:195], v[160:163], v[116:119]
	v_mfma_f32_16x16x32_bf16 v[112:115], v[184:187], v[168:171], v[112:115]
	v_mfma_f32_16x16x32_bf16 v[108:111], v[192:195], v[168:171], v[108:111]
	v_mfma_f32_16x16x32_bf16 v[104:107], v[184:187], v[176:179], v[104:107]
	v_mfma_f32_16x16x32_bf16 v[100:103], v[192:195], v[176:179], v[100:103]
	s_barrier
; #define PG8_STAGE(bufoff, gbase, voff) do { _Pragma("unroll") for (int _i = 0; _i < 2; ++_i) \
;         __builtin_amdgcn_global_load_lds((const unsigned*)((const char*)(gbase) + (voff)[_i]), (PG8_LAS unsigned*)(lds + (bufoff) + ldsw + _i * 8192), 16, 0, 0); } while (0)
; #define PG8_LDA(dst, b, h) do { _Pragma("unroll") for (int m = 0; m < 4; ++m) _Pragma("unroll") for (int k = 0; k < 2; ++k) dst[m][k] = *(const PG8_LAS bf16x8*)(lds + PG8_SA(b, h) + aoff + m * 2048 + k * 1024); } while (0)
; #define PG8_MMA(ai, bj, At, Bt) do { __builtin_amdgcn_s_setprio(1); _Pragma("unroll") for (int m = 0; m < 4; ++m) _Pragma("unroll") for (int n = 0; n < 2; ++n) _Pragma("unroll") for (int k = 0; k < 2; ++k) \
;         acc[ai][bj][m][n] = __builtin_amdgcn_mfma_f32_16x16x32_bf16(Bt[n][k], At[m][k], acc[ai][bj][m][n], 0, 0, 0); __builtin_amdgcn_s_setprio(0); } while (0)
; #define PG8_WAIT_V(n) asm volatile("s_waitcnt vmcnt(" #n ")" ::: "memory")
; #define PG8_WAIT_L(n) asm volatile("s_waitcnt lgkmcnt(" #n ")" ::: "memory")
; #define PG8_BAR __builtin_amdgcn_s_barrier()
; #define PG8_SCHED __builtin_amdgcn_sched_barrier(0)
; template <class Epi, class Sched>
; __device__ __forceinline__ void gemm_phase(PG8_LAS unsigned char* lds, const Gemm g, const Sched& S, const Epi& E) {
;     ...
;             PG8_LDA(At, 1, 1); PG8_STAGE(PG8_SA(1, 0), a3, voffA);
;             PG8_BAR; PG8_WAIT_L(0); PG8_MMA(1, 0, At, B0); PG8_BAR; PG8_SCHED;
;             PG8_STAGE(PG8_SB(1, 1), b3 + hstepB, voffB);
;             PG8_WAIT_V(6); PG8_BAR; PG8_MMA(1, 1, At, B1); PG8_BAR;
;         }
	global_load_lds_dwordx4 v[252:253], off
	v_lshl_add_u64 v[252:253], s[28:29], 0, v[200:201]
	s_add_i32 m0, s64, 0x2000
	s_nop 0
	global_load_lds_dwordx4 v[252:253], off
	s_mov_b32 m0, s55
	v_lshl_add_u64 v[2:3], v[212:213], 0, s[12:13]
	ds_read_b128 v[148:151], v233 offset:49152
	ds_read_b128 v[152:155], v233 offset:50176
	ds_read_b128 v[156:159], v233 offset:51200
	ds_read_b128 v[160:163], v233 offset:52224
	ds_read_b128 v[164:167], v233 offset:53248
	ds_read_b128 v[168:171], v233 offset:54272
	ds_read_b128 v[172:175], v233 offset:55296
	ds_read_b128 v[176:179], v233 offset:56320
	global_load_lds_dwordx4 v[2:3], off
	v_lshl_add_u64 v[2:3], v[214:215], 0, s[12:13]
	s_mov_b32 m0, s56
	s_nop 0
	global_load_lds_dwordx4 v[2:3], off
	s_add_u32 s26, s26, 0xc000
	s_addc_u32 s27, s27, 0
	s_add_i32 s28, s65, s48
	v_lshl_add_u64 v[2:3], s[26:27], 0, v[196:197]
	s_mov_b32 m0, s28
	s_nop 0
	global_load_lds_dwordx4 v[2:3], off
	v_lshl_add_u64 v[2:3], s[26:27], 0, v[200:201]
	s_add_i32 m0, s28, 0x2000
	s_nop 0
	global_load_lds_dwordx4 v[2:3], off
	s_add_i32 s63, s63, 2
	s_add_u32 s61, s61, 0x10000
	s_addc_u32 s62, s62, 0
	s_add_u32 s24, s24, 0x100
	s_addc_u32 s25, s25, 0
	s_cmp_gt_u32 s63, 13
	s_waitcnt vmcnt(8)
	s_waitcnt lgkmcnt(0)
	s_barrier
	v_mfma_f32_16x16x32_bf16 v[96:99], v[132:135], v[148:151], v[96:99]
	v_mfma_f32_16x16x32_bf16 v[92:95], v[140:143], v[148:151], v[92:95]
	v_mfma_f32_16x16x32_bf16 v[88:91], v[132:135], v[156:159], v[88:91]
	v_mfma_f32_16x16x32_bf16 v[84:87], v[140:143], v[156:159], v[84:87]
	v_mfma_f32_16x16x32_bf16 v[80:83], v[132:135], v[164:167], v[80:83]
	v_mfma_f32_16x16x32_bf16 v[76:79], v[140:143], v[164:167], v[76:79]
	v_mfma_f32_16x16x32_bf16 v[72:75], v[132:135], v[172:175], v[72:75]
	v_mfma_f32_16x16x32_bf16 v[68:71], v[140:143], v[172:175], v[68:71]
	v_mfma_f32_16x16x32_bf16 v[96:99], v[136:139], v[152:155], v[96:99]
	v_mfma_f32_16x16x32_bf16 v[92:95], v[144:147], v[152:155], v[92:95]
	v_mfma_f32_16x16x32_bf16 v[88:91], v[136:139], v[160:163], v[88:91]
	v_mfma_f32_16x16x32_bf16 v[84:87], v[144:147], v[160:163], v[84:87]
	v_mfma_f32_16x16x32_bf16 v[80:83], v[136:139], v[168:171], v[80:83]
	v_mfma_f32_16x16x32_bf16 v[76:79], v[144:147], v[168:171], v[76:79]
	v_mfma_f32_16x16x32_bf16 v[72:75], v[136:139], v[176:179], v[72:75]
	v_mfma_f32_16x16x32_bf16 v[68:71], v[144:147], v[176:179], v[68:71]
	v_mfma_f32_16x16x32_bf16 v[64:67], v[180:183], v[148:151], v[64:67]
	v_mfma_f32_16x16x32_bf16 v[60:63], v[188:191], v[148:151], v[60:63]
	v_mfma_f32_16x16x32_bf16 v[56:59], v[180:183], v[156:159], v[56:59]
	v_mfma_f32_16x16x32_bf16 v[52:55], v[188:191], v[156:159], v[52:55]
	v_mfma_f32_16x16x32_bf16 v[48:51], v[180:183], v[164:167], v[48:51]
	v_mfma_f32_16x16x32_bf16 v[44:47], v[188:191], v[164:167], v[44:47]
	v_mfma_f32_16x16x32_bf16 v[40:43], v[180:183], v[172:175], v[40:43]
	v_mfma_f32_16x16x32_bf16 v[36:39], v[188:191], v[172:175], v[36:39]
	v_mfma_f32_16x16x32_bf16 v[64:67], v[184:187], v[152:155], v[64:67]
	v_mfma_f32_16x16x32_bf16 v[60:63], v[192:195], v[152:155], v[60:63]
	v_mfma_f32_16x16x32_bf16 v[56:59], v[184:187], v[160:163], v[56:59]
	v_mfma_f32_16x16x32_bf16 v[52:55], v[192:195], v[160:163], v[52:55]
	s_cbranch_scc1 .Lunit_exit_4
	v_mfma_f32_16x16x32_bf16 v[48:51], v[184:187], v[168:171], v[48:51]
	v_mfma_f32_16x16x32_bf16 v[44:47], v[192:195], v[168:171], v[44:47]
	v_mfma_f32_16x16x32_bf16 v[40:43], v[184:187], v[176:179], v[40:43]
	v_mfma_f32_16x16x32_bf16 v[36:39], v[192:195], v[176:179], v[36:39]
	s_barrier
	s_branch .LBB0_613

; #define PG8_STAGE(bufoff, gbase, voff) do { _Pragma("unroll") for (int _i = 0; _i < 2; ++_i) \
;         __builtin_amdgcn_global_load_lds((const unsigned*)((const char*)(gbase) + (voff)[_i]), (PG8_LAS unsigned*)(lds + (bufoff) + ldsw + _i * 8192), 16, 0, 0); } while (0)
; #define PG8_LDA(dst, b, h) do { _Pragma("unroll") for (int m = 0; m < 4; ++m) _Pragma("unroll") for (int k = 0; k < 2; ++k) dst[m][k] = *(const PG8_LAS bf16x8*)(lds + PG8_SA(b, h) + aoff + m * 2048 + k * 1024); } while (0)
; #define PG8_LDB(dst, b, h) do { _Pragma("unroll") for (int n = 0; n < 2; ++n) _Pragma("unroll") for (int k = 0; k < 2; ++k) dst[n][k] = *(const PG8_LAS bf16x8*)(lds + PG8_SB(b, h) + boff + n * 2048 + k * 1024); } while (0)
; #define PG8_MMA(ai, bj, At, Bt) do { __builtin_amdgcn_s_setprio(1); _Pragma("unroll") for (int m = 0; m < 4; ++m) _Pragma("unroll") for (int n = 0; n < 2; ++n) _Pragma("unroll") for (int k = 0; k < 2; ++k) \
;         acc[ai][bj][m][n] = __builtin_amdgcn_mfma_f32_16x16x32_bf16(Bt[n][k], At[m][k], acc[ai][bj][m][n], 0, 0, 0); __builtin_amdgcn_s_setprio(0); } while (0)
; #define PG8_WAIT_V(n) asm volatile("s_waitcnt vmcnt(" #n ")" ::: "memory")
; template <class Epi, class Sched>
; __device__ __forceinline__ void gemm_phase(PG8_LAS unsigned char* lds, const Gemm g, const Sched& S, const Epi& E) {
;     ...
;         for (int t = 0; t < nt; t += 2) {
;             const bool last = (t == nt - 2);
;             const char* a1 = cA + (size_t)(t + 1) * kstep;
;             const char* a2 = last ? nA : cA + (size_t)(t + 2) * kstep; const char* b2 = last ? nB : cB + (size_t)(t + 2) * kstepB;
;             const char* a3 = a2 + kstep; const char* b3 = b2 + kstepB;
;             if (last && has_next) S.a_ready(nxt);
;             PG8_LDB(B0, 0, 0); PG8_SCHED; PG8_LDA(At, 0, 0); PG8_STAGE(PG8_SA(1, 1), a1 + hstep, voffA);
;             PG8_WAIT_L(8); PG8_BAR; PG8_WAIT_L(0); PG8_MMA(0, 0, At, B0); PG8_BAR; PG8_SCHED;
;             PG8_LDB(B1, 0, 1); PG8_STAGE(PG8_SB(0, 0), b2, voffB);
;             PG8_BAR; PG8_WAIT_L(0); PG8_MMA(0, 1, At, B1); PG8_BAR;
;             PG8_LDA(At, 0, 1); PG8_STAGE(PG8_SA(0, 0), a2, voffA);
;             PG8_BAR; PG8_WAIT_L(0); PG8_MMA(1, 0, At, B0); PG8_BAR; PG8_SCHED;
;             PG8_STAGE(PG8_SB(0, 1), b2 + hstepB, voffB);
;             PG8_WAIT_V(6); PG8_BAR; PG8_MMA(1, 1, At, B1); PG8_BAR;
.Lhalf_skip_y_5:
.LBB0_783:
	ds_read_b128 v[128:131], v197
	ds_read_b128 v[132:135], v197 offset:1024
	ds_read_b128 v[136:139], v197 offset:2048
	ds_read_b128 v[140:143], v197 offset:3072
	s_add_u32 s30, s28, 0x100
	s_addc_u32 s31, s29, 0
	s_cmp_eq_u32 s69, 28
	s_cselect_b32 s39, s19, s31
	s_cselect_b32 s38, s65, s30
	s_cselect_b32 s37, s21, s68
	s_cselect_b32 s36, s66, s67
	v_lshl_add_u64 v[192:193], s[28:29], 0, v[172:173]
	s_add_i32 m0, s27, 0xc000
	ds_read_b128 v[144:147], v198
	ds_read_b128 v[148:151], v198 offset:1024
	ds_read_b128 v[152:155], v198 offset:2048
	ds_read_b128 v[156:159], v198 offset:3072
	ds_read_b128 v[160:163], v198 offset:4096
	ds_read_b128 v[180:183], v198 offset:5120
	ds_read_b128 v[184:187], v198 offset:6144
	ds_read_b128 v[188:191], v198 offset:7168
	ds_read_b128 v[200:203], v199
	ds_read_b128 v[204:207], v199 offset:1024
	ds_read_b128 v[208:211], v199 offset:2048
	ds_read_b128 v[212:215], v199 offset:3072
	global_load_lds_dwordx4 v[192:193], off
	v_lshl_add_u64 v[192:193], s[28:29], 0, v[174:175]
	s_add_i32 m0, s27, 0xe000
	s_nop 0
	global_load_lds_dwordx4 v[192:193], off
	s_add_i32 s28, s62, s54
	s_mov_b32 m0, s28
	s_waitcnt vmcnt(8)
	s_waitcnt lgkmcnt(0)
	s_barrier
	v_mfma_f32_16x16x32_bf16 v[124:127], v[128:131], v[144:147], v[124:127]
	v_mfma_f32_16x16x32_bf16 v[120:123], v[136:139], v[144:147], v[120:123]
	v_mfma_f32_16x16x32_bf16 v[116:119], v[128:131], v[152:155], v[116:119]
	v_mfma_f32_16x16x32_bf16 v[104:107], v[136:139], v[152:155], v[104:107]
	v_mfma_f32_16x16x32_bf16 v[92:95], v[128:131], v[160:163], v[92:95]
	v_mfma_f32_16x16x32_bf16 v[88:91], v[136:139], v[160:163], v[88:91]
	v_mfma_f32_16x16x32_bf16 v[76:79], v[128:131], v[184:187], v[76:79]
	v_mfma_f32_16x16x32_bf16 v[72:75], v[136:139], v[184:187], v[72:75]
	v_mfma_f32_16x16x32_bf16 v[124:127], v[132:135], v[148:151], v[124:127]
	v_mfma_f32_16x16x32_bf16 v[120:123], v[140:143], v[148:151], v[120:123]
	v_mfma_f32_16x16x32_bf16 v[116:119], v[132:135], v[156:159], v[116:119]
	v_mfma_f32_16x16x32_bf16 v[104:107], v[140:143], v[156:159], v[104:107]
	v_mfma_f32_16x16x32_bf16 v[92:95], v[132:135], v[180:183], v[92:95]
	v_mfma_f32_16x16x32_bf16 v[88:91], v[140:143], v[180:183], v[88:91]
	v_mfma_f32_16x16x32_bf16 v[76:79], v[132:135], v[188:191], v[76:79]
	v_mfma_f32_16x16x32_bf16 v[72:75], v[140:143], v[188:191], v[72:75]
	v_mfma_f32_16x16x32_bf16 v[112:115], v[200:203], v[144:147], v[112:115]
	v_mfma_f32_16x16x32_bf16 v[108:111], v[208:211], v[144:147], v[108:111]
	v_mfma_f32_16x16x32_bf16 v[100:103], v[200:203], v[152:155], v[100:103]
	v_mfma_f32_16x16x32_bf16 v[96:99], v[208:211], v[152:155], v[96:99]
	v_mfma_f32_16x16x32_bf16 v[84:87], v[200:203], v[160:163], v[84:87]
	v_mfma_f32_16x16x32_bf16 v[80:83], v[208:211], v[160:163], v[80:83]
	v_mfma_f32_16x16x32_bf16 v[68:71], v[200:203], v[184:187], v[68:71]
	v_mfma_f32_16x16x32_bf16 v[64:67], v[208:211], v[184:187], v[64:67]
	v_mfma_f32_16x16x32_bf16 v[112:115], v[204:207], v[148:151], v[112:115]
	v_mfma_f32_16x16x32_bf16 v[108:111], v[212:215], v[148:151], v[108:111]
	v_mfma_f32_16x16x32_bf16 v[100:103], v[204:207], v[156:159], v[100:103]
	v_mfma_f32_16x16x32_bf16 v[96:99], v[212:215], v[156:159], v[96:99]
	v_mfma_f32_16x16x32_bf16 v[84:87], v[204:207], v[180:183], v[84:87]
	v_mfma_f32_16x16x32_bf16 v[80:83], v[212:215], v[180:183], v[80:83]
	v_mfma_f32_16x16x32_bf16 v[68:71], v[204:207], v[188:191], v[68:71]
	v_mfma_f32_16x16x32_bf16 v[64:67], v[212:215], v[188:191], v[64:67]
	s_barrier
	global_load_lds_dwordx4 v164, s[36:37]
	s_add_i32 m0, s28, 0x2000
	s_nop 0
	global_load_lds_dwordx4 v168, s[36:37]
	s_mov_b32 m0, s27
	v_lshl_add_u64 v[192:193], s[38:39], 0, v[166:167]
	ds_read_b128 v[144:147], v198 offset:16384
	ds_read_b128 v[148:151], v198 offset:17408
	ds_read_b128 v[152:155], v198 offset:18432
	ds_read_b128 v[156:159], v198 offset:19456
	ds_read_b128 v[160:163], v198 offset:20480
	ds_read_b128 v[180:183], v198 offset:21504
	ds_read_b128 v[184:187], v198 offset:22528
	ds_read_b128 v[188:191], v198 offset:23552
	global_load_lds_dwordx4 v[192:193], off
	v_lshl_add_u64 v[216:217], s[38:39], 0, v[170:171]
	s_mov_b32 m0, s55
	s_nop 0
	global_load_lds_dwordx4 v[216:217], off
	s_add_u32 s28, s36, 0x4000
	s_addc_u32 s29, s37, 0
	s_add_i32 s70, s63, s54
	s_mov_b32 m0, s70
	s_nop 0
	global_load_lds_dwordx4 v164, s[28:29]
	s_add_i32 m0, s70, 0x2000
	s_nop 0
	global_load_lds_dwordx4 v168, s[28:29]
	s_waitcnt vmcnt(8)
	s_waitcnt lgkmcnt(0)
	s_barrier
	v_mfma_f32_16x16x32_bf16 v[60:63], v[128:131], v[144:147], v[60:63]
	v_mfma_f32_16x16x32_bf16 v[56:59], v[136:139], v[144:147], v[56:59]
	v_mfma_f32_16x16x32_bf16 v[44:47], v[128:131], v[152:155], v[44:47]
	v_mfma_f32_16x16x32_bf16 v[40:43], v[136:139], v[152:155], v[40:43]
	v_mfma_f32_16x16x32_bf16 v[28:31], v[128:131], v[160:163], v[28:31]
	v_mfma_f32_16x16x32_bf16 v[24:27], v[136:139], v[160:163], v[24:27]
	v_mfma_f32_16x16x32_bf16 v[12:15], v[128:131], v[184:187], v[12:15]
	v_mfma_f32_16x16x32_bf16 v[8:11], v[136:139], v[184:187], v[8:11]
	v_mfma_f32_16x16x32_bf16 v[60:63], v[132:135], v[148:151], v[60:63]
	v_mfma_f32_16x16x32_bf16 v[56:59], v[140:143], v[148:151], v[56:59]
	v_mfma_f32_16x16x32_bf16 v[44:47], v[132:135], v[156:159], v[44:47]
	v_mfma_f32_16x16x32_bf16 v[40:43], v[140:143], v[156:159], v[40:43]
	v_mfma_f32_16x16x32_bf16 v[28:31], v[132:135], v[180:183], v[28:31]
	v_mfma_f32_16x16x32_bf16 v[24:27], v[140:143], v[180:183], v[24:27]
	v_mfma_f32_16x16x32_bf16 v[12:15], v[132:135], v[188:191], v[12:15]
	v_mfma_f32_16x16x32_bf16 v[8:11], v[140:143], v[188:191], v[8:11]
	v_mfma_f32_16x16x32_bf16 v[52:55], v[200:203], v[144:147], v[52:55]
	v_mfma_f32_16x16x32_bf16 v[48:51], v[208:211], v[144:147], v[48:51]
	v_mfma_f32_16x16x32_bf16 v[36:39], v[200:203], v[152:155], v[36:39]
	v_mfma_f32_16x16x32_bf16 v[32:35], v[208:211], v[152:155], v[32:35]
	v_mfma_f32_16x16x32_bf16 v[20:23], v[200:203], v[160:163], v[20:23]
	v_mfma_f32_16x16x32_bf16 v[16:19], v[208:211], v[160:163], v[16:19]
	v_mfma_f32_16x16x32_bf16 v[4:7], v[200:203], v[184:187], v[4:7]
	v_mfma_f32_16x16x32_bf16 v[0:3], v[208:211], v[184:187], v[0:3]
	v_mfma_f32_16x16x32_bf16 v[52:55], v[204:207], v[148:151], v[52:55]
	v_mfma_f32_16x16x32_bf16 v[48:51], v[212:215], v[148:151], v[48:51]
	v_mfma_f32_16x16x32_bf16 v[36:39], v[204:207], v[156:159], v[36:39]
	v_mfma_f32_16x16x32_bf16 v[32:35], v[212:215], v[156:159], v[32:35]
	v_mfma_f32_16x16x32_bf16 v[20:23], v[204:207], v[180:183], v[20:23]
	v_mfma_f32_16x16x32_bf16 v[16:19], v[212:215], v[180:183], v[16:19]
	v_mfma_f32_16x16x32_bf16 v[4:7], v[204:207], v[188:191], v[4:7]
	v_mfma_f32_16x16x32_bf16 v[0:3], v[212:215], v[188:191], v[0:3]
	s_barrier
; #define PG8_STAGE(bufoff, gbase, voff) do { _Pragma("unroll") for (int _i = 0; _i < 2; ++_i) \
;         __builtin_amdgcn_global_load_lds((const unsigned*)((const char*)(gbase) + (voff)[_i]), (PG8_LAS unsigned*)(lds + (bufoff) + ldsw + _i * 8192), 16, 0, 0); } while (0)
; #define PG8_LDA(dst, b, h) do { _Pragma("unroll") for (int m = 0; m < 4; ++m) _Pragma("unroll") for (int k = 0; k < 2; ++k) dst[m][k] = *(const PG8_LAS bf16x8*)(lds + PG8_SA(b, h) + aoff + m * 2048 + k * 1024); } while (0)
; #define PG8_LDB(dst, b, h) do { _Pragma("unroll") for (int n = 0; n < 2; ++n) _Pragma("unroll") for (int k = 0; k < 2; ++k) dst[n][k] = *(const PG8_LAS bf16x8*)(lds + PG8_SB(b, h) + boff + n * 2048 + k * 1024); } while (0)
; #define PG8_MMA(ai, bj, At, Bt) do { __builtin_amdgcn_s_setprio(1); _Pragma("unroll") for (int m = 0; m < 4; ++m) _Pragma("unroll") for (int n = 0; n < 2; ++n) _Pragma("unroll") for (int k = 0; k < 2; ++k) \
;         acc[ai][bj][m][n] = __builtin_amdgcn_mfma_f32_16x16x32_bf16(Bt[n][k], At[m][k], acc[ai][bj][m][n], 0, 0, 0); __builtin_amdgcn_s_setprio(0); } while (0)
; #define PG8_WAIT_V(n) asm volatile("s_waitcnt vmcnt(" #n ")" ::: "memory")
; #define PG8_WAIT_L(n) asm volatile("s_waitcnt lgkmcnt(" #n ")" ::: "memory")
; #define PG8_BAR __builtin_amdgcn_s_barrier()
; #define PG8_SCHED __builtin_amdgcn_sched_barrier(0)
; template <class Epi, class Sched>
; __device__ __forceinline__ void gemm_phase(PG8_LAS unsigned char* lds, const Gemm g, const Sched& S, const Epi& E) {
;     ...
;             PG8_LDB(B0, 1, 0); PG8_SCHED; PG8_LDA(At, 1, 0); PG8_STAGE(PG8_SA(0, 1), a2 + hstep, voffA);
;             PG8_WAIT_L(8); PG8_BAR; PG8_WAIT_L(0); PG8_MMA(0, 0, At, B0); PG8_BAR; PG8_SCHED;
;             PG8_LDB(B1, 1, 1); PG8_STAGE(PG8_SB(1, 0), b3, voffB);
;             PG8_BAR; PG8_WAIT_L(0); PG8_MMA(0, 1, At, B1); PG8_BAR;
;             PG8_LDA(At, 1, 1); PG8_STAGE(PG8_SA(1, 0), a3, voffA);
;             PG8_BAR; PG8_WAIT_L(0); PG8_MMA(1, 0, At, B0); PG8_BAR; PG8_SCHED;
;             PG8_STAGE(PG8_SB(1, 1), b3 + hstepB, voffB);
;             PG8_WAIT_V(6); PG8_BAR; PG8_MMA(1, 1, At, B1); PG8_BAR;
;         }
	s_add_i32 s70, 0, 0x18000
	v_add_u32_e32 v140, s70, v195
	ds_read_b128 v[128:131], v140
	ds_read_b128 v[132:135], v140 offset:1024
	ds_read_b128 v[136:139], v140 offset:2048
	ds_read_b128 v[140:143], v140 offset:3072
	s_add_u32 s28, s38, 0x80000
	s_addc_u32 s29, s39, 0
	s_mov_b32 m0, s56
	ds_read_b128 v[144:147], v198 offset:32768
	ds_read_b128 v[148:151], v198 offset:33792
	ds_read_b128 v[152:155], v198 offset:34816
	ds_read_b128 v[156:159], v198 offset:35840
	ds_read_b128 v[160:163], v198 offset:36864
	ds_read_b128 v[180:183], v198 offset:37888
	ds_read_b128 v[184:187], v198 offset:38912
	ds_read_b128 v[188:191], v198 offset:39936
	s_add_i32 s38, 0, 0x1c000
	v_add_u32_e32 v212, s38, v195
	ds_read_b128 v[200:203], v212
	ds_read_b128 v[204:207], v212 offset:1024
	ds_read_b128 v[208:211], v212 offset:2048
	ds_read_b128 v[212:215], v212 offset:3072
	global_load_lds_dwordx4 v166, s[28:29]
	s_mov_b32 m0, s57
	s_nop 0
	global_load_lds_dwordx4 v170, s[28:29]
	s_add_u32 s28, s36, 0x8000
	s_addc_u32 s29, s37, 0
	s_add_i32 s39, s70, s54
	s_mov_b32 m0, s39
	s_waitcnt vmcnt(8)
	s_waitcnt lgkmcnt(0)
	s_barrier
	v_mfma_f32_16x16x32_bf16 v[124:127], v[128:131], v[144:147], v[124:127]
	v_mfma_f32_16x16x32_bf16 v[120:123], v[136:139], v[144:147], v[120:123]
	v_mfma_f32_16x16x32_bf16 v[116:119], v[128:131], v[152:155], v[116:119]
	v_mfma_f32_16x16x32_bf16 v[104:107], v[136:139], v[152:155], v[104:107]
	v_mfma_f32_16x16x32_bf16 v[92:95], v[128:131], v[160:163], v[92:95]
	v_mfma_f32_16x16x32_bf16 v[88:91], v[136:139], v[160:163], v[88:91]
	v_mfma_f32_16x16x32_bf16 v[76:79], v[128:131], v[184:187], v[76:79]
	v_mfma_f32_16x16x32_bf16 v[72:75], v[136:139], v[184:187], v[72:75]
	v_mfma_f32_16x16x32_bf16 v[124:127], v[132:135], v[148:151], v[124:127]
	v_mfma_f32_16x16x32_bf16 v[120:123], v[140:143], v[148:151], v[120:123]
	v_mfma_f32_16x16x32_bf16 v[116:119], v[132:135], v[156:159], v[116:119]
	v_mfma_f32_16x16x32_bf16 v[104:107], v[140:143], v[156:159], v[104:107]
	v_mfma_f32_16x16x32_bf16 v[92:95], v[132:135], v[180:183], v[92:95]
	v_mfma_f32_16x16x32_bf16 v[88:91], v[140:143], v[180:183], v[88:91]
	v_mfma_f32_16x16x32_bf16 v[76:79], v[132:135], v[188:191], v[76:79]
	v_mfma_f32_16x16x32_bf16 v[72:75], v[140:143], v[188:191], v[72:75]
	v_mfma_f32_16x16x32_bf16 v[112:115], v[200:203], v[144:147], v[112:115]
	v_mfma_f32_16x16x32_bf16 v[108:111], v[208:211], v[144:147], v[108:111]
	v_mfma_f32_16x16x32_bf16 v[100:103], v[200:203], v[152:155], v[100:103]
	v_mfma_f32_16x16x32_bf16 v[96:99], v[208:211], v[152:155], v[96:99]
	v_mfma_f32_16x16x32_bf16 v[84:87], v[200:203], v[160:163], v[84:87]
	v_mfma_f32_16x16x32_bf16 v[80:83], v[208:211], v[160:163], v[80:83]
	v_mfma_f32_16x16x32_bf16 v[68:71], v[200:203], v[184:187], v[68:71]
	v_mfma_f32_16x16x32_bf16 v[64:67], v[208:211], v[184:187], v[64:67]
	v_mfma_f32_16x16x32_bf16 v[112:115], v[204:207], v[148:151], v[112:115]
	v_mfma_f32_16x16x32_bf16 v[108:111], v[212:215], v[148:151], v[108:111]
	v_mfma_f32_16x16x32_bf16 v[100:103], v[204:207], v[156:159], v[100:103]
	v_mfma_f32_16x16x32_bf16 v[96:99], v[212:215], v[156:159], v[96:99]
	v_mfma_f32_16x16x32_bf16 v[84:87], v[204:207], v[180:183], v[84:87]
	v_mfma_f32_16x16x32_bf16 v[80:83], v[212:215], v[180:183], v[80:83]
	v_mfma_f32_16x16x32_bf16 v[68:71], v[204:207], v[188:191], v[68:71]
	v_mfma_f32_16x16x32_bf16 v[64:67], v[212:215], v[188:191], v[64:67]
	s_barrier
	global_load_lds_dwordx4 v164, s[28:29]
	s_add_i32 m0, s39, 0x2000
	s_nop 0
	global_load_lds_dwordx4 v168, s[28:29]
	s_mov_b32 m0, s59
	v_lshl_add_u64 v[192:193], v[192:193], 0, s[10:11]
	ds_read_b128 v[144:147], v198 offset:49152
	ds_read_b128 v[148:151], v198 offset:50176
	ds_read_b128 v[152:155], v198 offset:51200
	ds_read_b128 v[156:159], v198 offset:52224
	ds_read_b128 v[160:163], v198 offset:53248
	ds_read_b128 v[180:183], v198 offset:54272
	ds_read_b128 v[184:187], v198 offset:55296
	ds_read_b128 v[188:191], v198 offset:56320
	global_load_lds_dwordx4 v[192:193], off
	v_lshl_add_u64 v[192:193], v[216:217], 0, s[10:11]
	s_mov_b32 m0, s60
	s_nop 0
	global_load_lds_dwordx4 v[192:193], off
	s_add_u32 s28, s36, 0xc000
	s_addc_u32 s29, s37, 0
	s_add_i32 s36, s38, s54
	s_mov_b32 m0, s36
	s_nop 0
	global_load_lds_dwordx4 v164, s[28:29]
	s_add_i32 m0, s36, 0x2000
	s_nop 0
	global_load_lds_dwordx4 v168, s[28:29]
	s_add_i32 s69, s69, 2
	s_add_u32 s67, s67, 0x10000
	s_addc_u32 s68, s68, 0
	s_cmp_gt_u32 s69, 29
	s_mov_b64 s[28:29], s[30:31]
	s_waitcnt vmcnt(8)
	s_waitcnt lgkmcnt(0)
	s_barrier
	v_mfma_f32_16x16x32_bf16 v[60:63], v[128:131], v[144:147], v[60:63]
	v_mfma_f32_16x16x32_bf16 v[56:59], v[136:139], v[144:147], v[56:59]
	v_mfma_f32_16x16x32_bf16 v[44:47], v[128:131], v[152:155], v[44:47]
	v_mfma_f32_16x16x32_bf16 v[40:43], v[136:139], v[152:155], v[40:43]
	v_mfma_f32_16x16x32_bf16 v[28:31], v[128:131], v[160:163], v[28:31]
	v_mfma_f32_16x16x32_bf16 v[24:27], v[136:139], v[160:163], v[24:27]
	v_mfma_f32_16x16x32_bf16 v[12:15], v[128:131], v[184:187], v[12:15]
	v_mfma_f32_16x16x32_bf16 v[8:11], v[136:139], v[184:187], v[8:11]
	v_mfma_f32_16x16x32_bf16 v[60:63], v[132:135], v[148:151], v[60:63]
	v_mfma_f32_16x16x32_bf16 v[56:59], v[140:143], v[148:151], v[56:59]
	v_mfma_f32_16x16x32_bf16 v[44:47], v[132:135], v[156:159], v[44:47]
	v_mfma_f32_16x16x32_bf16 v[40:43], v[140:143], v[156:159], v[40:43]
	v_mfma_f32_16x16x32_bf16 v[28:31], v[132:135], v[180:183], v[28:31]
	v_mfma_f32_16x16x32_bf16 v[24:27], v[140:143], v[180:183], v[24:27]
	v_mfma_f32_16x16x32_bf16 v[12:15], v[132:135], v[188:191], v[12:15]
	v_mfma_f32_16x16x32_bf16 v[8:11], v[140:143], v[188:191], v[8:11]
	v_mfma_f32_16x16x32_bf16 v[52:55], v[200:203], v[144:147], v[52:55]
	v_mfma_f32_16x16x32_bf16 v[48:51], v[208:211], v[144:147], v[48:51]
	v_mfma_f32_16x16x32_bf16 v[36:39], v[200:203], v[152:155], v[36:39]
	v_mfma_f32_16x16x32_bf16 v[32:35], v[208:211], v[152:155], v[32:35]
	v_mfma_f32_16x16x32_bf16 v[20:23], v[200:203], v[160:163], v[20:23]
	v_mfma_f32_16x16x32_bf16 v[16:19], v[208:211], v[160:163], v[16:19]
	v_mfma_f32_16x16x32_bf16 v[4:7], v[200:203], v[184:187], v[4:7]
	v_mfma_f32_16x16x32_bf16 v[0:3], v[208:211], v[184:187], v[0:3]
	v_mfma_f32_16x16x32_bf16 v[52:55], v[204:207], v[148:151], v[52:55]
	v_mfma_f32_16x16x32_bf16 v[48:51], v[212:215], v[148:151], v[48:51]
	v_mfma_f32_16x16x32_bf16 v[36:39], v[204:207], v[156:159], v[36:39]
	v_mfma_f32_16x16x32_bf16 v[32:35], v[212:215], v[156:159], v[32:35]
	s_cbranch_scc1 .Lunit_exit_5
	v_mfma_f32_16x16x32_bf16 v[20:23], v[204:207], v[180:183], v[20:23]
	v_mfma_f32_16x16x32_bf16 v[16:19], v[212:215], v[180:183], v[16:19]
	v_mfma_f32_16x16x32_bf16 v[4:7], v[204:207], v[188:191], v[4:7]
	v_mfma_f32_16x16x32_bf16 v[0:3], v[212:215], v[188:191], v[0:3]
	s_barrier
	s_branch .LBB0_783

; #define PG8_STAGE(bufoff, gbase, voff) do { _Pragma("unroll") for (int _i = 0; _i < 2; ++_i) \
;         __builtin_amdgcn_global_load_lds((const unsigned*)((const char*)(gbase) + (voff)[_i]), (PG8_LAS unsigned*)(lds + (bufoff) + ldsw + _i * 8192), 16, 0, 0); } while (0)
; #define PG8_LDA(dst, b, h) do { _Pragma("unroll") for (int m = 0; m < 4; ++m) _Pragma("unroll") for (int k = 0; k < 2; ++k) dst[m][k] = *(const PG8_LAS bf16x8*)(lds + PG8_SA(b, h) + aoff + m * 2048 + k * 1024); } while (0)
; #define PG8_LDB(dst, b, h) do { _Pragma("unroll") for (int n = 0; n < 2; ++n) _Pragma("unroll") for (int k = 0; k < 2; ++k) dst[n][k] = *(const PG8_LAS bf16x8*)(lds + PG8_SB(b, h) + boff + n * 2048 + k * 1024); } while (0)
; #define PG8_MMA(ai, bj, At, Bt) do { __builtin_amdgcn_s_setprio(1); _Pragma("unroll") for (int m = 0; m < 4; ++m) _Pragma("unroll") for (int n = 0; n < 2; ++n) _Pragma("unroll") for (int k = 0; k < 2; ++k) \
;         acc[ai][bj][m][n] = __builtin_amdgcn_mfma_f32_16x16x32_bf16(Bt[n][k], At[m][k], acc[ai][bj][m][n], 0, 0, 0); __builtin_amdgcn_s_setprio(0); } while (0)
; #define PG8_WAIT_V(n) asm volatile("s_waitcnt vmcnt(" #n ")" ::: "memory")
; template <class Epi, class Sched>
; __device__ __forceinline__ void gemm_phase(PG8_LAS unsigned char* lds, const Gemm g, const Sched& S, const Epi& E) {
;     ...
;         for (int t = 0; t < nt; t += 2) {
;             const bool last = (t == nt - 2);
;             const char* a1 = cA + (size_t)(t + 1) * kstep;
;             const char* a2 = last ? nA : cA + (size_t)(t + 2) * kstep; const char* b2 = last ? nB : cB + (size_t)(t + 2) * kstepB;
;             const char* a3 = a2 + kstep; const char* b3 = b2 + kstepB;
;             if (last && has_next) S.a_ready(nxt);
;             PG8_LDB(B0, 0, 0); PG8_SCHED; PG8_LDA(At, 0, 0); PG8_STAGE(PG8_SA(1, 1), a1 + hstep, voffA);
;             PG8_WAIT_L(8); PG8_BAR; PG8_WAIT_L(0); PG8_MMA(0, 0, At, B0); PG8_BAR; PG8_SCHED;
;             PG8_LDB(B1, 0, 1); PG8_STAGE(PG8_SB(0, 0), b2, voffB);
;             PG8_BAR; PG8_WAIT_L(0); PG8_MMA(0, 1, At, B1); PG8_BAR;
;             PG8_LDA(At, 0, 1); PG8_STAGE(PG8_SA(0, 0), a2, voffA);
;             PG8_BAR; PG8_WAIT_L(0); PG8_MMA(1, 0, At, B0); PG8_BAR; PG8_SCHED;
;             PG8_STAGE(PG8_SB(0, 1), b2 + hstepB, voffB);
;             PG8_WAIT_V(6); PG8_BAR; PG8_MMA(1, 1, At, B1); PG8_BAR;
.Lhalf_skip_y_6:
.LBB0_904:
	ds_read_b128 v[152:155], v149
	ds_read_b128 v[156:159], v149 offset:1024
	ds_read_b128 v[160:163], v149 offset:2048
	ds_read_b128 v[164:167], v149 offset:3072
	s_add_u32 s22, s20, 0xfff80080
	s_addc_u32 s23, s21, -1
	s_cmp_eq_u32 s61, 28
	s_cselect_b32 s25, s11, s23
	s_cselect_b32 s24, s57, s22
	s_cselect_b32 s23, s13, s60
	s_cselect_b32 s22, s58, s59
	s_add_i32 m0, s19, 0xc000
	ds_read_b128 v[168:171], v150
	ds_read_b128 v[172:175], v150 offset:1024
	ds_read_b128 v[176:179], v150 offset:2048
	ds_read_b128 v[180:183], v150 offset:3072
	ds_read_b128 v[184:187], v150 offset:4096
	ds_read_b128 v[188:191], v150 offset:5120
	ds_read_b128 v[192:195], v150 offset:6144
	ds_read_b128 v[196:199], v150 offset:7168
	ds_read_b128 v[200:203], v151
	ds_read_b128 v[204:207], v151 offset:1024
	ds_read_b128 v[208:211], v151 offset:2048
	ds_read_b128 v[212:215], v151 offset:3072
	global_load_lds_dwordx4 v136, s[20:21]
	s_add_i32 m0, s19, 0xe000
	s_nop 0
	global_load_lds_dwordx4 v138, s[20:21]
	s_add_i32 s62, s53, s38
	s_mov_b32 m0, s62
	s_waitcnt vmcnt(8)
	s_waitcnt lgkmcnt(0)
	s_barrier
	v_mfma_f32_16x16x32_bf16 v[124:127], v[152:155], v[168:171], v[124:127]
	v_mfma_f32_16x16x32_bf16 v[120:123], v[160:163], v[168:171], v[120:123]
	v_mfma_f32_16x16x32_bf16 v[108:111], v[152:155], v[176:179], v[108:111]
	v_mfma_f32_16x16x32_bf16 v[104:107], v[160:163], v[176:179], v[104:107]
	v_mfma_f32_16x16x32_bf16 v[92:95], v[152:155], v[184:187], v[92:95]
	v_mfma_f32_16x16x32_bf16 v[88:91], v[160:163], v[184:187], v[88:91]
	v_mfma_f32_16x16x32_bf16 v[76:79], v[152:155], v[192:195], v[76:79]
	v_mfma_f32_16x16x32_bf16 v[72:75], v[160:163], v[192:195], v[72:75]
	v_mfma_f32_16x16x32_bf16 v[124:127], v[156:159], v[172:175], v[124:127]
	v_mfma_f32_16x16x32_bf16 v[120:123], v[164:167], v[172:175], v[120:123]
	v_mfma_f32_16x16x32_bf16 v[108:111], v[156:159], v[180:183], v[108:111]
	v_mfma_f32_16x16x32_bf16 v[104:107], v[164:167], v[180:183], v[104:107]
	v_mfma_f32_16x16x32_bf16 v[92:95], v[156:159], v[188:191], v[92:95]
	v_mfma_f32_16x16x32_bf16 v[88:91], v[164:167], v[188:191], v[88:91]
	v_mfma_f32_16x16x32_bf16 v[76:79], v[156:159], v[196:199], v[76:79]
	v_mfma_f32_16x16x32_bf16 v[72:75], v[164:167], v[196:199], v[72:75]
	v_mfma_f32_16x16x32_bf16 v[116:119], v[200:203], v[168:171], v[116:119]
	v_mfma_f32_16x16x32_bf16 v[112:115], v[208:211], v[168:171], v[112:115]
	v_mfma_f32_16x16x32_bf16 v[100:103], v[200:203], v[176:179], v[100:103]
	v_mfma_f32_16x16x32_bf16 v[96:99], v[208:211], v[176:179], v[96:99]
	v_mfma_f32_16x16x32_bf16 v[84:87], v[200:203], v[184:187], v[84:87]
	v_mfma_f32_16x16x32_bf16 v[80:83], v[208:211], v[184:187], v[80:83]
	v_mfma_f32_16x16x32_bf16 v[68:71], v[200:203], v[192:195], v[68:71]
	v_mfma_f32_16x16x32_bf16 v[64:67], v[208:211], v[192:195], v[64:67]
	v_mfma_f32_16x16x32_bf16 v[116:119], v[204:207], v[172:175], v[116:119]
	v_mfma_f32_16x16x32_bf16 v[112:115], v[212:215], v[172:175], v[112:115]
	v_mfma_f32_16x16x32_bf16 v[100:103], v[204:207], v[180:183], v[100:103]
	v_mfma_f32_16x16x32_bf16 v[96:99], v[212:215], v[180:183], v[96:99]
	v_mfma_f32_16x16x32_bf16 v[84:87], v[204:207], v[188:191], v[84:87]
	v_mfma_f32_16x16x32_bf16 v[80:83], v[212:215], v[188:191], v[80:83]
	v_mfma_f32_16x16x32_bf16 v[68:71], v[204:207], v[196:199], v[68:71]
	v_mfma_f32_16x16x32_bf16 v[64:67], v[212:215], v[196:199], v[64:67]
	s_barrier
	global_load_lds_dwordx4 v128, s[22:23]
	s_add_i32 m0, s62, 0x2000
	s_nop 0
	global_load_lds_dwordx4 v130, s[22:23]
	s_mov_b32 m0, s19
	v_lshl_add_u64 v[144:145], s[24:25], 0, v[134:135]
	ds_read_b128 v[168:171], v150 offset:16384
	ds_read_b128 v[172:175], v150 offset:17408
	ds_read_b128 v[176:179], v150 offset:18432
	ds_read_b128 v[180:183], v150 offset:19456
	ds_read_b128 v[184:187], v150 offset:20480
	ds_read_b128 v[188:191], v150 offset:21504
	ds_read_b128 v[192:195], v150 offset:22528
	ds_read_b128 v[196:199], v150 offset:23552
	global_load_lds_dwordx4 v[144:145], off
	v_lshl_add_u64 v[216:217], s[24:25], 0, v[132:133]
	s_mov_b32 m0, s46
	s_nop 0
	global_load_lds_dwordx4 v[216:217], off
	s_add_u32 s62, s22, 0x4000
	s_addc_u32 s63, s23, 0
	s_add_i32 s64, s54, s38
	s_mov_b32 m0, s64
	s_nop 0
	global_load_lds_dwordx4 v128, s[62:63]
	s_add_i32 m0, s64, 0x2000
	s_nop 0
	global_load_lds_dwordx4 v130, s[62:63]
	s_waitcnt vmcnt(8)
	s_waitcnt lgkmcnt(0)
	s_barrier
	v_mfma_f32_16x16x32_bf16 v[60:63], v[152:155], v[168:171], v[60:63]
	v_mfma_f32_16x16x32_bf16 v[56:59], v[160:163], v[168:171], v[56:59]
	v_mfma_f32_16x16x32_bf16 v[44:47], v[152:155], v[176:179], v[44:47]
	v_mfma_f32_16x16x32_bf16 v[40:43], v[160:163], v[176:179], v[40:43]
	v_mfma_f32_16x16x32_bf16 v[28:31], v[152:155], v[184:187], v[28:31]
	v_mfma_f32_16x16x32_bf16 v[24:27], v[160:163], v[184:187], v[24:27]
	v_mfma_f32_16x16x32_bf16 v[12:15], v[152:155], v[192:195], v[12:15]
	v_mfma_f32_16x16x32_bf16 v[8:11], v[160:163], v[192:195], v[8:11]
	v_mfma_f32_16x16x32_bf16 v[60:63], v[156:159], v[172:175], v[60:63]
	v_mfma_f32_16x16x32_bf16 v[56:59], v[164:167], v[172:175], v[56:59]
	v_mfma_f32_16x16x32_bf16 v[44:47], v[156:159], v[180:183], v[44:47]
	v_mfma_f32_16x16x32_bf16 v[40:43], v[164:167], v[180:183], v[40:43]
	v_mfma_f32_16x16x32_bf16 v[28:31], v[156:159], v[188:191], v[28:31]
	v_mfma_f32_16x16x32_bf16 v[24:27], v[164:167], v[188:191], v[24:27]
	v_mfma_f32_16x16x32_bf16 v[12:15], v[156:159], v[196:199], v[12:15]
	v_mfma_f32_16x16x32_bf16 v[8:11], v[164:167], v[196:199], v[8:11]
	v_mfma_f32_16x16x32_bf16 v[52:55], v[200:203], v[168:171], v[52:55]
	v_mfma_f32_16x16x32_bf16 v[48:51], v[208:211], v[168:171], v[48:51]
	v_mfma_f32_16x16x32_bf16 v[36:39], v[200:203], v[176:179], v[36:39]
	v_mfma_f32_16x16x32_bf16 v[32:35], v[208:211], v[176:179], v[32:35]
	v_mfma_f32_16x16x32_bf16 v[20:23], v[200:203], v[184:187], v[20:23]
	v_mfma_f32_16x16x32_bf16 v[16:19], v[208:211], v[184:187], v[16:19]
	v_mfma_f32_16x16x32_bf16 v[4:7], v[200:203], v[192:195], v[4:7]
	v_mfma_f32_16x16x32_bf16 v[0:3], v[208:211], v[192:195], v[0:3]
	v_mfma_f32_16x16x32_bf16 v[52:55], v[204:207], v[172:175], v[52:55]
	v_mfma_f32_16x16x32_bf16 v[48:51], v[212:215], v[172:175], v[48:51]
	v_mfma_f32_16x16x32_bf16 v[36:39], v[204:207], v[180:183], v[36:39]
	v_mfma_f32_16x16x32_bf16 v[32:35], v[212:215], v[180:183], v[32:35]
	v_mfma_f32_16x16x32_bf16 v[20:23], v[204:207], v[188:191], v[20:23]
	v_mfma_f32_16x16x32_bf16 v[16:19], v[212:215], v[188:191], v[16:19]
	v_mfma_f32_16x16x32_bf16 v[4:7], v[204:207], v[196:199], v[4:7]
	v_mfma_f32_16x16x32_bf16 v[0:3], v[212:215], v[196:199], v[0:3]
	s_barrier
; #define PG8_STAGE(bufoff, gbase, voff) do { _Pragma("unroll") for (int _i = 0; _i < 2; ++_i) \
;         __builtin_amdgcn_global_load_lds((const unsigned*)((const char*)(gbase) + (voff)[_i]), (PG8_LAS unsigned*)(lds + (bufoff) + ldsw + _i * 8192), 16, 0, 0); } while (0)
; #define PG8_LDA(dst, b, h) do { _Pragma("unroll") for (int m = 0; m < 4; ++m) _Pragma("unroll") for (int k = 0; k < 2; ++k) dst[m][k] = *(const PG8_LAS bf16x8*)(lds + PG8_SA(b, h) + aoff + m * 2048 + k * 1024); } while (0)
; #define PG8_LDB(dst, b, h) do { _Pragma("unroll") for (int n = 0; n < 2; ++n) _Pragma("unroll") for (int k = 0; k < 2; ++k) dst[n][k] = *(const PG8_LAS bf16x8*)(lds + PG8_SB(b, h) + boff + n * 2048 + k * 1024); } while (0)
; #define PG8_MMA(ai, bj, At, Bt) do { __builtin_amdgcn_s_setprio(1); _Pragma("unroll") for (int m = 0; m < 4; ++m) _Pragma("unroll") for (int n = 0; n < 2; ++n) _Pragma("unroll") for (int k = 0; k < 2; ++k) \
;         acc[ai][bj][m][n] = __builtin_amdgcn_mfma_f32_16x16x32_bf16(Bt[n][k], At[m][k], acc[ai][bj][m][n], 0, 0, 0); __builtin_amdgcn_s_setprio(0); } while (0)
; #define PG8_WAIT_V(n) asm volatile("s_waitcnt vmcnt(" #n ")" ::: "memory")
; #define PG8_WAIT_L(n) asm volatile("s_waitcnt lgkmcnt(" #n ")" ::: "memory")
; #define PG8_BAR __builtin_amdgcn_s_barrier()
; #define PG8_SCHED __builtin_amdgcn_sched_barrier(0)
; template <class Epi, class Sched>
; __device__ __forceinline__ void gemm_phase(PG8_LAS unsigned char* lds, const Gemm g, const Sched& S, const Epi& E) {
;     ...
;             PG8_LDB(B0, 1, 0); PG8_SCHED; PG8_LDA(At, 1, 0); PG8_STAGE(PG8_SA(0, 1), a2 + hstep, voffA);
;             PG8_WAIT_L(8); PG8_BAR; PG8_WAIT_L(0); PG8_MMA(0, 0, At, B0); PG8_BAR; PG8_SCHED;
;             PG8_LDB(B1, 1, 1); PG8_STAGE(PG8_SB(1, 0), b3, voffB);
;             PG8_BAR; PG8_WAIT_L(0); PG8_MMA(0, 1, At, B1); PG8_BAR;
;             PG8_LDA(At, 1, 1); PG8_STAGE(PG8_SA(1, 0), a3, voffA);
;             PG8_BAR; PG8_WAIT_L(0); PG8_MMA(1, 0, At, B0); PG8_BAR; PG8_SCHED;
;             PG8_STAGE(PG8_SB(1, 1), b3 + hstepB, voffB);
;             PG8_WAIT_V(6); PG8_BAR; PG8_MMA(1, 1, At, B1); PG8_BAR;
;         }
	s_add_i32 s62, 0, 0x18000
	v_add_u32_e32 v164, s62, v147
	ds_read_b128 v[152:155], v164
	ds_read_b128 v[156:159], v164 offset:1024
	ds_read_b128 v[160:163], v164 offset:2048
	ds_read_b128 v[164:167], v164 offset:3072
	s_add_u32 s24, s24, 0x80000
	s_addc_u32 s25, s25, 0
	s_mov_b32 m0, s47
	ds_read_b128 v[168:171], v150 offset:32768
	ds_read_b128 v[172:175], v150 offset:33792
	ds_read_b128 v[176:179], v150 offset:34816
	ds_read_b128 v[180:183], v150 offset:35840
	ds_read_b128 v[184:187], v150 offset:36864
	ds_read_b128 v[188:191], v150 offset:37888
	ds_read_b128 v[192:195], v150 offset:38912
	ds_read_b128 v[196:199], v150 offset:39936
	s_add_i32 s63, 0, 0x1c000
	v_add_u32_e32 v212, s63, v147
	ds_read_b128 v[200:203], v212
	ds_read_b128 v[204:207], v212 offset:1024
	ds_read_b128 v[208:211], v212 offset:2048
	ds_read_b128 v[212:215], v212 offset:3072
	global_load_lds_dwordx4 v134, s[24:25]
	s_mov_b32 m0, s48
	s_nop 0
	global_load_lds_dwordx4 v132, s[24:25]
	s_add_u32 s24, s22, 0x8000
	s_addc_u32 s25, s23, 0
	s_add_i32 s62, s62, s38
	s_mov_b32 m0, s62
	s_waitcnt vmcnt(8)
	s_waitcnt lgkmcnt(0)
	s_barrier
	v_mfma_f32_16x16x32_bf16 v[124:127], v[152:155], v[168:171], v[124:127]
	v_mfma_f32_16x16x32_bf16 v[120:123], v[160:163], v[168:171], v[120:123]
	v_mfma_f32_16x16x32_bf16 v[108:111], v[152:155], v[176:179], v[108:111]
	v_mfma_f32_16x16x32_bf16 v[104:107], v[160:163], v[176:179], v[104:107]
	v_mfma_f32_16x16x32_bf16 v[92:95], v[152:155], v[184:187], v[92:95]
	v_mfma_f32_16x16x32_bf16 v[88:91], v[160:163], v[184:187], v[88:91]
	v_mfma_f32_16x16x32_bf16 v[76:79], v[152:155], v[192:195], v[76:79]
	v_mfma_f32_16x16x32_bf16 v[72:75], v[160:163], v[192:195], v[72:75]
	v_mfma_f32_16x16x32_bf16 v[124:127], v[156:159], v[172:175], v[124:127]
	v_mfma_f32_16x16x32_bf16 v[120:123], v[164:167], v[172:175], v[120:123]
	v_mfma_f32_16x16x32_bf16 v[108:111], v[156:159], v[180:183], v[108:111]
	v_mfma_f32_16x16x32_bf16 v[104:107], v[164:167], v[180:183], v[104:107]
	v_mfma_f32_16x16x32_bf16 v[92:95], v[156:159], v[188:191], v[92:95]
	v_mfma_f32_16x16x32_bf16 v[88:91], v[164:167], v[188:191], v[88:91]
	v_mfma_f32_16x16x32_bf16 v[76:79], v[156:159], v[196:199], v[76:79]
	v_mfma_f32_16x16x32_bf16 v[72:75], v[164:167], v[196:199], v[72:75]
	v_mfma_f32_16x16x32_bf16 v[116:119], v[200:203], v[168:171], v[116:119]
	v_mfma_f32_16x16x32_bf16 v[112:115], v[208:211], v[168:171], v[112:115]
	v_mfma_f32_16x16x32_bf16 v[100:103], v[200:203], v[176:179], v[100:103]
	v_mfma_f32_16x16x32_bf16 v[96:99], v[208:211], v[176:179], v[96:99]
	v_mfma_f32_16x16x32_bf16 v[84:87], v[200:203], v[184:187], v[84:87]
	v_mfma_f32_16x16x32_bf16 v[80:83], v[208:211], v[184:187], v[80:83]
	v_mfma_f32_16x16x32_bf16 v[68:71], v[200:203], v[192:195], v[68:71]
	v_mfma_f32_16x16x32_bf16 v[64:67], v[208:211], v[192:195], v[64:67]
	v_mfma_f32_16x16x32_bf16 v[116:119], v[204:207], v[172:175], v[116:119]
	v_mfma_f32_16x16x32_bf16 v[112:115], v[212:215], v[172:175], v[112:115]
	v_mfma_f32_16x16x32_bf16 v[100:103], v[204:207], v[180:183], v[100:103]
	v_mfma_f32_16x16x32_bf16 v[96:99], v[212:215], v[180:183], v[96:99]
	v_mfma_f32_16x16x32_bf16 v[84:87], v[204:207], v[188:191], v[84:87]
	v_mfma_f32_16x16x32_bf16 v[80:83], v[212:215], v[188:191], v[80:83]
	v_mfma_f32_16x16x32_bf16 v[68:71], v[204:207], v[196:199], v[68:71]
	v_mfma_f32_16x16x32_bf16 v[64:67], v[212:215], v[196:199], v[64:67]
	s_barrier
	global_load_lds_dwordx4 v128, s[24:25]
	s_add_i32 m0, s62, 0x2000
	s_nop 0
	global_load_lds_dwordx4 v130, s[24:25]
	s_mov_b32 m0, s50
	v_lshl_add_u64 v[144:145], v[144:145], 0, s[8:9]
	ds_read_b128 v[168:171], v150 offset:49152
	ds_read_b128 v[172:175], v150 offset:50176
	ds_read_b128 v[176:179], v150 offset:51200
	ds_read_b128 v[180:183], v150 offset:52224
	ds_read_b128 v[184:187], v150 offset:53248
	ds_read_b128 v[188:191], v150 offset:54272
	ds_read_b128 v[192:195], v150 offset:55296
	ds_read_b128 v[196:199], v150 offset:56320
	global_load_lds_dwordx4 v[144:145], off
	v_lshl_add_u64 v[144:145], v[216:217], 0, s[8:9]
	s_mov_b32 m0, s51
	s_nop 0
	global_load_lds_dwordx4 v[144:145], off
	s_add_u32 s22, s22, 0xc000
	s_addc_u32 s23, s23, 0
	s_add_i32 s24, s63, s38
	s_mov_b32 m0, s24
	s_nop 0
	global_load_lds_dwordx4 v128, s[22:23]
	s_add_i32 m0, s24, 0x2000
	s_nop 0
	global_load_lds_dwordx4 v130, s[22:23]
	s_add_i32 s61, s61, 2
	s_add_u32 s59, s59, 0x10000
	s_addc_u32 s60, s60, 0
	s_add_u32 s20, s20, 0x100
	s_addc_u32 s21, s21, 0
	s_cmp_gt_u32 s61, 29
	s_waitcnt vmcnt(8)
	s_waitcnt lgkmcnt(0)
	s_barrier
	v_mfma_f32_16x16x32_bf16 v[60:63], v[152:155], v[168:171], v[60:63]
	v_mfma_f32_16x16x32_bf16 v[56:59], v[160:163], v[168:171], v[56:59]
	v_mfma_f32_16x16x32_bf16 v[44:47], v[152:155], v[176:179], v[44:47]
	v_mfma_f32_16x16x32_bf16 v[40:43], v[160:163], v[176:179], v[40:43]
	v_mfma_f32_16x16x32_bf16 v[28:31], v[152:155], v[184:187], v[28:31]
	v_mfma_f32_16x16x32_bf16 v[24:27], v[160:163], v[184:187], v[24:27]
	v_mfma_f32_16x16x32_bf16 v[12:15], v[152:155], v[192:195], v[12:15]
	v_mfma_f32_16x16x32_bf16 v[8:11], v[160:163], v[192:195], v[8:11]
	v_mfma_f32_16x16x32_bf16 v[60:63], v[156:159], v[172:175], v[60:63]
	v_mfma_f32_16x16x32_bf16 v[56:59], v[164:167], v[172:175], v[56:59]
	v_mfma_f32_16x16x32_bf16 v[44:47], v[156:159], v[180:183], v[44:47]
	v_mfma_f32_16x16x32_bf16 v[40:43], v[164:167], v[180:183], v[40:43]
	v_mfma_f32_16x16x32_bf16 v[28:31], v[156:159], v[188:191], v[28:31]
	v_mfma_f32_16x16x32_bf16 v[24:27], v[164:167], v[188:191], v[24:27]
	v_mfma_f32_16x16x32_bf16 v[12:15], v[156:159], v[196:199], v[12:15]
	v_mfma_f32_16x16x32_bf16 v[8:11], v[164:167], v[196:199], v[8:11]
	v_mfma_f32_16x16x32_bf16 v[52:55], v[200:203], v[168:171], v[52:55]
	v_mfma_f32_16x16x32_bf16 v[48:51], v[208:211], v[168:171], v[48:51]
	v_mfma_f32_16x16x32_bf16 v[36:39], v[200:203], v[176:179], v[36:39]
	v_mfma_f32_16x16x32_bf16 v[32:35], v[208:211], v[176:179], v[32:35]
	v_mfma_f32_16x16x32_bf16 v[20:23], v[200:203], v[184:187], v[20:23]
	v_mfma_f32_16x16x32_bf16 v[16:19], v[208:211], v[184:187], v[16:19]
	v_mfma_f32_16x16x32_bf16 v[4:7], v[200:203], v[192:195], v[4:7]
	v_mfma_f32_16x16x32_bf16 v[0:3], v[208:211], v[192:195], v[0:3]
	v_mfma_f32_16x16x32_bf16 v[52:55], v[204:207], v[172:175], v[52:55]
	v_mfma_f32_16x16x32_bf16 v[48:51], v[212:215], v[172:175], v[48:51]
	v_mfma_f32_16x16x32_bf16 v[36:39], v[204:207], v[180:183], v[36:39]
	v_mfma_f32_16x16x32_bf16 v[32:35], v[212:215], v[180:183], v[32:35]
	s_cbranch_scc1 .Lunit_exit_6
	v_mfma_f32_16x16x32_bf16 v[20:23], v[204:207], v[188:191], v[20:23]
	v_mfma_f32_16x16x32_bf16 v[16:19], v[212:215], v[188:191], v[16:19]
	v_mfma_f32_16x16x32_bf16 v[4:7], v[204:207], v[196:199], v[4:7]
	v_mfma_f32_16x16x32_bf16 v[0:3], v[212:215], v[196:199], v[0:3]
	s_barrier
	s_branch .LBB0_904

; #define PG8_STAGE(bufoff, gbase, voff) do { _Pragma("unroll") for (int _i = 0; _i < 2; ++_i) \
;         __builtin_amdgcn_global_load_lds((const unsigned*)((const char*)(gbase) + (voff)[_i]), (PG8_LAS unsigned*)(lds + (bufoff) + ldsw + _i * 8192), 16, 0, 0); } while (0)
; #define PG8_LDA(dst, b, h) do { _Pragma("unroll") for (int m = 0; m < 4; ++m) _Pragma("unroll") for (int k = 0; k < 2; ++k) dst[m][k] = *(const PG8_LAS bf16x8*)(lds + PG8_SA(b, h) + aoff + m * 2048 + k * 1024); } while (0)
; #define PG8_LDB(dst, b, h) do { _Pragma("unroll") for (int n = 0; n < 2; ++n) _Pragma("unroll") for (int k = 0; k < 2; ++k) dst[n][k] = *(const PG8_LAS bf16x8*)(lds + PG8_SB(b, h) + boff + n * 2048 + k * 1024); } while (0)
; #define PG8_MMA(ai, bj, At, Bt) do { __builtin_amdgcn_s_setprio(1); _Pragma("unroll") for (int m = 0; m < 4; ++m) _Pragma("unroll") for (int n = 0; n < 2; ++n) _Pragma("unroll") for (int k = 0; k < 2; ++k) \
;         acc[ai][bj][m][n] = __builtin_amdgcn_mfma_f32_16x16x32_bf16(Bt[n][k], At[m][k], acc[ai][bj][m][n], 0, 0, 0); __builtin_amdgcn_s_setprio(0); } while (0)
; #define PG8_WAIT_V(n) asm volatile("s_waitcnt vmcnt(" #n ")" ::: "memory")
; template <class Epi, class Sched>
; __device__ __forceinline__ void gemm_phase(PG8_LAS unsigned char* lds, const Gemm g, const Sched& S, const Epi& E) {
;     ...
;         for (int t = 0; t < nt; t += 2) {
;             const bool last = (t == nt - 2);
;             const char* a1 = cA + (size_t)(t + 1) * kstep;
;             const char* a2 = last ? nA : cA + (size_t)(t + 2) * kstep; const char* b2 = last ? nB : cB + (size_t)(t + 2) * kstepB;
;             const char* a3 = a2 + kstep; const char* b3 = b2 + kstepB;
;             if (last && has_next) S.a_ready(nxt);
;             PG8_LDB(B0, 0, 0); PG8_SCHED; PG8_LDA(At, 0, 0); PG8_STAGE(PG8_SA(1, 1), a1 + hstep, voffA);
;             PG8_WAIT_L(8); PG8_BAR; PG8_WAIT_L(0); PG8_MMA(0, 0, At, B0); PG8_BAR; PG8_SCHED;
;             PG8_LDB(B1, 0, 1); PG8_STAGE(PG8_SB(0, 0), b2, voffB);
;             PG8_BAR; PG8_WAIT_L(0); PG8_MMA(0, 1, At, B1); PG8_BAR;
;             PG8_LDA(At, 0, 1); PG8_STAGE(PG8_SA(0, 0), a2, voffA);
;             PG8_BAR; PG8_WAIT_L(0); PG8_MMA(1, 0, At, B0); PG8_BAR; PG8_SCHED;
;             PG8_STAGE(PG8_SB(0, 1), b2 + hstepB, voffB);
;             PG8_WAIT_V(6); PG8_BAR; PG8_MMA(1, 1, At, B1); PG8_BAR;
.Lhalf_skip_y_7:
.LBB0_980:
	ds_read_b128 v[128:131], v197
	ds_read_b128 v[132:135], v197 offset:1024
	ds_read_b128 v[136:139], v197 offset:2048
	ds_read_b128 v[140:143], v197 offset:3072
	s_add_u32 s24, s22, 0x100
	s_addc_u32 s25, s23, 0
	s_cmpk_eq_i32 s65, 0x52
	s_cselect_b32 s29, s7, s25
	s_cselect_b32 s28, s6, s24
	s_cselect_b32 s27, s9, s64
	s_cselect_b32 s26, s8, s63
	v_lshl_add_u64 v[192:193], s[22:23], 0, v[172:173]
	s_add_i32 m0, s49, 0xc000
	ds_read_b128 v[144:147], v198
	ds_read_b128 v[148:151], v198 offset:1024
	ds_read_b128 v[152:155], v198 offset:2048
	ds_read_b128 v[156:159], v198 offset:3072
	ds_read_b128 v[160:163], v198 offset:4096
	ds_read_b128 v[180:183], v198 offset:5120
	ds_read_b128 v[184:187], v198 offset:6144
	ds_read_b128 v[188:191], v198 offset:7168
	ds_read_b128 v[200:203], v199
	ds_read_b128 v[204:207], v199 offset:1024
	ds_read_b128 v[208:211], v199 offset:2048
	ds_read_b128 v[212:215], v199 offset:3072
	global_load_lds_dwordx4 v[192:193], off
	v_lshl_add_u64 v[192:193], s[22:23], 0, v[174:175]
	s_add_i32 m0, s49, 0xe000
	s_nop 0
	global_load_lds_dwordx4 v[192:193], off
	s_add_i32 s22, s57, s48
	s_mov_b32 m0, s22
	s_waitcnt vmcnt(8)
	s_waitcnt lgkmcnt(0)
	s_barrier
	v_mfma_f32_16x16x32_bf16 v[124:127], v[128:131], v[144:147], v[124:127]
	v_mfma_f32_16x16x32_bf16 v[120:123], v[136:139], v[144:147], v[120:123]
	v_mfma_f32_16x16x32_bf16 v[116:119], v[128:131], v[152:155], v[116:119]
	v_mfma_f32_16x16x32_bf16 v[104:107], v[136:139], v[152:155], v[104:107]
	v_mfma_f32_16x16x32_bf16 v[92:95], v[128:131], v[160:163], v[92:95]
	v_mfma_f32_16x16x32_bf16 v[88:91], v[136:139], v[160:163], v[88:91]
	v_mfma_f32_16x16x32_bf16 v[76:79], v[128:131], v[184:187], v[76:79]
	v_mfma_f32_16x16x32_bf16 v[72:75], v[136:139], v[184:187], v[72:75]
	v_mfma_f32_16x16x32_bf16 v[124:127], v[132:135], v[148:151], v[124:127]
	v_mfma_f32_16x16x32_bf16 v[120:123], v[140:143], v[148:151], v[120:123]
	v_mfma_f32_16x16x32_bf16 v[116:119], v[132:135], v[156:159], v[116:119]
	v_mfma_f32_16x16x32_bf16 v[104:107], v[140:143], v[156:159], v[104:107]
	v_mfma_f32_16x16x32_bf16 v[92:95], v[132:135], v[180:183], v[92:95]
	v_mfma_f32_16x16x32_bf16 v[88:91], v[140:143], v[180:183], v[88:91]
	v_mfma_f32_16x16x32_bf16 v[76:79], v[132:135], v[188:191], v[76:79]
	v_mfma_f32_16x16x32_bf16 v[72:75], v[140:143], v[188:191], v[72:75]
	v_mfma_f32_16x16x32_bf16 v[112:115], v[200:203], v[144:147], v[112:115]
	v_mfma_f32_16x16x32_bf16 v[108:111], v[208:211], v[144:147], v[108:111]
	v_mfma_f32_16x16x32_bf16 v[100:103], v[200:203], v[152:155], v[100:103]
	v_mfma_f32_16x16x32_bf16 v[96:99], v[208:211], v[152:155], v[96:99]
	v_mfma_f32_16x16x32_bf16 v[84:87], v[200:203], v[160:163], v[84:87]
	v_mfma_f32_16x16x32_bf16 v[80:83], v[208:211], v[160:163], v[80:83]
	v_mfma_f32_16x16x32_bf16 v[68:71], v[200:203], v[184:187], v[68:71]
	v_mfma_f32_16x16x32_bf16 v[64:67], v[208:211], v[184:187], v[64:67]
	v_mfma_f32_16x16x32_bf16 v[112:115], v[204:207], v[148:151], v[112:115]
	v_mfma_f32_16x16x32_bf16 v[108:111], v[212:215], v[148:151], v[108:111]
	v_mfma_f32_16x16x32_bf16 v[100:103], v[204:207], v[156:159], v[100:103]
	v_mfma_f32_16x16x32_bf16 v[96:99], v[212:215], v[156:159], v[96:99]
	v_mfma_f32_16x16x32_bf16 v[84:87], v[204:207], v[180:183], v[84:87]
	v_mfma_f32_16x16x32_bf16 v[80:83], v[212:215], v[180:183], v[80:83]
	v_mfma_f32_16x16x32_bf16 v[68:71], v[204:207], v[188:191], v[68:71]
	v_mfma_f32_16x16x32_bf16 v[64:67], v[212:215], v[188:191], v[64:67]
	s_barrier
	global_load_lds_dwordx4 v164, s[26:27]
	s_add_i32 m0, s22, 0x2000
	s_nop 0
	global_load_lds_dwordx4 v168, s[26:27]
	s_mov_b32 m0, s49
	v_lshl_add_u64 v[192:193], s[28:29], 0, v[166:167]
	ds_read_b128 v[144:147], v198 offset:16384
	ds_read_b128 v[148:151], v198 offset:17408
	ds_read_b128 v[152:155], v198 offset:18432
	ds_read_b128 v[156:159], v198 offset:19456
	ds_read_b128 v[160:163], v198 offset:20480
	ds_read_b128 v[180:183], v198 offset:21504
	ds_read_b128 v[184:187], v198 offset:22528
	ds_read_b128 v[188:191], v198 offset:23552
	global_load_lds_dwordx4 v[192:193], off
	v_lshl_add_u64 v[216:217], s[28:29], 0, v[170:171]
	s_mov_b32 m0, s50
	s_nop 0
	global_load_lds_dwordx4 v[216:217], off
	s_add_u32 s22, s26, 0x4000
	s_addc_u32 s23, s27, 0
	s_add_i32 s66, s58, s48
	s_mov_b32 m0, s66
	s_nop 0
	global_load_lds_dwordx4 v164, s[22:23]
	s_add_i32 m0, s66, 0x2000
	s_nop 0
	global_load_lds_dwordx4 v168, s[22:23]
	s_waitcnt vmcnt(8)
	s_waitcnt lgkmcnt(0)
	s_barrier
	v_mfma_f32_16x16x32_bf16 v[60:63], v[128:131], v[144:147], v[60:63]
	v_mfma_f32_16x16x32_bf16 v[56:59], v[136:139], v[144:147], v[56:59]
	v_mfma_f32_16x16x32_bf16 v[44:47], v[128:131], v[152:155], v[44:47]
	v_mfma_f32_16x16x32_bf16 v[40:43], v[136:139], v[152:155], v[40:43]
	v_mfma_f32_16x16x32_bf16 v[28:31], v[128:131], v[160:163], v[28:31]
	v_mfma_f32_16x16x32_bf16 v[24:27], v[136:139], v[160:163], v[24:27]
	v_mfma_f32_16x16x32_bf16 v[12:15], v[128:131], v[184:187], v[12:15]
	v_mfma_f32_16x16x32_bf16 v[8:11], v[136:139], v[184:187], v[8:11]
	v_mfma_f32_16x16x32_bf16 v[60:63], v[132:135], v[148:151], v[60:63]
	v_mfma_f32_16x16x32_bf16 v[56:59], v[140:143], v[148:151], v[56:59]
	v_mfma_f32_16x16x32_bf16 v[44:47], v[132:135], v[156:159], v[44:47]
	v_mfma_f32_16x16x32_bf16 v[40:43], v[140:143], v[156:159], v[40:43]
	v_mfma_f32_16x16x32_bf16 v[28:31], v[132:135], v[180:183], v[28:31]
	v_mfma_f32_16x16x32_bf16 v[24:27], v[140:143], v[180:183], v[24:27]
	v_mfma_f32_16x16x32_bf16 v[12:15], v[132:135], v[188:191], v[12:15]
	v_mfma_f32_16x16x32_bf16 v[8:11], v[140:143], v[188:191], v[8:11]
	v_mfma_f32_16x16x32_bf16 v[52:55], v[200:203], v[144:147], v[52:55]
	v_mfma_f32_16x16x32_bf16 v[48:51], v[208:211], v[144:147], v[48:51]
	v_mfma_f32_16x16x32_bf16 v[36:39], v[200:203], v[152:155], v[36:39]
	v_mfma_f32_16x16x32_bf16 v[32:35], v[208:211], v[152:155], v[32:35]
	v_mfma_f32_16x16x32_bf16 v[20:23], v[200:203], v[160:163], v[20:23]
	v_mfma_f32_16x16x32_bf16 v[16:19], v[208:211], v[160:163], v[16:19]
	v_mfma_f32_16x16x32_bf16 v[4:7], v[200:203], v[184:187], v[4:7]
	v_mfma_f32_16x16x32_bf16 v[0:3], v[208:211], v[184:187], v[0:3]
	v_mfma_f32_16x16x32_bf16 v[52:55], v[204:207], v[148:151], v[52:55]
	v_mfma_f32_16x16x32_bf16 v[48:51], v[212:215], v[148:151], v[48:51]
	v_mfma_f32_16x16x32_bf16 v[36:39], v[204:207], v[156:159], v[36:39]
	v_mfma_f32_16x16x32_bf16 v[32:35], v[212:215], v[156:159], v[32:35]
	v_mfma_f32_16x16x32_bf16 v[20:23], v[204:207], v[180:183], v[20:23]
	v_mfma_f32_16x16x32_bf16 v[16:19], v[212:215], v[180:183], v[16:19]
	v_mfma_f32_16x16x32_bf16 v[4:7], v[204:207], v[188:191], v[4:7]
	v_mfma_f32_16x16x32_bf16 v[0:3], v[212:215], v[188:191], v[0:3]
	s_barrier
; #define PG8_STAGE(bufoff, gbase, voff) do { _Pragma("unroll") for (int _i = 0; _i < 2; ++_i) \
;         __builtin_amdgcn_global_load_lds((const unsigned*)((const char*)(gbase) + (voff)[_i]), (PG8_LAS unsigned*)(lds + (bufoff) + ldsw + _i * 8192), 16, 0, 0); } while (0)
; #define PG8_LDA(dst, b, h) do { _Pragma("unroll") for (int m = 0; m < 4; ++m) _Pragma("unroll") for (int k = 0; k < 2; ++k) dst[m][k] = *(const PG8_LAS bf16x8*)(lds + PG8_SA(b, h) + aoff + m * 2048 + k * 1024); } while (0)
; #define PG8_WAIT_V(n) asm volatile("s_waitcnt vmcnt(" #n ")" ::: "memory")
; template <class Epi, class Sched>
; __device__ __forceinline__ void gemm_phase(PG8_LAS unsigned char* lds, const Gemm g, const Sched& S, const Epi& E) {
;     ...
;         for (int t = 0; t < nt; t += 2) {
;             const bool last = (t == nt - 2);
;             const char* a1 = cA + (size_t)(t + 1) * kstep;
;             const char* a2 = last ? nA : cA + (size_t)(t + 2) * kstep; const char* b2 = last ? nB : cB + (size_t)(t + 2) * kstepB;
;             const char* a3 = a2 + kstep; const char* b3 = b2 + kstepB;
;             if (last && has_next) S.a_ready(nxt);
;             PG8_LDB(B0, 0, 0); PG8_SCHED; PG8_LDA(At, 0, 0); PG8_STAGE(PG8_SA(1, 1), a1 + hstep, voffA);
;             PG8_WAIT_L(8); PG8_BAR; PG8_WAIT_L(0); PG8_MMA(0, 0, At, B0); PG8_BAR; PG8_SCHED;
;             PG8_LDB(B1, 0, 1); PG8_STAGE(PG8_SB(0, 0), b2, voffB);
;             PG8_BAR; PG8_WAIT_L(0); PG8_MMA(0, 1, At, B1); PG8_BAR;
;             PG8_LDA(At, 0, 1); PG8_STAGE(PG8_SA(0, 0), a2, voffA);
;             PG8_BAR; PG8_WAIT_L(0); PG8_MMA(1, 0, At, B0); PG8_BAR; PG8_SCHED;
;             PG8_STAGE(PG8_SB(0, 1), b2 + hstepB, voffB);
;             PG8_WAIT_V(6); PG8_BAR; PG8_MMA(1, 1, At, B1); PG8_BAR;
;             PG8_LDB(B0, 1, 0); PG8_SCHED; PG8_LDA(At, 1, 0); PG8_STAGE(PG8_SA(0, 1), a2 + hstep, voffA);
;             PG8_WAIT_L(8); PG8_BAR; PG8_WAIT_L(0); PG8_MMA(0, 0, At, B0); PG8_BAR; PG8_SCHED;
;             PG8_LDB(B1, 1, 1); PG8_STAGE(PG8_SB(1, 0), b3, voffB);
;             PG8_BAR; PG8_WAIT_L(0); PG8_MMA(0, 1, At, B1); PG8_BAR;
;             PG8_LDA(At, 1, 1); PG8_STAGE(PG8_SA(1, 0), a3, voffA);
;             PG8_BAR; PG8_WAIT_L(0); PG8_MMA(1, 0, At, B0); PG8_BAR; PG8_SCHED;
;             PG8_STAGE(PG8_SB(1, 1), b3 + hstepB, voffB);
;             PG8_WAIT_V(6); PG8_BAR; PG8_MMA(1, 1, At, B1); PG8_BAR;
	s_add_i32 s66, 0, 0x18000
	v_add_u32_e32 v140, s66, v195
	ds_read_b128 v[128:131], v140
	ds_read_b128 v[132:135], v140 offset:1024
	ds_read_b128 v[136:139], v140 offset:2048
	ds_read_b128 v[140:143], v140 offset:3072
	s_add_u32 s22, s28, 0x158000
	s_addc_u32 s23, s29, 0
	s_mov_b32 m0, s51
	ds_read_b128 v[144:147], v198 offset:32768
	ds_read_b128 v[148:151], v198 offset:33792
	ds_read_b128 v[152:155], v198 offset:34816
	ds_read_b128 v[156:159], v198 offset:35840
	ds_read_b128 v[160:163], v198 offset:36864
	ds_read_b128 v[180:183], v198 offset:37888
	ds_read_b128 v[184:187], v198 offset:38912
	ds_read_b128 v[188:191], v198 offset:39936
	s_add_i32 s28, 0, 0x1c000
	v_add_u32_e32 v212, s28, v195
	ds_read_b128 v[200:203], v212
	ds_read_b128 v[204:207], v212 offset:1024
	ds_read_b128 v[208:211], v212 offset:2048
	ds_read_b128 v[212:215], v212 offset:3072
	global_load_lds_dwordx4 v166, s[22:23]
	s_mov_b32 m0, s52
	s_nop 0
	global_load_lds_dwordx4 v170, s[22:23]
	s_add_u32 s22, s26, 0x8000
	s_addc_u32 s23, s27, 0
	s_add_i32 s29, s66, s48
	s_mov_b32 m0, s29
	s_waitcnt vmcnt(8)
	s_waitcnt lgkmcnt(0)
	s_barrier
	v_mfma_f32_16x16x32_bf16 v[124:127], v[128:131], v[144:147], v[124:127]
	v_mfma_f32_16x16x32_bf16 v[120:123], v[136:139], v[144:147], v[120:123]
	v_mfma_f32_16x16x32_bf16 v[116:119], v[128:131], v[152:155], v[116:119]
	v_mfma_f32_16x16x32_bf16 v[104:107], v[136:139], v[152:155], v[104:107]
	v_mfma_f32_16x16x32_bf16 v[92:95], v[128:131], v[160:163], v[92:95]
	v_mfma_f32_16x16x32_bf16 v[88:91], v[136:139], v[160:163], v[88:91]
	v_mfma_f32_16x16x32_bf16 v[76:79], v[128:131], v[184:187], v[76:79]
	v_mfma_f32_16x16x32_bf16 v[72:75], v[136:139], v[184:187], v[72:75]
	v_mfma_f32_16x16x32_bf16 v[124:127], v[132:135], v[148:151], v[124:127]
	v_mfma_f32_16x16x32_bf16 v[120:123], v[140:143], v[148:151], v[120:123]
	v_mfma_f32_16x16x32_bf16 v[116:119], v[132:135], v[156:159], v[116:119]
	v_mfma_f32_16x16x32_bf16 v[104:107], v[140:143], v[156:159], v[104:107]
	v_mfma_f32_16x16x32_bf16 v[92:95], v[132:135], v[180:183], v[92:95]
	v_mfma_f32_16x16x32_bf16 v[88:91], v[140:143], v[180:183], v[88:91]
	v_mfma_f32_16x16x32_bf16 v[76:79], v[132:135], v[188:191], v[76:79]
	v_mfma_f32_16x16x32_bf16 v[72:75], v[140:143], v[188:191], v[72:75]
	v_mfma_f32_16x16x32_bf16 v[112:115], v[200:203], v[144:147], v[112:115]
	v_mfma_f32_16x16x32_bf16 v[108:111], v[208:211], v[144:147], v[108:111]
	v_mfma_f32_16x16x32_bf16 v[100:103], v[200:203], v[152:155], v[100:103]
	v_mfma_f32_16x16x32_bf16 v[96:99], v[208:211], v[152:155], v[96:99]
	v_mfma_f32_16x16x32_bf16 v[84:87], v[200:203], v[160:163], v[84:87]
	v_mfma_f32_16x16x32_bf16 v[80:83], v[208:211], v[160:163], v[80:83]
	v_mfma_f32_16x16x32_bf16 v[68:71], v[200:203], v[184:187], v[68:71]
	v_mfma_f32_16x16x32_bf16 v[64:67], v[208:211], v[184:187], v[64:67]
	v_mfma_f32_16x16x32_bf16 v[112:115], v[204:207], v[148:151], v[112:115]
	v_mfma_f32_16x16x32_bf16 v[108:111], v[212:215], v[148:151], v[108:111]
	v_mfma_f32_16x16x32_bf16 v[100:103], v[204:207], v[156:159], v[100:103]
	v_mfma_f32_16x16x32_bf16 v[96:99], v[212:215], v[156:159], v[96:99]
	v_mfma_f32_16x16x32_bf16 v[84:87], v[204:207], v[180:183], v[84:87]
	v_mfma_f32_16x16x32_bf16 v[80:83], v[212:215], v[180:183], v[80:83]
	v_mfma_f32_16x16x32_bf16 v[68:71], v[204:207], v[188:191], v[68:71]
	v_mfma_f32_16x16x32_bf16 v[64:67], v[212:215], v[188:191], v[64:67]
	s_barrier
	global_load_lds_dwordx4 v164, s[22:23]
	s_add_i32 m0, s29, 0x2000
	s_nop 0
	global_load_lds_dwordx4 v168, s[22:23]
	s_mov_b32 m0, s54
	v_lshl_add_u64 v[192:193], v[192:193], 0, s[12:13]
	ds_read_b128 v[144:147], v198 offset:49152
	ds_read_b128 v[148:151], v198 offset:50176
	ds_read_b128 v[152:155], v198 offset:51200
	ds_read_b128 v[156:159], v198 offset:52224
	ds_read_b128 v[160:163], v198 offset:53248
	ds_read_b128 v[180:183], v198 offset:54272
	ds_read_b128 v[184:187], v198 offset:55296
	ds_read_b128 v[188:191], v198 offset:56320
	global_load_lds_dwordx4 v[192:193], off
	v_lshl_add_u64 v[192:193], v[216:217], 0, s[12:13]
	s_mov_b32 m0, s55
	s_nop 0
	global_load_lds_dwordx4 v[192:193], off
	s_add_u32 s22, s26, 0xc000
	s_addc_u32 s23, s27, 0
	s_add_i32 s26, s28, s48
	s_mov_b32 m0, s26
	s_nop 0
	global_load_lds_dwordx4 v164, s[22:23]
	s_add_i32 m0, s26, 0x2000
	s_nop 0
	global_load_lds_dwordx4 v168, s[22:23]
	s_add_i32 s65, s65, 2
	s_add_u32 s63, s63, 0x10000
	s_addc_u32 s64, s64, 0
	s_cmpk_gt_u32 s65, 0x53
	s_mov_b64 s[22:23], s[24:25]
	s_waitcnt vmcnt(8)
	s_waitcnt lgkmcnt(0)
	s_barrier
	v_mfma_f32_16x16x32_bf16 v[60:63], v[128:131], v[144:147], v[60:63]
	v_mfma_f32_16x16x32_bf16 v[56:59], v[136:139], v[144:147], v[56:59]
	v_mfma_f32_16x16x32_bf16 v[44:47], v[128:131], v[152:155], v[44:47]
	v_mfma_f32_16x16x32_bf16 v[40:43], v[136:139], v[152:155], v[40:43]
	v_mfma_f32_16x16x32_bf16 v[28:31], v[128:131], v[160:163], v[28:31]
	v_mfma_f32_16x16x32_bf16 v[24:27], v[136:139], v[160:163], v[24:27]
	v_mfma_f32_16x16x32_bf16 v[12:15], v[128:131], v[184:187], v[12:15]
	v_mfma_f32_16x16x32_bf16 v[8:11], v[136:139], v[184:187], v[8:11]
	v_mfma_f32_16x16x32_bf16 v[60:63], v[132:135], v[148:151], v[60:63]
	v_mfma_f32_16x16x32_bf16 v[56:59], v[140:143], v[148:151], v[56:59]
	v_mfma_f32_16x16x32_bf16 v[44:47], v[132:135], v[156:159], v[44:47]
	v_mfma_f32_16x16x32_bf16 v[40:43], v[140:143], v[156:159], v[40:43]
	v_mfma_f32_16x16x32_bf16 v[28:31], v[132:135], v[180:183], v[28:31]
	v_mfma_f32_16x16x32_bf16 v[24:27], v[140:143], v[180:183], v[24:27]
	v_mfma_f32_16x16x32_bf16 v[12:15], v[132:135], v[188:191], v[12:15]
	v_mfma_f32_16x16x32_bf16 v[8:11], v[140:143], v[188:191], v[8:11]
	v_mfma_f32_16x16x32_bf16 v[52:55], v[200:203], v[144:147], v[52:55]
	v_mfma_f32_16x16x32_bf16 v[48:51], v[208:211], v[144:147], v[48:51]
	v_mfma_f32_16x16x32_bf16 v[36:39], v[200:203], v[152:155], v[36:39]
	v_mfma_f32_16x16x32_bf16 v[32:35], v[208:211], v[152:155], v[32:35]
	v_mfma_f32_16x16x32_bf16 v[20:23], v[200:203], v[160:163], v[20:23]
	v_mfma_f32_16x16x32_bf16 v[16:19], v[208:211], v[160:163], v[16:19]
	v_mfma_f32_16x16x32_bf16 v[4:7], v[200:203], v[184:187], v[4:7]
	v_mfma_f32_16x16x32_bf16 v[0:3], v[208:211], v[184:187], v[0:3]
	v_mfma_f32_16x16x32_bf16 v[52:55], v[204:207], v[148:151], v[52:55]
	v_mfma_f32_16x16x32_bf16 v[48:51], v[212:215], v[148:151], v[48:51]
	v_mfma_f32_16x16x32_bf16 v[36:39], v[204:207], v[156:159], v[36:39]
	v_mfma_f32_16x16x32_bf16 v[32:35], v[212:215], v[156:159], v[32:35]
	s_cbranch_scc1 .Lunit_exit_7
	v_mfma_f32_16x16x32_bf16 v[20:23], v[204:207], v[180:183], v[20:23]
	v_mfma_f32_16x16x32_bf16 v[16:19], v[212:215], v[180:183], v[16:19]
	v_mfma_f32_16x16x32_bf16 v[4:7], v[204:207], v[188:191], v[4:7]
	v_mfma_f32_16x16x32_bf16 v[0:3], v[212:215], v[188:191], v[0:3]
	s_barrier
	s_branch .LBB0_980
